# hyena: per-channel L1 invalidate (buffer_inv) after the spectrum stores replaced by L1-bypassing (sc1) loads of the block's own spectrum and scratch data
# speedup vs baseline: 1.2033x; 1.0156x over previous
; HD float2 cmul(float2 a, float2 b){ return make_float2(a.x*b.x - a.y*b.y, a.x*b.y + a.y*b.x); }
; HD void fwd12_padded(float2* Z, const float2* twA, const float2* twB, int t, float2 a0, float2 a1){
;   float2 w1=cmul(twA[t>>6],twB[t&63]), w2=cmul(w1,w1), w3=cmul(w2,w1);
;   Z[t]=make_float2(a0.x+a1.x,a0.y+a1.y);
;   Z[t+4096]=cmul(make_float2(a0.x+a1.y,a0.y-a1.x),w1);
;   Z[t+8192]=cmul(make_float2(a0.x-a1.x,a0.y-a1.y),w2);
;   Z[t+12288]=cmul(make_float2(a0.x-a1.y,a0.y+a1.x),w3);
; }
; __device__ __forceinline__ void phase_hyena(KP kp_, int hf){ asm volatile("" : "+s"(kp_)); const Params p=load_params(kp_);
;     ...
;       } else { int tq=tid; asm volatile("" : "+v"(tq));
;         _Pragma("unroll 4") for (int i=0;i<8;++i){ int t=tq+512*i; fwd12_padded(Z,twA,twB,t,Zs[t],Zs[t+4096]); }
;         __syncthreads();
.LBB0_1319:
	s_mov_b64 s[12:13], -1
	s_and_b64 vcc, exec, s[68:69]
	s_barrier
	s_cbranch_vccz .LBB0_1329
	s_cmp_lg_u32 s89, 1
	s_cbranch_scc0 .LBB0_1324
	v_lshlrev_b32_e32 v15, 3, v86
	v_mov_b32_e32 v0, v15
	v_add_u32_e32 v1, 0x1000, v15
	v_add_u32_e32 v2, 0x2000, v15
	v_add_u32_e32 v4, 0x3000, v15
	v_add_u32_e32 v5, 0x4000, v15
	v_add_u32_e32 v6, 0x5000, v15
	v_add_u32_e32 v7, 0x6000, v15
	v_add_u32_e32 v8, 0x7000, v15
	s_add_u32 s12, s80, 0x8000
	s_addc_u32 s13, s81, 0
	global_load_dwordx2 v[104:105], v0, s[80:81] sc1
	global_load_dwordx2 v[106:107], v0, s[12:13] sc1
	global_load_dwordx2 v[108:109], v1, s[80:81] sc1
	global_load_dwordx2 v[110:111], v1, s[12:13] sc1
	global_load_dwordx2 v[112:113], v2, s[80:81] sc1
	global_load_dwordx2 v[114:115], v2, s[12:13] sc1
	global_load_dwordx2 v[116:117], v4, s[80:81] sc1
	global_load_dwordx2 v[118:119], v4, s[12:13] sc1
	global_load_dwordx2 v[120:121], v5, s[80:81] sc1
	global_load_dwordx2 v[122:123], v5, s[12:13] sc1
	global_load_dwordx2 v[124:125], v6, s[80:81] sc1
	global_load_dwordx2 v[126:127], v6, s[12:13] sc1
	global_load_dwordx2 v[134:135], v7, s[80:81] sc1
	global_load_dwordx2 v[136:137], v7, s[12:13] sc1
	global_load_dwordx2 v[138:139], v8, s[80:81] sc1
	global_load_dwordx2 v[140:141], v8, s[12:13] sc1
	v_lshlrev_b32_e32 v12, 3, v86
	v_add_u32_e32 v13, 0x10000, v12
	v_lshrrev_b32_e32 v14, 6, v86
	v_lshl_add_u32 v14, v14, 3, s88
	v_and_b32_e32 v15, 63, v86
	v_lshl_add_u32 v15, v15, 3, s91
	ds_read_b64 v[10:11], v15
	ds_read_b64 v[58:59], v14 offset:0
	ds_read_b64 v[60:61], v14 offset:64
	ds_read_b64 v[62:63], v14 offset:128
	ds_read_b64 v[64:65], v14 offset:192
	ds_read_b64 v[66:67], v14 offset:256
	ds_read_b64 v[68:69], v14 offset:320
	ds_read_b64 v[70:71], v14 offset:384
	ds_read_b64 v[72:73], v14 offset:448
	s_waitcnt lgkmcnt(0)
	v_pk_mul_f32 v[222:223], v[58:59], v[10:11] op_sel:[1,1] op_sel_hi:[1,0]
	v_pk_fma_f32 v[22:23], v[58:59], v[10:11], v[222:223] op_sel:[0,0,0] op_sel_hi:[0,1,1] neg_lo:[0,0,1]
	v_pk_mul_f32 v[222:223], v[22:23], v[22:23] op_sel:[1,1] op_sel_hi:[1,0]
	v_pk_fma_f32 v[24:25], v[22:23], v[22:23], v[222:223] op_sel:[0,0,0] op_sel_hi:[0,1,1] neg_lo:[0,0,1]
	v_pk_mul_f32 v[222:223], v[24:25], v[22:23] op_sel:[1,1] op_sel_hi:[1,0]
	v_pk_fma_f32 v[26:27], v[24:25], v[22:23], v[222:223] op_sel:[0,0,0] op_sel_hi:[0,1,1] neg_lo:[0,0,1]
	s_waitcnt vmcnt(14)
	v_pk_add_f32 v[84:85], v[104:105], v[106:107]
	ds_write_b64 v12, v[84:85] offset:0
	v_pk_add_f32 v[74:75], v[104:105], v[106:107] op_sel:[0,1] op_sel_hi:[1,0] neg_hi:[0,1]
	v_pk_mul_f32 v[222:223], v[74:75], v[22:23] op_sel:[1,1] op_sel_hi:[1,0]
	v_pk_fma_f32 v[84:85], v[74:75], v[22:23], v[222:223] op_sel:[0,0,0] op_sel_hi:[0,1,1] neg_lo:[0,0,1]
	ds_write_b64 v12, v[84:85] offset:32768
	v_pk_add_f32 v[74:75], v[104:105], v[106:107] neg_lo:[0,1] neg_hi:[0,1]
	v_pk_mul_f32 v[222:223], v[74:75], v[24:25] op_sel:[1,1] op_sel_hi:[1,0]
	v_pk_fma_f32 v[84:85], v[74:75], v[24:25], v[222:223] op_sel:[0,0,0] op_sel_hi:[0,1,1] neg_lo:[0,0,1]
	ds_write_b64 v13, v[84:85] offset:0
	v_pk_add_f32 v[74:75], v[104:105], v[106:107] op_sel:[0,1] op_sel_hi:[1,0] neg_lo:[0,1]
	v_pk_mul_f32 v[222:223], v[74:75], v[26:27] op_sel:[1,1] op_sel_hi:[1,0]
	v_pk_fma_f32 v[84:85], v[74:75], v[26:27], v[222:223] op_sel:[0,0,0] op_sel_hi:[0,1,1] neg_lo:[0,0,1]
	ds_write_b64 v13, v[84:85] offset:32768
	v_pk_mul_f32 v[222:223], v[60:61], v[10:11] op_sel:[1,1] op_sel_hi:[1,0]
	v_pk_fma_f32 v[22:23], v[60:61], v[10:11], v[222:223] op_sel:[0,0,0] op_sel_hi:[0,1,1] neg_lo:[0,0,1]
	v_pk_mul_f32 v[222:223], v[22:23], v[22:23] op_sel:[1,1] op_sel_hi:[1,0]
	v_pk_fma_f32 v[24:25], v[22:23], v[22:23], v[222:223] op_sel:[0,0,0] op_sel_hi:[0,1,1] neg_lo:[0,0,1]
	v_pk_mul_f32 v[222:223], v[24:25], v[22:23] op_sel:[1,1] op_sel_hi:[1,0]
	v_pk_fma_f32 v[26:27], v[24:25], v[22:23], v[222:223] op_sel:[0,0,0] op_sel_hi:[0,1,1] neg_lo:[0,0,1]
	s_waitcnt vmcnt(12)
	v_pk_add_f32 v[84:85], v[108:109], v[110:111]
	ds_write_b64 v12, v[84:85] offset:4096
	v_pk_add_f32 v[74:75], v[108:109], v[110:111] op_sel:[0,1] op_sel_hi:[1,0] neg_hi:[0,1]
	v_pk_mul_f32 v[222:223], v[74:75], v[22:23] op_sel:[1,1] op_sel_hi:[1,0]
	v_pk_fma_f32 v[84:85], v[74:75], v[22:23], v[222:223] op_sel:[0,0,0] op_sel_hi:[0,1,1] neg_lo:[0,0,1]
	ds_write_b64 v12, v[84:85] offset:36864
	v_pk_add_f32 v[74:75], v[108:109], v[110:111] neg_lo:[0,1] neg_hi:[0,1]
	v_pk_mul_f32 v[222:223], v[74:75], v[24:25] op_sel:[1,1] op_sel_hi:[1,0]
	v_pk_fma_f32 v[84:85], v[74:75], v[24:25], v[222:223] op_sel:[0,0,0] op_sel_hi:[0,1,1] neg_lo:[0,0,1]
	ds_write_b64 v13, v[84:85] offset:4096
	v_pk_add_f32 v[74:75], v[108:109], v[110:111] op_sel:[0,1] op_sel_hi:[1,0] neg_lo:[0,1]
	v_pk_mul_f32 v[222:223], v[74:75], v[26:27] op_sel:[1,1] op_sel_hi:[1,0]
	v_pk_fma_f32 v[84:85], v[74:75], v[26:27], v[222:223] op_sel:[0,0,0] op_sel_hi:[0,1,1] neg_lo:[0,0,1]
	ds_write_b64 v13, v[84:85] offset:36864
	v_pk_mul_f32 v[222:223], v[62:63], v[10:11] op_sel:[1,1] op_sel_hi:[1,0]
	v_pk_fma_f32 v[22:23], v[62:63], v[10:11], v[222:223] op_sel:[0,0,0] op_sel_hi:[0,1,1] neg_lo:[0,0,1]
	v_pk_mul_f32 v[222:223], v[22:23], v[22:23] op_sel:[1,1] op_sel_hi:[1,0]
	v_pk_fma_f32 v[24:25], v[22:23], v[22:23], v[222:223] op_sel:[0,0,0] op_sel_hi:[0,1,1] neg_lo:[0,0,1]
	v_pk_mul_f32 v[222:223], v[24:25], v[22:23] op_sel:[1,1] op_sel_hi:[1,0]
	v_pk_fma_f32 v[26:27], v[24:25], v[22:23], v[222:223] op_sel:[0,0,0] op_sel_hi:[0,1,1] neg_lo:[0,0,1]
	s_waitcnt vmcnt(10)
; HD float2 cmul(float2 a, float2 b){ return make_float2(a.x*b.x - a.y*b.y, a.x*b.y + a.y*b.x); }
; HD void fwd12_padded(float2* Z, const float2* twA, const float2* twB, int t, float2 a0, float2 a1){
;   float2 w1=cmul(twA[t>>6],twB[t&63]), w2=cmul(w1,w1), w3=cmul(w2,w1);
;   Z[t]=make_float2(a0.x+a1.x,a0.y+a1.y);
;   Z[t+4096]=cmul(make_float2(a0.x+a1.y,a0.y-a1.x),w1);
;   Z[t+8192]=cmul(make_float2(a0.x-a1.x,a0.y-a1.y),w2);
;   Z[t+12288]=cmul(make_float2(a0.x-a1.y,a0.y+a1.x),w3);
; }
	v_pk_add_f32 v[84:85], v[112:113], v[114:115]
	ds_write_b64 v12, v[84:85] offset:8192
	v_pk_add_f32 v[74:75], v[112:113], v[114:115] op_sel:[0,1] op_sel_hi:[1,0] neg_hi:[0,1]
	v_pk_mul_f32 v[222:223], v[74:75], v[22:23] op_sel:[1,1] op_sel_hi:[1,0]
	v_pk_fma_f32 v[84:85], v[74:75], v[22:23], v[222:223] op_sel:[0,0,0] op_sel_hi:[0,1,1] neg_lo:[0,0,1]
	ds_write_b64 v12, v[84:85] offset:40960
	v_pk_add_f32 v[74:75], v[112:113], v[114:115] neg_lo:[0,1] neg_hi:[0,1]
	v_pk_mul_f32 v[222:223], v[74:75], v[24:25] op_sel:[1,1] op_sel_hi:[1,0]
	v_pk_fma_f32 v[84:85], v[74:75], v[24:25], v[222:223] op_sel:[0,0,0] op_sel_hi:[0,1,1] neg_lo:[0,0,1]
	ds_write_b64 v13, v[84:85] offset:8192
	v_pk_add_f32 v[74:75], v[112:113], v[114:115] op_sel:[0,1] op_sel_hi:[1,0] neg_lo:[0,1]
	v_pk_mul_f32 v[222:223], v[74:75], v[26:27] op_sel:[1,1] op_sel_hi:[1,0]
	v_pk_fma_f32 v[84:85], v[74:75], v[26:27], v[222:223] op_sel:[0,0,0] op_sel_hi:[0,1,1] neg_lo:[0,0,1]
	ds_write_b64 v13, v[84:85] offset:40960
	v_pk_mul_f32 v[222:223], v[64:65], v[10:11] op_sel:[1,1] op_sel_hi:[1,0]
	v_pk_fma_f32 v[22:23], v[64:65], v[10:11], v[222:223] op_sel:[0,0,0] op_sel_hi:[0,1,1] neg_lo:[0,0,1]
	v_pk_mul_f32 v[222:223], v[22:23], v[22:23] op_sel:[1,1] op_sel_hi:[1,0]
	v_pk_fma_f32 v[24:25], v[22:23], v[22:23], v[222:223] op_sel:[0,0,0] op_sel_hi:[0,1,1] neg_lo:[0,0,1]
	v_pk_mul_f32 v[222:223], v[24:25], v[22:23] op_sel:[1,1] op_sel_hi:[1,0]
	v_pk_fma_f32 v[26:27], v[24:25], v[22:23], v[222:223] op_sel:[0,0,0] op_sel_hi:[0,1,1] neg_lo:[0,0,1]
	s_waitcnt vmcnt(8)
	v_pk_add_f32 v[84:85], v[116:117], v[118:119]
	ds_write_b64 v12, v[84:85] offset:12288
	v_pk_add_f32 v[74:75], v[116:117], v[118:119] op_sel:[0,1] op_sel_hi:[1,0] neg_hi:[0,1]
	v_pk_mul_f32 v[222:223], v[74:75], v[22:23] op_sel:[1,1] op_sel_hi:[1,0]
	v_pk_fma_f32 v[84:85], v[74:75], v[22:23], v[222:223] op_sel:[0,0,0] op_sel_hi:[0,1,1] neg_lo:[0,0,1]
	ds_write_b64 v12, v[84:85] offset:45056
	v_pk_add_f32 v[74:75], v[116:117], v[118:119] neg_lo:[0,1] neg_hi:[0,1]
	v_pk_mul_f32 v[222:223], v[74:75], v[24:25] op_sel:[1,1] op_sel_hi:[1,0]
	v_pk_fma_f32 v[84:85], v[74:75], v[24:25], v[222:223] op_sel:[0,0,0] op_sel_hi:[0,1,1] neg_lo:[0,0,1]
	ds_write_b64 v13, v[84:85] offset:12288
	v_pk_add_f32 v[74:75], v[116:117], v[118:119] op_sel:[0,1] op_sel_hi:[1,0] neg_lo:[0,1]
	v_pk_mul_f32 v[222:223], v[74:75], v[26:27] op_sel:[1,1] op_sel_hi:[1,0]
	v_pk_fma_f32 v[84:85], v[74:75], v[26:27], v[222:223] op_sel:[0,0,0] op_sel_hi:[0,1,1] neg_lo:[0,0,1]
	ds_write_b64 v13, v[84:85] offset:45056
	v_pk_mul_f32 v[222:223], v[66:67], v[10:11] op_sel:[1,1] op_sel_hi:[1,0]
	v_pk_fma_f32 v[22:23], v[66:67], v[10:11], v[222:223] op_sel:[0,0,0] op_sel_hi:[0,1,1] neg_lo:[0,0,1]
	v_pk_mul_f32 v[222:223], v[22:23], v[22:23] op_sel:[1,1] op_sel_hi:[1,0]
	v_pk_fma_f32 v[24:25], v[22:23], v[22:23], v[222:223] op_sel:[0,0,0] op_sel_hi:[0,1,1] neg_lo:[0,0,1]
	v_pk_mul_f32 v[222:223], v[24:25], v[22:23] op_sel:[1,1] op_sel_hi:[1,0]
	v_pk_fma_f32 v[26:27], v[24:25], v[22:23], v[222:223] op_sel:[0,0,0] op_sel_hi:[0,1,1] neg_lo:[0,0,1]
	s_waitcnt vmcnt(6)
	v_pk_add_f32 v[84:85], v[120:121], v[122:123]
	ds_write_b64 v12, v[84:85] offset:16384
	v_pk_add_f32 v[74:75], v[120:121], v[122:123] op_sel:[0,1] op_sel_hi:[1,0] neg_hi:[0,1]
	v_pk_mul_f32 v[222:223], v[74:75], v[22:23] op_sel:[1,1] op_sel_hi:[1,0]
	v_pk_fma_f32 v[84:85], v[74:75], v[22:23], v[222:223] op_sel:[0,0,0] op_sel_hi:[0,1,1] neg_lo:[0,0,1]
	ds_write_b64 v12, v[84:85] offset:49152
	v_pk_add_f32 v[74:75], v[120:121], v[122:123] neg_lo:[0,1] neg_hi:[0,1]
	v_pk_mul_f32 v[222:223], v[74:75], v[24:25] op_sel:[1,1] op_sel_hi:[1,0]
	v_pk_fma_f32 v[84:85], v[74:75], v[24:25], v[222:223] op_sel:[0,0,0] op_sel_hi:[0,1,1] neg_lo:[0,0,1]
	ds_write_b64 v13, v[84:85] offset:16384
	v_pk_add_f32 v[74:75], v[120:121], v[122:123] op_sel:[0,1] op_sel_hi:[1,0] neg_lo:[0,1]
	v_pk_mul_f32 v[222:223], v[74:75], v[26:27] op_sel:[1,1] op_sel_hi:[1,0]
	v_pk_fma_f32 v[84:85], v[74:75], v[26:27], v[222:223] op_sel:[0,0,0] op_sel_hi:[0,1,1] neg_lo:[0,0,1]
	ds_write_b64 v13, v[84:85] offset:49152
	v_pk_mul_f32 v[222:223], v[68:69], v[10:11] op_sel:[1,1] op_sel_hi:[1,0]
	v_pk_fma_f32 v[22:23], v[68:69], v[10:11], v[222:223] op_sel:[0,0,0] op_sel_hi:[0,1,1] neg_lo:[0,0,1]
	v_pk_mul_f32 v[222:223], v[22:23], v[22:23] op_sel:[1,1] op_sel_hi:[1,0]
	v_pk_fma_f32 v[24:25], v[22:23], v[22:23], v[222:223] op_sel:[0,0,0] op_sel_hi:[0,1,1] neg_lo:[0,0,1]
	v_pk_mul_f32 v[222:223], v[24:25], v[22:23] op_sel:[1,1] op_sel_hi:[1,0]
	v_pk_fma_f32 v[26:27], v[24:25], v[22:23], v[222:223] op_sel:[0,0,0] op_sel_hi:[0,1,1] neg_lo:[0,0,1]
	s_waitcnt vmcnt(4)
; HD float2 cmul(float2 a, float2 b){ return make_float2(a.x*b.x - a.y*b.y, a.x*b.y + a.y*b.x); }
; HD void fwd12_padded(float2* Z, const float2* twA, const float2* twB, int t, float2 a0, float2 a1){
;   float2 w1=cmul(twA[t>>6],twB[t&63]), w2=cmul(w1,w1), w3=cmul(w2,w1);
;   Z[t]=make_float2(a0.x+a1.x,a0.y+a1.y);
;   Z[t+4096]=cmul(make_float2(a0.x+a1.y,a0.y-a1.x),w1);
;   Z[t+8192]=cmul(make_float2(a0.x-a1.x,a0.y-a1.y),w2);
;   Z[t+12288]=cmul(make_float2(a0.x-a1.y,a0.y+a1.x),w3);
; }
; __device__ __forceinline__ void phase_hyena(KP kp_, int hf){ asm volatile("" : "+s"(kp_)); const Params p=load_params(kp_);
;     ...
;         __syncthreads();
	v_pk_add_f32 v[84:85], v[124:125], v[126:127]
	ds_write_b64 v12, v[84:85] offset:20480
	v_pk_add_f32 v[74:75], v[124:125], v[126:127] op_sel:[0,1] op_sel_hi:[1,0] neg_hi:[0,1]
	v_pk_mul_f32 v[222:223], v[74:75], v[22:23] op_sel:[1,1] op_sel_hi:[1,0]
	v_pk_fma_f32 v[84:85], v[74:75], v[22:23], v[222:223] op_sel:[0,0,0] op_sel_hi:[0,1,1] neg_lo:[0,0,1]
	ds_write_b64 v12, v[84:85] offset:53248
	v_pk_add_f32 v[74:75], v[124:125], v[126:127] neg_lo:[0,1] neg_hi:[0,1]
	v_pk_mul_f32 v[222:223], v[74:75], v[24:25] op_sel:[1,1] op_sel_hi:[1,0]
	v_pk_fma_f32 v[84:85], v[74:75], v[24:25], v[222:223] op_sel:[0,0,0] op_sel_hi:[0,1,1] neg_lo:[0,0,1]
	ds_write_b64 v13, v[84:85] offset:20480
	v_pk_add_f32 v[74:75], v[124:125], v[126:127] op_sel:[0,1] op_sel_hi:[1,0] neg_lo:[0,1]
	v_pk_mul_f32 v[222:223], v[74:75], v[26:27] op_sel:[1,1] op_sel_hi:[1,0]
	v_pk_fma_f32 v[84:85], v[74:75], v[26:27], v[222:223] op_sel:[0,0,0] op_sel_hi:[0,1,1] neg_lo:[0,0,1]
	ds_write_b64 v13, v[84:85] offset:53248
	v_pk_mul_f32 v[222:223], v[70:71], v[10:11] op_sel:[1,1] op_sel_hi:[1,0]
	v_pk_fma_f32 v[22:23], v[70:71], v[10:11], v[222:223] op_sel:[0,0,0] op_sel_hi:[0,1,1] neg_lo:[0,0,1]
	v_pk_mul_f32 v[222:223], v[22:23], v[22:23] op_sel:[1,1] op_sel_hi:[1,0]
	v_pk_fma_f32 v[24:25], v[22:23], v[22:23], v[222:223] op_sel:[0,0,0] op_sel_hi:[0,1,1] neg_lo:[0,0,1]
	v_pk_mul_f32 v[222:223], v[24:25], v[22:23] op_sel:[1,1] op_sel_hi:[1,0]
	v_pk_fma_f32 v[26:27], v[24:25], v[22:23], v[222:223] op_sel:[0,0,0] op_sel_hi:[0,1,1] neg_lo:[0,0,1]
	s_waitcnt vmcnt(2)
	v_pk_add_f32 v[84:85], v[134:135], v[136:137]
	ds_write_b64 v12, v[84:85] offset:24576
	v_pk_add_f32 v[74:75], v[134:135], v[136:137] op_sel:[0,1] op_sel_hi:[1,0] neg_hi:[0,1]
	v_pk_mul_f32 v[222:223], v[74:75], v[22:23] op_sel:[1,1] op_sel_hi:[1,0]
	v_pk_fma_f32 v[84:85], v[74:75], v[22:23], v[222:223] op_sel:[0,0,0] op_sel_hi:[0,1,1] neg_lo:[0,0,1]
	ds_write_b64 v12, v[84:85] offset:57344
	v_pk_add_f32 v[74:75], v[134:135], v[136:137] neg_lo:[0,1] neg_hi:[0,1]
	v_pk_mul_f32 v[222:223], v[74:75], v[24:25] op_sel:[1,1] op_sel_hi:[1,0]
	v_pk_fma_f32 v[84:85], v[74:75], v[24:25], v[222:223] op_sel:[0,0,0] op_sel_hi:[0,1,1] neg_lo:[0,0,1]
	ds_write_b64 v13, v[84:85] offset:24576
	v_pk_add_f32 v[74:75], v[134:135], v[136:137] op_sel:[0,1] op_sel_hi:[1,0] neg_lo:[0,1]
	v_pk_mul_f32 v[222:223], v[74:75], v[26:27] op_sel:[1,1] op_sel_hi:[1,0]
	v_pk_fma_f32 v[84:85], v[74:75], v[26:27], v[222:223] op_sel:[0,0,0] op_sel_hi:[0,1,1] neg_lo:[0,0,1]
	ds_write_b64 v13, v[84:85] offset:57344
	v_pk_mul_f32 v[222:223], v[72:73], v[10:11] op_sel:[1,1] op_sel_hi:[1,0]
	v_pk_fma_f32 v[22:23], v[72:73], v[10:11], v[222:223] op_sel:[0,0,0] op_sel_hi:[0,1,1] neg_lo:[0,0,1]
	v_pk_mul_f32 v[222:223], v[22:23], v[22:23] op_sel:[1,1] op_sel_hi:[1,0]
	v_pk_fma_f32 v[24:25], v[22:23], v[22:23], v[222:223] op_sel:[0,0,0] op_sel_hi:[0,1,1] neg_lo:[0,0,1]
	v_pk_mul_f32 v[222:223], v[24:25], v[22:23] op_sel:[1,1] op_sel_hi:[1,0]
	v_pk_fma_f32 v[26:27], v[24:25], v[22:23], v[222:223] op_sel:[0,0,0] op_sel_hi:[0,1,1] neg_lo:[0,0,1]
	s_waitcnt vmcnt(0)
	v_pk_add_f32 v[84:85], v[138:139], v[140:141]
	ds_write_b64 v12, v[84:85] offset:28672
	v_pk_add_f32 v[74:75], v[138:139], v[140:141] op_sel:[0,1] op_sel_hi:[1,0] neg_hi:[0,1]
	v_pk_mul_f32 v[222:223], v[74:75], v[22:23] op_sel:[1,1] op_sel_hi:[1,0]
	v_pk_fma_f32 v[84:85], v[74:75], v[22:23], v[222:223] op_sel:[0,0,0] op_sel_hi:[0,1,1] neg_lo:[0,0,1]
	ds_write_b64 v12, v[84:85] offset:61440
	v_pk_add_f32 v[74:75], v[138:139], v[140:141] neg_lo:[0,1] neg_hi:[0,1]
	v_pk_mul_f32 v[222:223], v[74:75], v[24:25] op_sel:[1,1] op_sel_hi:[1,0]
	v_pk_fma_f32 v[84:85], v[74:75], v[24:25], v[222:223] op_sel:[0,0,0] op_sel_hi:[0,1,1] neg_lo:[0,0,1]
	ds_write_b64 v13, v[84:85] offset:28672
	v_pk_add_f32 v[74:75], v[138:139], v[140:141] op_sel:[0,1] op_sel_hi:[1,0] neg_lo:[0,1]
	v_pk_mul_f32 v[222:223], v[74:75], v[26:27] op_sel:[1,1] op_sel_hi:[1,0]
	v_pk_fma_f32 v[84:85], v[74:75], v[26:27], v[222:223] op_sel:[0,0,0] op_sel_hi:[0,1,1] neg_lo:[0,0,1]
	ds_write_b64 v13, v[84:85] offset:61440
	s_mov_b32 s12, 0x8000
	s_mov_b64 s[12:13], 0
	s_waitcnt lgkmcnt(0)
	s_barrier

; __device__ __forceinline__ void fft_mid(float2* Z, const f16x2* Hp, int tid){
;   _Pragma("unroll 4") for (int i=0;i<8;++i){ int base=(tid<<2)+i*2048;
;     u32x4 hw=*(const u32x4*)(Hp+base);
; __device__ __forceinline__ void phase_hyena(KP kp_, int hf){ asm volatile("" : "+s"(kp_)); const Params p=load_params(kp_);
;     ...
;         const f16x2* Hp = st==1 ? H0p : H1p;
;         fft_mid(Z,Hp,tid);
.Lmy_pf_skipb:
	s_cmp_eq_u32 s89, 0
	s_cbranch_scc1 .Lmy_noH
	s_cmp_eq_u32 s89, 1
	s_cselect_b32 s98, s76, s78
	s_cselect_b32 s99, s77, s79
	v_lshrrev_b32_e32 v222, 6, v154
	v_bfe_u32 v223, v154, 4, 2
	v_lshlrev_b32_e32 v222, 8, v222
	v_lshl_add_u32 v222, v223, 11, v222
	v_and_b32_e32 v223, 15, v154
	v_lshl_add_u32 v222, v223, 4, v222
	v_lshlrev_b32_e32 v222, 2, v222
	global_load_dwordx4 v[170:173], v222, s[98:99] offset:0 sc1
	global_load_dwordx4 v[174:177], v222, s[98:99] offset:16 sc1
	global_load_dwordx4 v[178:181], v222, s[98:99] offset:32 sc1
	global_load_dwordx4 v[182:185], v222, s[98:99] offset:48 sc1
	v_add_u32_e32 v223, 0x8000, v222
	global_load_dwordx4 v[104:107], v223, s[98:99] offset:0 sc1
	global_load_dwordx4 v[108:111], v223, s[98:99] offset:16 sc1
	global_load_dwordx4 v[112:115], v223, s[98:99] offset:32 sc1
	global_load_dwordx4 v[116:119], v223, s[98:99] offset:48 sc1

; template<bool INV, bool NOTW>
; HD void bf4c(float2* Z, int i0, int i1, int i2, int i3, float2 w1, float2 w2, float2 w3){
;   float2 a0=Z[i0], a1=Z[i1], a2=Z[i2], a3=Z[i3];
;   if (INV && !NOTW){ a1=cmulc(a1,w1); a2=cmulc(a2,w2); a3=cmulc(a3,w3); }
;   float2 s02=make_float2(a0.x+a2.x,a0.y+a2.y), d02=make_float2(a0.x-a2.x,a0.y-a2.y);
;   float2 s13=make_float2(a1.x+a3.x,a1.y+a3.y), d13=make_float2(a1.x-a3.x,a1.y-a3.y);
;   float2 y0=make_float2(s02.x+s13.x,s02.y+s13.y), y2=make_float2(s02.x-s13.x,s02.y-s13.y);
;   float2 ym=make_float2(d02.x+d13.y,d02.y-d13.x);
;   float2 yp=make_float2(d02.x-d13.y,d02.y+d13.x);
;   float2 y1, y3;
;   if (INV){ y1=yp; y3=ym; } else if (NOTW){ y1=ym; y3=yp; } else { y1=cmul(ym,w1); y2=cmul(y2,w2); y3=cmul(yp,w3); }
;   Z[i0]=y0; Z[i1]=y1; Z[i2]=y2; Z[i3]=y3;
; }
; HD int rev4_14(int p){ unsigned r = __brev((unsigned)p) >> 18; return (int)(((r & 0x2AAAu) >> 1) | ((r & 0x1555u) << 1)); }
; template<bool INV, int LQ, bool BARRIER=true>
; HD void fft_pass(float2* Z, const float2* twA, const float2* twB, int tid){
;   constexpr int q=1<<LQ; constexpr int tws=4096>>LQ;
;   if (LQ==12){
;     _Pragma("unroll 2") for (int i=0;i<8;++i){ int t=tid+512*i; int k=t;
;       float2 w1=cmul(twA[k>>6],twB[k&63]), w2=cmul(w1,w1), w3=cmul(w2,w1);
;       bf4c<INV,false>(Z,t,t+q,t+2*q,t+3*q,w1,w2,w3); }
;   } else if (LQ==10){
;     _Pragma("unroll") for (int e=0;e<2;++e){ int j=tid+512*e; int k=j*tws;
;       float2 w1=cmul(twA[k>>6],twB[k&63]), w2=cmul(w1,w1), w3=cmul(w2,w1);
;       _Pragma("unroll") for (int ip=0;ip<4;++ip){ int base=ip*4096+j; bf4c<INV,false>(Z,base,base+q,base+2*q,base+3*q,w1,w2,w3); } }
;   } else {
;     int j=tid&(q-1); int base0=((tid>>LQ)<<(LQ+2))+j;
;     float2 w1=make_float2(1.f,0.f), w2=w1, w3=w1;
;     if (LQ>0){ int k=j*tws; w1=cmul(twA[k>>6],twB[k&63]); w2=cmul(w1,w1); w3=cmul(w2,w1); }
;     _Pragma("unroll") for (int i=0;i<8;++i){ int base=base0+i*2048; bf4c<INV,(LQ==0)>(Z,base,base+q,base+2*q,base+3*q,w1,w2,w3); }
;   }
;   if (BARRIER) __syncthreads(); else asm volatile("s_waitcnt lgkmcnt(0)" ::: "memory");
; }
; __device__ __forceinline__ void fft_fwd_head(float2* Z, const float2* twA, const float2* twB, int tid){
;   fft_pass<false,10>(Z,twA,twB,tid); fft_pass<false,8>(Z,twA,twB,tid); fft_pass<false,6,false>(Z,twA,twB,tid);
.Lmy_pf_st1:
	global_load_dwordx4 v[228:231], v232, s[98:99]
	global_load_dwordx4 v[228:231], v233, s[98:99]
	global_load_dwordx4 v[228:231], v234, s[98:99]
	global_load_dwordx4 v[228:231], v235, s[98:99]
	s_add_u32 s98, s98, 0x1000000
	s_addc_u32 s99, s99, 0
	global_load_dwordx4 v[228:231], v232, s[98:99]
	global_load_dwordx4 v[228:231], v233, s[98:99]
	global_load_dwordx4 v[228:231], v234, s[98:99]
	global_load_dwordx4 v[228:231], v235, s[98:99]
	s_waitcnt lgkmcnt(0)
	v_mov_b32_e32 v222, 0x3f6c835e
	v_mov_b32_e32 v223, 0x3ec3ef15
	v_mov_b32_e32 v224, 0x3f3504f3
	v_mov_b32_e32 v225, 0x3f3504f3
	v_and_b32_e32 v8, 15, v154
	v_lshlrev_b32_e32 v9, 3, v8
	v_add_u32_e32 v9, 0x20800, v9
	v_mov_b32_e32 v10, 0x20a00
	ds_read_b64 v[0:1], v9
	ds_read_b64 v[2:3], v10
	s_waitcnt lgkmcnt(0)
	v_pk_mul_f32 v[250:251], v[0:1], v[2:3] op_sel:[1,1] op_sel_hi:[1,0]
	v_pk_fma_f32 v[80:81], v[0:1], v[2:3], v[250:251] op_sel:[0,0,0] op_sel_hi:[0,1,1] neg_lo:[0,0,1]
	v_pk_mul_f32 v[250:251], v[80:81], v[80:81] op_sel:[1,1] op_sel_hi:[1,0]
	v_pk_fma_f32 v[82:83], v[80:81], v[80:81], v[250:251] op_sel:[0,0,0] op_sel_hi:[0,1,1] neg_lo:[0,0,1]
	v_pk_mul_f32 v[250:251], v[82:83], v[80:81] op_sel:[1,1] op_sel_hi:[1,0]
	v_pk_fma_f32 v[84:85], v[82:83], v[80:81], v[250:251] op_sel:[0,0,0] op_sel_hi:[0,1,1] neg_lo:[0,0,1]
	v_lshlrev_b32_e32 v9, 5, v8
	v_add_u32_e32 v9, 0x20800, v9
	v_mov_b32_e32 v10, 0x20a00
	ds_read_b64 v[0:1], v9
	ds_read_b64 v[2:3], v10
	s_waitcnt lgkmcnt(0)
	v_pk_mul_f32 v[250:251], v[0:1], v[2:3] op_sel:[1,1] op_sel_hi:[1,0]
	v_pk_fma_f32 v[236:237], v[0:1], v[2:3], v[250:251] op_sel:[0,0,0] op_sel_hi:[0,1,1] neg_lo:[0,0,1]
	v_pk_mul_f32 v[250:251], v[236:237], v[236:237] op_sel:[1,1] op_sel_hi:[1,0]
	v_pk_fma_f32 v[238:239], v[236:237], v[236:237], v[250:251] op_sel:[0,0,0] op_sel_hi:[0,1,1] neg_lo:[0,0,1]
	v_pk_mul_f32 v[250:251], v[238:239], v[236:237] op_sel:[1,1] op_sel_hi:[1,0]
	v_pk_fma_f32 v[240:241], v[238:239], v[236:237], v[250:251] op_sel:[0,0,0] op_sel_hi:[0,1,1] neg_lo:[0,0,1]
	v_lshrrev_b32_e32 v226, 6, v154
	v_bfe_u32 v227, v154, 4, 2
	v_lshl_add_u32 v226, v227, 3, v226
	v_lshlrev_b32_e32 v226, 8, v226
	v_and_b32_e32 v227, 15, v154
	v_add_u32_e32 v226, v226, v227
	v_lshlrev_b32_e32 v226, 3, v226
	v_add_u32_e32 v227, 0x10000, v226
	ds_read_b64 v[0:1], v226 offset:0
	ds_read_b64 v[2:3], v226 offset:128
	ds_read_b64 v[4:5], v226 offset:256
	ds_read_b64 v[6:7], v226 offset:384
	ds_read_b64 v[8:9], v226 offset:512
	ds_read_b64 v[10:11], v226 offset:640
	ds_read_b64 v[12:13], v226 offset:768
	ds_read_b64 v[14:15], v226 offset:896
	ds_read_b64 v[16:17], v226 offset:1024
	ds_read_b64 v[18:19], v226 offset:1152
	ds_read_b64 v[20:21], v226 offset:1280
	ds_read_b64 v[22:23], v226 offset:1408
	ds_read_b64 v[24:25], v226 offset:1536
	ds_read_b64 v[26:27], v226 offset:1664
	ds_read_b64 v[28:29], v226 offset:1792
	ds_read_b64 v[30:31], v226 offset:1920
	s_waitcnt lgkmcnt(12)
	v_pk_mul_f32 v[250:251], v[4:5], v[238:239] op_sel:[1,1] op_sel_hi:[0,1]
	v_pk_fma_f32 v[4:5], v[4:5], v[238:239], v[250:251] op_sel:[0,0,0] op_sel_hi:[1,0,1] neg_hi:[0,0,1]
	v_pk_mul_f32 v[250:251], v[2:3], v[236:237] op_sel:[1,1] op_sel_hi:[0,1]
	v_pk_fma_f32 v[2:3], v[2:3], v[236:237], v[250:251] op_sel:[0,0,0] op_sel_hi:[1,0,1] neg_hi:[0,0,1]
	v_pk_mul_f32 v[250:251], v[6:7], v[240:241] op_sel:[1,1] op_sel_hi:[0,1]
	v_pk_fma_f32 v[6:7], v[6:7], v[240:241], v[250:251] op_sel:[0,0,0] op_sel_hi:[1,0,1] neg_hi:[0,0,1]
	v_pk_add_f32 v[242:243], v[0:1], v[4:5]
	v_pk_add_f32 v[244:245], v[0:1], v[4:5] neg_lo:[0,1] neg_hi:[0,1]
	v_pk_add_f32 v[246:247], v[2:3], v[6:7]
	v_pk_add_f32 v[248:249], v[2:3], v[6:7] neg_lo:[0,1] neg_hi:[0,1]
	v_pk_add_f32 v[0:1], v[242:243], v[246:247]
	v_pk_add_f32 v[2:3], v[244:245], v[248:249] op_sel:[0,1] op_sel_hi:[1,0] neg_lo:[0,1]
	v_pk_add_f32 v[4:5], v[242:243], v[246:247] neg_lo:[0,1] neg_hi:[0,1]
	v_pk_add_f32 v[6:7], v[244:245], v[248:249] op_sel:[0,1] op_sel_hi:[1,0] neg_hi:[0,1]
	s_waitcnt lgkmcnt(8)
	v_pk_mul_f32 v[250:251], v[12:13], v[238:239] op_sel:[1,1] op_sel_hi:[0,1]
	v_pk_fma_f32 v[12:13], v[12:13], v[238:239], v[250:251] op_sel:[0,0,0] op_sel_hi:[1,0,1] neg_hi:[0,0,1]
	v_pk_mul_f32 v[250:251], v[10:11], v[236:237] op_sel:[1,1] op_sel_hi:[0,1]
	v_pk_fma_f32 v[10:11], v[10:11], v[236:237], v[250:251] op_sel:[0,0,0] op_sel_hi:[1,0,1] neg_hi:[0,0,1]
	v_pk_mul_f32 v[250:251], v[14:15], v[240:241] op_sel:[1,1] op_sel_hi:[0,1]
	v_pk_fma_f32 v[14:15], v[14:15], v[240:241], v[250:251] op_sel:[0,0,0] op_sel_hi:[1,0,1] neg_hi:[0,0,1]
	v_pk_add_f32 v[242:243], v[8:9], v[12:13]
	v_pk_add_f32 v[244:245], v[8:9], v[12:13] neg_lo:[0,1] neg_hi:[0,1]
	v_pk_add_f32 v[246:247], v[10:11], v[14:15]
	v_pk_add_f32 v[248:249], v[10:11], v[14:15] neg_lo:[0,1] neg_hi:[0,1]
	v_pk_add_f32 v[8:9], v[242:243], v[246:247]
	v_pk_add_f32 v[10:11], v[244:245], v[248:249] op_sel:[0,1] op_sel_hi:[1,0] neg_lo:[0,1]
	v_pk_add_f32 v[12:13], v[242:243], v[246:247] neg_lo:[0,1] neg_hi:[0,1]
	v_pk_add_f32 v[14:15], v[244:245], v[248:249] op_sel:[0,1] op_sel_hi:[1,0] neg_hi:[0,1]
	s_waitcnt lgkmcnt(4)
	v_pk_mul_f32 v[250:251], v[20:21], v[238:239] op_sel:[1,1] op_sel_hi:[0,1]
	v_pk_fma_f32 v[20:21], v[20:21], v[238:239], v[250:251] op_sel:[0,0,0] op_sel_hi:[1,0,1] neg_hi:[0,0,1]
	v_pk_mul_f32 v[250:251], v[18:19], v[236:237] op_sel:[1,1] op_sel_hi:[0,1]
	v_pk_fma_f32 v[18:19], v[18:19], v[236:237], v[250:251] op_sel:[0,0,0] op_sel_hi:[1,0,1] neg_hi:[0,0,1]
	v_pk_mul_f32 v[250:251], v[22:23], v[240:241] op_sel:[1,1] op_sel_hi:[0,1]
	v_pk_fma_f32 v[22:23], v[22:23], v[240:241], v[250:251] op_sel:[0,0,0] op_sel_hi:[1,0,1] neg_hi:[0,0,1]
	v_pk_add_f32 v[242:243], v[16:17], v[20:21]
	v_pk_add_f32 v[244:245], v[16:17], v[20:21] neg_lo:[0,1] neg_hi:[0,1]
	v_pk_add_f32 v[246:247], v[18:19], v[22:23]
	v_pk_add_f32 v[248:249], v[18:19], v[22:23] neg_lo:[0,1] neg_hi:[0,1]
	v_pk_add_f32 v[16:17], v[242:243], v[246:247]
	v_pk_add_f32 v[18:19], v[244:245], v[248:249] op_sel:[0,1] op_sel_hi:[1,0] neg_lo:[0,1]
	v_pk_add_f32 v[20:21], v[242:243], v[246:247] neg_lo:[0,1] neg_hi:[0,1]
	v_pk_add_f32 v[22:23], v[244:245], v[248:249] op_sel:[0,1] op_sel_hi:[1,0] neg_hi:[0,1]
	s_waitcnt lgkmcnt(0)
; HD float2 cmul(float2 a, float2 b){ return make_float2(a.x*b.x - a.y*b.y, a.x*b.y + a.y*b.x); }
; HD float2 cmulc(float2 a, float2 b){ return make_float2(a.x*b.x + a.y*b.y, a.y*b.x - a.x*b.y); }
; template<bool INV, bool NOTW>
; HD void bf4c(float2* Z, int i0, int i1, int i2, int i3, float2 w1, float2 w2, float2 w3){
;   float2 a0=Z[i0], a1=Z[i1], a2=Z[i2], a3=Z[i3];
;   if (INV && !NOTW){ a1=cmulc(a1,w1); a2=cmulc(a2,w2); a3=cmulc(a3,w3); }
;   float2 s02=make_float2(a0.x+a2.x,a0.y+a2.y), d02=make_float2(a0.x-a2.x,a0.y-a2.y);
;   float2 s13=make_float2(a1.x+a3.x,a1.y+a3.y), d13=make_float2(a1.x-a3.x,a1.y-a3.y);
;   float2 y0=make_float2(s02.x+s13.x,s02.y+s13.y), y2=make_float2(s02.x-s13.x,s02.y-s13.y);
;   float2 ym=make_float2(d02.x+d13.y,d02.y-d13.x);
;   float2 yp=make_float2(d02.x-d13.y,d02.y+d13.x);
;   float2 y1, y3;
;   if (INV){ y1=yp; y3=ym; } else if (NOTW){ y1=ym; y3=yp; } else { y1=cmul(ym,w1); y2=cmul(y2,w2); y3=cmul(yp,w3); }
;   Z[i0]=y0; Z[i1]=y1; Z[i2]=y2; Z[i3]=y3;
; }
	v_pk_mul_f32 v[250:251], v[28:29], v[238:239] op_sel:[1,1] op_sel_hi:[0,1]
	v_pk_fma_f32 v[28:29], v[28:29], v[238:239], v[250:251] op_sel:[0,0,0] op_sel_hi:[1,0,1] neg_hi:[0,0,1]
	v_pk_mul_f32 v[250:251], v[26:27], v[236:237] op_sel:[1,1] op_sel_hi:[0,1]
	v_pk_fma_f32 v[26:27], v[26:27], v[236:237], v[250:251] op_sel:[0,0,0] op_sel_hi:[1,0,1] neg_hi:[0,0,1]
	v_pk_mul_f32 v[250:251], v[30:31], v[240:241] op_sel:[1,1] op_sel_hi:[0,1]
	v_pk_fma_f32 v[30:31], v[30:31], v[240:241], v[250:251] op_sel:[0,0,0] op_sel_hi:[1,0,1] neg_hi:[0,0,1]
	v_pk_add_f32 v[242:243], v[24:25], v[28:29]
	v_pk_add_f32 v[244:245], v[24:25], v[28:29] neg_lo:[0,1] neg_hi:[0,1]
	v_pk_add_f32 v[246:247], v[26:27], v[30:31]
	v_pk_add_f32 v[248:249], v[26:27], v[30:31] neg_lo:[0,1] neg_hi:[0,1]
	v_pk_add_f32 v[24:25], v[242:243], v[246:247]
	v_pk_add_f32 v[26:27], v[244:245], v[248:249] op_sel:[0,1] op_sel_hi:[1,0] neg_lo:[0,1]
	v_pk_add_f32 v[28:29], v[242:243], v[246:247] neg_lo:[0,1] neg_hi:[0,1]
	v_pk_add_f32 v[30:31], v[244:245], v[248:249] op_sel:[0,1] op_sel_hi:[1,0] neg_hi:[0,1]
	v_pk_mul_f32 v[250:251], v[16:17], v[82:83] op_sel:[1,1] op_sel_hi:[0,1]
	v_pk_fma_f32 v[16:17], v[16:17], v[82:83], v[250:251] op_sel:[0,0,0] op_sel_hi:[1,0,1] neg_hi:[0,0,1]
	v_pk_mul_f32 v[250:251], v[8:9], v[80:81] op_sel:[1,1] op_sel_hi:[0,1]
	v_pk_fma_f32 v[8:9], v[8:9], v[80:81], v[250:251] op_sel:[0,0,0] op_sel_hi:[1,0,1] neg_hi:[0,0,1]
	v_pk_mul_f32 v[250:251], v[24:25], v[84:85] op_sel:[1,1] op_sel_hi:[0,1]
	v_pk_fma_f32 v[24:25], v[24:25], v[84:85], v[250:251] op_sel:[0,0,0] op_sel_hi:[1,0,1] neg_hi:[0,0,1]
	v_pk_add_f32 v[242:243], v[0:1], v[16:17]
	v_pk_add_f32 v[244:245], v[0:1], v[16:17] neg_lo:[0,1] neg_hi:[0,1]
	v_pk_add_f32 v[246:247], v[8:9], v[24:25]
	v_pk_add_f32 v[248:249], v[8:9], v[24:25] neg_lo:[0,1] neg_hi:[0,1]
	v_pk_add_f32 v[0:1], v[242:243], v[246:247]
	ds_write_b64 v226, v[0:1] offset:0
	v_pk_add_f32 v[8:9], v[244:245], v[248:249] op_sel:[0,1] op_sel_hi:[1,0] neg_lo:[0,1]
	ds_write_b64 v226, v[8:9] offset:512
	v_pk_add_f32 v[16:17], v[242:243], v[246:247] neg_lo:[0,1] neg_hi:[0,1]
	ds_write_b64 v226, v[16:17] offset:1024
	v_pk_add_f32 v[24:25], v[244:245], v[248:249] op_sel:[0,1] op_sel_hi:[1,0] neg_hi:[0,1]
	ds_write_b64 v226, v[24:25] offset:1536
	v_pk_mul_f32 v[250:251], v[18:19], v[224:225] op_sel:[1,1] op_sel_hi:[1,0] neg_lo:[0,0] neg_hi:[0,0]
	v_pk_fma_f32 v[18:19], v[18:19], v[224:225], v[250:251] op_sel:[0,0,0] op_sel_hi:[0,1,1] neg_lo:[0,0,1] neg_hi:[0,0,0]
	v_pk_mul_f32 v[250:251], v[18:19], v[82:83] op_sel:[1,1] op_sel_hi:[0,1]
	v_pk_fma_f32 v[18:19], v[18:19], v[82:83], v[250:251] op_sel:[0,0,0] op_sel_hi:[1,0,1] neg_hi:[0,0,1]
	v_pk_mul_f32 v[250:251], v[10:11], v[222:223] op_sel:[1,1] op_sel_hi:[1,0] neg_lo:[0,0] neg_hi:[0,0]
	v_pk_fma_f32 v[10:11], v[10:11], v[222:223], v[250:251] op_sel:[0,0,0] op_sel_hi:[0,1,1] neg_lo:[0,0,1] neg_hi:[0,0,0]
	v_pk_mul_f32 v[250:251], v[10:11], v[80:81] op_sel:[1,1] op_sel_hi:[0,1]
	v_pk_fma_f32 v[10:11], v[10:11], v[80:81], v[250:251] op_sel:[0,0,0] op_sel_hi:[1,0,1] neg_hi:[0,0,1]
	v_pk_mul_f32 v[250:251], v[26:27], v[222:223] op_sel:[1,0] op_sel_hi:[1,1] neg_lo:[0,0] neg_hi:[0,0]
	v_pk_fma_f32 v[26:27], v[26:27], v[222:223], v[250:251] op_sel:[0,1,0] op_sel_hi:[0,0,1] neg_lo:[0,0,1] neg_hi:[0,0,0]
	v_pk_mul_f32 v[250:251], v[26:27], v[84:85] op_sel:[1,1] op_sel_hi:[0,1]
	v_pk_fma_f32 v[26:27], v[26:27], v[84:85], v[250:251] op_sel:[0,0,0] op_sel_hi:[1,0,1] neg_hi:[0,0,1]
	v_pk_add_f32 v[242:243], v[2:3], v[18:19]
	v_pk_add_f32 v[244:245], v[2:3], v[18:19] neg_lo:[0,1] neg_hi:[0,1]
	v_pk_add_f32 v[246:247], v[10:11], v[26:27]
	v_pk_add_f32 v[248:249], v[10:11], v[26:27] neg_lo:[0,1] neg_hi:[0,1]
	v_pk_add_f32 v[2:3], v[242:243], v[246:247]
	ds_write_b64 v226, v[2:3] offset:128
	v_pk_add_f32 v[10:11], v[244:245], v[248:249] op_sel:[0,1] op_sel_hi:[1,0] neg_lo:[0,1]
	ds_write_b64 v226, v[10:11] offset:640
	v_pk_add_f32 v[18:19], v[242:243], v[246:247] neg_lo:[0,1] neg_hi:[0,1]
	ds_write_b64 v226, v[18:19] offset:1152
	v_pk_add_f32 v[26:27], v[244:245], v[248:249] op_sel:[0,1] op_sel_hi:[1,0] neg_hi:[0,1]
	ds_write_b64 v226, v[26:27] offset:1664
	v_pk_add_f32 v[20:21], v[20:21], 0 op_sel:[1,0] op_sel_hi:[0,0] neg_lo:[1,0]
	v_pk_mul_f32 v[250:251], v[20:21], v[82:83] op_sel:[1,1] op_sel_hi:[0,1]
	v_pk_fma_f32 v[20:21], v[20:21], v[82:83], v[250:251] op_sel:[0,0,0] op_sel_hi:[1,0,1] neg_hi:[0,0,1]
	v_pk_mul_f32 v[250:251], v[12:13], v[224:225] op_sel:[1,1] op_sel_hi:[1,0] neg_lo:[0,0] neg_hi:[0,0]
	v_pk_fma_f32 v[12:13], v[12:13], v[224:225], v[250:251] op_sel:[0,0,0] op_sel_hi:[0,1,1] neg_lo:[0,0,1] neg_hi:[0,0,0]
	v_pk_mul_f32 v[250:251], v[12:13], v[80:81] op_sel:[1,1] op_sel_hi:[0,1]
	v_pk_fma_f32 v[12:13], v[12:13], v[80:81], v[250:251] op_sel:[0,0,0] op_sel_hi:[1,0,1] neg_hi:[0,0,1]
	v_pk_mul_f32 v[250:251], v[28:29], v[224:225] op_sel:[1,1] op_sel_hi:[1,0] neg_lo:[0,0] neg_hi:[0,1]
	v_pk_fma_f32 v[28:29], v[28:29], v[224:225], v[250:251] op_sel:[0,0,0] op_sel_hi:[0,1,1] neg_lo:[0,1,1] neg_hi:[0,0,0]
	v_pk_mul_f32 v[250:251], v[28:29], v[84:85] op_sel:[1,1] op_sel_hi:[0,1]
	v_pk_fma_f32 v[28:29], v[28:29], v[84:85], v[250:251] op_sel:[0,0,0] op_sel_hi:[1,0,1] neg_hi:[0,0,1]
	v_pk_add_f32 v[242:243], v[4:5], v[20:21]
	v_pk_add_f32 v[244:245], v[4:5], v[20:21] neg_lo:[0,1] neg_hi:[0,1]
	v_pk_add_f32 v[246:247], v[12:13], v[28:29]
	v_pk_add_f32 v[248:249], v[12:13], v[28:29] neg_lo:[0,1] neg_hi:[0,1]
	v_pk_add_f32 v[4:5], v[242:243], v[246:247]
	ds_write_b64 v226, v[4:5] offset:256
	v_pk_add_f32 v[12:13], v[244:245], v[248:249] op_sel:[0,1] op_sel_hi:[1,0] neg_lo:[0,1]
	ds_write_b64 v226, v[12:13] offset:768
; HD float2 cmul(float2 a, float2 b){ return make_float2(a.x*b.x - a.y*b.y, a.x*b.y + a.y*b.x); }
; HD float2 cmulc(float2 a, float2 b){ return make_float2(a.x*b.x + a.y*b.y, a.y*b.x - a.x*b.y); }
; template<bool INV, bool NOTW>
; HD void bf4c(float2* Z, int i0, int i1, int i2, int i3, float2 w1, float2 w2, float2 w3){
;   float2 a0=Z[i0], a1=Z[i1], a2=Z[i2], a3=Z[i3];
;   if (INV && !NOTW){ a1=cmulc(a1,w1); a2=cmulc(a2,w2); a3=cmulc(a3,w3); }
;   float2 s02=make_float2(a0.x+a2.x,a0.y+a2.y), d02=make_float2(a0.x-a2.x,a0.y-a2.y);
;   float2 s13=make_float2(a1.x+a3.x,a1.y+a3.y), d13=make_float2(a1.x-a3.x,a1.y-a3.y);
;   float2 y0=make_float2(s02.x+s13.x,s02.y+s13.y), y2=make_float2(s02.x-s13.x,s02.y-s13.y);
;   float2 ym=make_float2(d02.x+d13.y,d02.y-d13.x);
;   float2 yp=make_float2(d02.x-d13.y,d02.y+d13.x);
;   float2 y1, y3;
;   if (INV){ y1=yp; y3=ym; } else if (NOTW){ y1=ym; y3=yp; } else { y1=cmul(ym,w1); y2=cmul(y2,w2); y3=cmul(yp,w3); }
;   Z[i0]=y0; Z[i1]=y1; Z[i2]=y2; Z[i3]=y3;
; }
	v_pk_add_f32 v[20:21], v[242:243], v[246:247] neg_lo:[0,1] neg_hi:[0,1]
	ds_write_b64 v226, v[20:21] offset:1280
	v_pk_add_f32 v[28:29], v[244:245], v[248:249] op_sel:[0,1] op_sel_hi:[1,0] neg_hi:[0,1]
	ds_write_b64 v226, v[28:29] offset:1792
	v_pk_mul_f32 v[250:251], v[22:23], v[224:225] op_sel:[1,1] op_sel_hi:[1,0] neg_lo:[0,0] neg_hi:[0,1]
	v_pk_fma_f32 v[22:23], v[22:23], v[224:225], v[250:251] op_sel:[0,0,0] op_sel_hi:[0,1,1] neg_lo:[0,1,1] neg_hi:[0,0,0]
	v_pk_mul_f32 v[250:251], v[22:23], v[82:83] op_sel:[1,1] op_sel_hi:[0,1]
	v_pk_fma_f32 v[22:23], v[22:23], v[82:83], v[250:251] op_sel:[0,0,0] op_sel_hi:[1,0,1] neg_hi:[0,0,1]
	v_pk_mul_f32 v[250:251], v[14:15], v[222:223] op_sel:[1,0] op_sel_hi:[1,1] neg_lo:[0,0] neg_hi:[0,0]
	v_pk_fma_f32 v[14:15], v[14:15], v[222:223], v[250:251] op_sel:[0,1,0] op_sel_hi:[0,0,1] neg_lo:[0,0,1] neg_hi:[0,0,0]
	v_pk_mul_f32 v[250:251], v[14:15], v[80:81] op_sel:[1,1] op_sel_hi:[0,1]
	v_pk_fma_f32 v[14:15], v[14:15], v[80:81], v[250:251] op_sel:[0,0,0] op_sel_hi:[1,0,1] neg_hi:[0,0,1]
	v_pk_mul_f32 v[250:251], v[30:31], v[222:223] op_sel:[1,1] op_sel_hi:[1,0] neg_lo:[0,1] neg_hi:[0,1]
	v_pk_fma_f32 v[30:31], v[30:31], v[222:223], v[250:251] op_sel:[0,0,0] op_sel_hi:[0,1,1] neg_lo:[0,1,1] neg_hi:[0,1,0]
	v_pk_mul_f32 v[250:251], v[30:31], v[84:85] op_sel:[1,1] op_sel_hi:[0,1]
	v_pk_fma_f32 v[30:31], v[30:31], v[84:85], v[250:251] op_sel:[0,0,0] op_sel_hi:[1,0,1] neg_hi:[0,0,1]
	v_pk_add_f32 v[242:243], v[6:7], v[22:23]
	v_pk_add_f32 v[244:245], v[6:7], v[22:23] neg_lo:[0,1] neg_hi:[0,1]
	v_pk_add_f32 v[246:247], v[14:15], v[30:31]
	v_pk_add_f32 v[248:249], v[14:15], v[30:31] neg_lo:[0,1] neg_hi:[0,1]
	v_pk_add_f32 v[6:7], v[242:243], v[246:247]
	ds_write_b64 v226, v[6:7] offset:384
	v_pk_add_f32 v[14:15], v[244:245], v[248:249] op_sel:[0,1] op_sel_hi:[1,0] neg_lo:[0,1]
	ds_write_b64 v226, v[14:15] offset:896
	v_pk_add_f32 v[22:23], v[242:243], v[246:247] neg_lo:[0,1] neg_hi:[0,1]
	ds_write_b64 v226, v[22:23] offset:1408
	v_pk_add_f32 v[30:31], v[244:245], v[248:249] op_sel:[0,1] op_sel_hi:[1,0] neg_hi:[0,1]
	ds_write_b64 v226, v[30:31] offset:1920
	ds_read_b64 v[0:1], v227 offset:0
	ds_read_b64 v[2:3], v227 offset:128
	ds_read_b64 v[4:5], v227 offset:256
	ds_read_b64 v[6:7], v227 offset:384
	ds_read_b64 v[8:9], v227 offset:512
	ds_read_b64 v[10:11], v227 offset:640
	ds_read_b64 v[12:13], v227 offset:768
	ds_read_b64 v[14:15], v227 offset:896
	ds_read_b64 v[16:17], v227 offset:1024
	ds_read_b64 v[18:19], v227 offset:1152
	ds_read_b64 v[20:21], v227 offset:1280
	ds_read_b64 v[22:23], v227 offset:1408
	ds_read_b64 v[24:25], v227 offset:1536
	ds_read_b64 v[26:27], v227 offset:1664
	ds_read_b64 v[28:29], v227 offset:1792
	ds_read_b64 v[30:31], v227 offset:1920
	s_waitcnt lgkmcnt(12)
	v_pk_mul_f32 v[250:251], v[4:5], v[238:239] op_sel:[1,1] op_sel_hi:[0,1]
	v_pk_fma_f32 v[4:5], v[4:5], v[238:239], v[250:251] op_sel:[0,0,0] op_sel_hi:[1,0,1] neg_hi:[0,0,1]
	v_pk_mul_f32 v[250:251], v[2:3], v[236:237] op_sel:[1,1] op_sel_hi:[0,1]
	v_pk_fma_f32 v[2:3], v[2:3], v[236:237], v[250:251] op_sel:[0,0,0] op_sel_hi:[1,0,1] neg_hi:[0,0,1]
	v_pk_mul_f32 v[250:251], v[6:7], v[240:241] op_sel:[1,1] op_sel_hi:[0,1]
	v_pk_fma_f32 v[6:7], v[6:7], v[240:241], v[250:251] op_sel:[0,0,0] op_sel_hi:[1,0,1] neg_hi:[0,0,1]
	v_pk_add_f32 v[242:243], v[0:1], v[4:5]
	v_pk_add_f32 v[244:245], v[0:1], v[4:5] neg_lo:[0,1] neg_hi:[0,1]
	v_pk_add_f32 v[246:247], v[2:3], v[6:7]
	v_pk_add_f32 v[248:249], v[2:3], v[6:7] neg_lo:[0,1] neg_hi:[0,1]
	v_pk_add_f32 v[0:1], v[242:243], v[246:247]
	v_pk_add_f32 v[2:3], v[244:245], v[248:249] op_sel:[0,1] op_sel_hi:[1,0] neg_lo:[0,1]
	v_pk_add_f32 v[4:5], v[242:243], v[246:247] neg_lo:[0,1] neg_hi:[0,1]
	v_pk_add_f32 v[6:7], v[244:245], v[248:249] op_sel:[0,1] op_sel_hi:[1,0] neg_hi:[0,1]
	s_waitcnt lgkmcnt(8)
	v_pk_mul_f32 v[250:251], v[12:13], v[238:239] op_sel:[1,1] op_sel_hi:[0,1]
	v_pk_fma_f32 v[12:13], v[12:13], v[238:239], v[250:251] op_sel:[0,0,0] op_sel_hi:[1,0,1] neg_hi:[0,0,1]
	v_pk_mul_f32 v[250:251], v[10:11], v[236:237] op_sel:[1,1] op_sel_hi:[0,1]
	v_pk_fma_f32 v[10:11], v[10:11], v[236:237], v[250:251] op_sel:[0,0,0] op_sel_hi:[1,0,1] neg_hi:[0,0,1]
	v_pk_mul_f32 v[250:251], v[14:15], v[240:241] op_sel:[1,1] op_sel_hi:[0,1]
	v_pk_fma_f32 v[14:15], v[14:15], v[240:241], v[250:251] op_sel:[0,0,0] op_sel_hi:[1,0,1] neg_hi:[0,0,1]
	v_pk_add_f32 v[242:243], v[8:9], v[12:13]
	v_pk_add_f32 v[244:245], v[8:9], v[12:13] neg_lo:[0,1] neg_hi:[0,1]
	v_pk_add_f32 v[246:247], v[10:11], v[14:15]
	v_pk_add_f32 v[248:249], v[10:11], v[14:15] neg_lo:[0,1] neg_hi:[0,1]
	v_pk_add_f32 v[8:9], v[242:243], v[246:247]
	v_pk_add_f32 v[10:11], v[244:245], v[248:249] op_sel:[0,1] op_sel_hi:[1,0] neg_lo:[0,1]
	v_pk_add_f32 v[12:13], v[242:243], v[246:247] neg_lo:[0,1] neg_hi:[0,1]
	v_pk_add_f32 v[14:15], v[244:245], v[248:249] op_sel:[0,1] op_sel_hi:[1,0] neg_hi:[0,1]
	s_waitcnt lgkmcnt(4)
	v_pk_mul_f32 v[250:251], v[20:21], v[238:239] op_sel:[1,1] op_sel_hi:[0,1]
	v_pk_fma_f32 v[20:21], v[20:21], v[238:239], v[250:251] op_sel:[0,0,0] op_sel_hi:[1,0,1] neg_hi:[0,0,1]
	v_pk_mul_f32 v[250:251], v[18:19], v[236:237] op_sel:[1,1] op_sel_hi:[0,1]
	v_pk_fma_f32 v[18:19], v[18:19], v[236:237], v[250:251] op_sel:[0,0,0] op_sel_hi:[1,0,1] neg_hi:[0,0,1]
	v_pk_mul_f32 v[250:251], v[22:23], v[240:241] op_sel:[1,1] op_sel_hi:[0,1]
	v_pk_fma_f32 v[22:23], v[22:23], v[240:241], v[250:251] op_sel:[0,0,0] op_sel_hi:[1,0,1] neg_hi:[0,0,1]
	v_pk_add_f32 v[242:243], v[16:17], v[20:21]
	v_pk_add_f32 v[244:245], v[16:17], v[20:21] neg_lo:[0,1] neg_hi:[0,1]
	v_pk_add_f32 v[246:247], v[18:19], v[22:23]
	v_pk_add_f32 v[248:249], v[18:19], v[22:23] neg_lo:[0,1] neg_hi:[0,1]
	v_pk_add_f32 v[16:17], v[242:243], v[246:247]
	v_pk_add_f32 v[18:19], v[244:245], v[248:249] op_sel:[0,1] op_sel_hi:[1,0] neg_lo:[0,1]
	v_pk_add_f32 v[20:21], v[242:243], v[246:247] neg_lo:[0,1] neg_hi:[0,1]
	v_pk_add_f32 v[22:23], v[244:245], v[248:249] op_sel:[0,1] op_sel_hi:[1,0] neg_hi:[0,1]
	s_waitcnt lgkmcnt(0)
; HD float2 cmul(float2 a, float2 b){ return make_float2(a.x*b.x - a.y*b.y, a.x*b.y + a.y*b.x); }
; HD float2 cmulc(float2 a, float2 b){ return make_float2(a.x*b.x + a.y*b.y, a.y*b.x - a.x*b.y); }
; template<bool INV, bool NOTW>
; HD void bf4c(float2* Z, int i0, int i1, int i2, int i3, float2 w1, float2 w2, float2 w3){
;   float2 a0=Z[i0], a1=Z[i1], a2=Z[i2], a3=Z[i3];
;   if (INV && !NOTW){ a1=cmulc(a1,w1); a2=cmulc(a2,w2); a3=cmulc(a3,w3); }
;   float2 s02=make_float2(a0.x+a2.x,a0.y+a2.y), d02=make_float2(a0.x-a2.x,a0.y-a2.y);
;   float2 s13=make_float2(a1.x+a3.x,a1.y+a3.y), d13=make_float2(a1.x-a3.x,a1.y-a3.y);
;   float2 y0=make_float2(s02.x+s13.x,s02.y+s13.y), y2=make_float2(s02.x-s13.x,s02.y-s13.y);
;   float2 ym=make_float2(d02.x+d13.y,d02.y-d13.x);
;   float2 yp=make_float2(d02.x-d13.y,d02.y+d13.x);
;   float2 y1, y3;
;   if (INV){ y1=yp; y3=ym; } else if (NOTW){ y1=ym; y3=yp; } else { y1=cmul(ym,w1); y2=cmul(y2,w2); y3=cmul(yp,w3); }
;   Z[i0]=y0; Z[i1]=y1; Z[i2]=y2; Z[i3]=y3;
; }
	v_pk_mul_f32 v[250:251], v[28:29], v[238:239] op_sel:[1,1] op_sel_hi:[0,1]
	v_pk_fma_f32 v[28:29], v[28:29], v[238:239], v[250:251] op_sel:[0,0,0] op_sel_hi:[1,0,1] neg_hi:[0,0,1]
	v_pk_mul_f32 v[250:251], v[26:27], v[236:237] op_sel:[1,1] op_sel_hi:[0,1]
	v_pk_fma_f32 v[26:27], v[26:27], v[236:237], v[250:251] op_sel:[0,0,0] op_sel_hi:[1,0,1] neg_hi:[0,0,1]
	v_pk_mul_f32 v[250:251], v[30:31], v[240:241] op_sel:[1,1] op_sel_hi:[0,1]
	v_pk_fma_f32 v[30:31], v[30:31], v[240:241], v[250:251] op_sel:[0,0,0] op_sel_hi:[1,0,1] neg_hi:[0,0,1]
	v_pk_add_f32 v[242:243], v[24:25], v[28:29]
	v_pk_add_f32 v[244:245], v[24:25], v[28:29] neg_lo:[0,1] neg_hi:[0,1]
	v_pk_add_f32 v[246:247], v[26:27], v[30:31]
	v_pk_add_f32 v[248:249], v[26:27], v[30:31] neg_lo:[0,1] neg_hi:[0,1]
	v_pk_add_f32 v[24:25], v[242:243], v[246:247]
	v_pk_add_f32 v[26:27], v[244:245], v[248:249] op_sel:[0,1] op_sel_hi:[1,0] neg_lo:[0,1]
	v_pk_add_f32 v[28:29], v[242:243], v[246:247] neg_lo:[0,1] neg_hi:[0,1]
	v_pk_add_f32 v[30:31], v[244:245], v[248:249] op_sel:[0,1] op_sel_hi:[1,0] neg_hi:[0,1]
	v_pk_mul_f32 v[250:251], v[16:17], v[82:83] op_sel:[1,1] op_sel_hi:[0,1]
	v_pk_fma_f32 v[16:17], v[16:17], v[82:83], v[250:251] op_sel:[0,0,0] op_sel_hi:[1,0,1] neg_hi:[0,0,1]
	v_pk_mul_f32 v[250:251], v[8:9], v[80:81] op_sel:[1,1] op_sel_hi:[0,1]
	v_pk_fma_f32 v[8:9], v[8:9], v[80:81], v[250:251] op_sel:[0,0,0] op_sel_hi:[1,0,1] neg_hi:[0,0,1]
	v_pk_mul_f32 v[250:251], v[24:25], v[84:85] op_sel:[1,1] op_sel_hi:[0,1]
	v_pk_fma_f32 v[24:25], v[24:25], v[84:85], v[250:251] op_sel:[0,0,0] op_sel_hi:[1,0,1] neg_hi:[0,0,1]
	v_pk_add_f32 v[242:243], v[0:1], v[16:17]
	v_pk_add_f32 v[244:245], v[0:1], v[16:17] neg_lo:[0,1] neg_hi:[0,1]
	v_pk_add_f32 v[246:247], v[8:9], v[24:25]
	v_pk_add_f32 v[248:249], v[8:9], v[24:25] neg_lo:[0,1] neg_hi:[0,1]
	v_pk_add_f32 v[0:1], v[242:243], v[246:247]
	ds_write_b64 v227, v[0:1] offset:0
	v_pk_add_f32 v[8:9], v[244:245], v[248:249] op_sel:[0,1] op_sel_hi:[1,0] neg_lo:[0,1]
	ds_write_b64 v227, v[8:9] offset:512
	v_pk_add_f32 v[16:17], v[242:243], v[246:247] neg_lo:[0,1] neg_hi:[0,1]
	ds_write_b64 v227, v[16:17] offset:1024
	v_pk_add_f32 v[24:25], v[244:245], v[248:249] op_sel:[0,1] op_sel_hi:[1,0] neg_hi:[0,1]
	ds_write_b64 v227, v[24:25] offset:1536
	v_pk_mul_f32 v[250:251], v[18:19], v[224:225] op_sel:[1,1] op_sel_hi:[1,0] neg_lo:[0,0] neg_hi:[0,0]
	v_pk_fma_f32 v[18:19], v[18:19], v[224:225], v[250:251] op_sel:[0,0,0] op_sel_hi:[0,1,1] neg_lo:[0,0,1] neg_hi:[0,0,0]
	v_pk_mul_f32 v[250:251], v[18:19], v[82:83] op_sel:[1,1] op_sel_hi:[0,1]
	v_pk_fma_f32 v[18:19], v[18:19], v[82:83], v[250:251] op_sel:[0,0,0] op_sel_hi:[1,0,1] neg_hi:[0,0,1]
	v_pk_mul_f32 v[250:251], v[10:11], v[222:223] op_sel:[1,1] op_sel_hi:[1,0] neg_lo:[0,0] neg_hi:[0,0]
	v_pk_fma_f32 v[10:11], v[10:11], v[222:223], v[250:251] op_sel:[0,0,0] op_sel_hi:[0,1,1] neg_lo:[0,0,1] neg_hi:[0,0,0]
	v_pk_mul_f32 v[250:251], v[10:11], v[80:81] op_sel:[1,1] op_sel_hi:[0,1]
	v_pk_fma_f32 v[10:11], v[10:11], v[80:81], v[250:251] op_sel:[0,0,0] op_sel_hi:[1,0,1] neg_hi:[0,0,1]
	v_pk_mul_f32 v[250:251], v[26:27], v[222:223] op_sel:[1,0] op_sel_hi:[1,1] neg_lo:[0,0] neg_hi:[0,0]
	v_pk_fma_f32 v[26:27], v[26:27], v[222:223], v[250:251] op_sel:[0,1,0] op_sel_hi:[0,0,1] neg_lo:[0,0,1] neg_hi:[0,0,0]
	v_pk_mul_f32 v[250:251], v[26:27], v[84:85] op_sel:[1,1] op_sel_hi:[0,1]
	v_pk_fma_f32 v[26:27], v[26:27], v[84:85], v[250:251] op_sel:[0,0,0] op_sel_hi:[1,0,1] neg_hi:[0,0,1]
	v_pk_add_f32 v[242:243], v[2:3], v[18:19]
	v_pk_add_f32 v[244:245], v[2:3], v[18:19] neg_lo:[0,1] neg_hi:[0,1]
	v_pk_add_f32 v[246:247], v[10:11], v[26:27]
	v_pk_add_f32 v[248:249], v[10:11], v[26:27] neg_lo:[0,1] neg_hi:[0,1]
	v_pk_add_f32 v[2:3], v[242:243], v[246:247]
	ds_write_b64 v227, v[2:3] offset:128
	v_pk_add_f32 v[10:11], v[244:245], v[248:249] op_sel:[0,1] op_sel_hi:[1,0] neg_lo:[0,1]
	ds_write_b64 v227, v[10:11] offset:640
	v_pk_add_f32 v[18:19], v[242:243], v[246:247] neg_lo:[0,1] neg_hi:[0,1]
	ds_write_b64 v227, v[18:19] offset:1152
	v_pk_add_f32 v[26:27], v[244:245], v[248:249] op_sel:[0,1] op_sel_hi:[1,0] neg_hi:[0,1]
	ds_write_b64 v227, v[26:27] offset:1664
	v_pk_add_f32 v[20:21], v[20:21], 0 op_sel:[1,0] op_sel_hi:[0,0] neg_lo:[1,0]
	v_pk_mul_f32 v[250:251], v[20:21], v[82:83] op_sel:[1,1] op_sel_hi:[0,1]
	v_pk_fma_f32 v[20:21], v[20:21], v[82:83], v[250:251] op_sel:[0,0,0] op_sel_hi:[1,0,1] neg_hi:[0,0,1]
	v_pk_mul_f32 v[250:251], v[12:13], v[224:225] op_sel:[1,1] op_sel_hi:[1,0] neg_lo:[0,0] neg_hi:[0,0]
	v_pk_fma_f32 v[12:13], v[12:13], v[224:225], v[250:251] op_sel:[0,0,0] op_sel_hi:[0,1,1] neg_lo:[0,0,1] neg_hi:[0,0,0]
	v_pk_mul_f32 v[250:251], v[12:13], v[80:81] op_sel:[1,1] op_sel_hi:[0,1]
	v_pk_fma_f32 v[12:13], v[12:13], v[80:81], v[250:251] op_sel:[0,0,0] op_sel_hi:[1,0,1] neg_hi:[0,0,1]
	v_pk_mul_f32 v[250:251], v[28:29], v[224:225] op_sel:[1,1] op_sel_hi:[1,0] neg_lo:[0,0] neg_hi:[0,1]
	v_pk_fma_f32 v[28:29], v[28:29], v[224:225], v[250:251] op_sel:[0,0,0] op_sel_hi:[0,1,1] neg_lo:[0,1,1] neg_hi:[0,0,0]
	v_pk_mul_f32 v[250:251], v[28:29], v[84:85] op_sel:[1,1] op_sel_hi:[0,1]
	v_pk_fma_f32 v[28:29], v[28:29], v[84:85], v[250:251] op_sel:[0,0,0] op_sel_hi:[1,0,1] neg_hi:[0,0,1]
	v_pk_add_f32 v[242:243], v[4:5], v[20:21]
	v_pk_add_f32 v[244:245], v[4:5], v[20:21] neg_lo:[0,1] neg_hi:[0,1]
	v_pk_add_f32 v[246:247], v[12:13], v[28:29]
	v_pk_add_f32 v[248:249], v[12:13], v[28:29] neg_lo:[0,1] neg_hi:[0,1]
	v_pk_add_f32 v[4:5], v[242:243], v[246:247]
	ds_write_b64 v227, v[4:5] offset:256
	v_pk_add_f32 v[12:13], v[244:245], v[248:249] op_sel:[0,1] op_sel_hi:[1,0] neg_lo:[0,1]
	ds_write_b64 v227, v[12:13] offset:768
; template<bool INV, bool NOTW>
; HD void bf4c(float2* Z, int i0, int i1, int i2, int i3, float2 w1, float2 w2, float2 w3){
;   float2 a0=Z[i0], a1=Z[i1], a2=Z[i2], a3=Z[i3];
;   if (INV && !NOTW){ a1=cmulc(a1,w1); a2=cmulc(a2,w2); a3=cmulc(a3,w3); }
;   float2 s02=make_float2(a0.x+a2.x,a0.y+a2.y), d02=make_float2(a0.x-a2.x,a0.y-a2.y);
;   float2 s13=make_float2(a1.x+a3.x,a1.y+a3.y), d13=make_float2(a1.x-a3.x,a1.y-a3.y);
;   float2 y0=make_float2(s02.x+s13.x,s02.y+s13.y), y2=make_float2(s02.x-s13.x,s02.y-s13.y);
;   float2 ym=make_float2(d02.x+d13.y,d02.y-d13.x);
;   float2 yp=make_float2(d02.x-d13.y,d02.y+d13.x);
;   float2 y1, y3;
;   if (INV){ y1=yp; y3=ym; } else if (NOTW){ y1=ym; y3=yp; } else { y1=cmul(ym,w1); y2=cmul(y2,w2); y3=cmul(yp,w3); }
;   Z[i0]=y0; Z[i1]=y1; Z[i2]=y2; Z[i3]=y3;
; }
; HD int rev4_14(int p){ unsigned r = __brev((unsigned)p) >> 18; return (int)(((r & 0x2AAAu) >> 1) | ((r & 0x1555u) << 1)); }
; template<bool INV, int LQ, bool BARRIER=true>
; HD void fft_pass(float2* Z, const float2* twA, const float2* twB, int tid){
;   constexpr int q=1<<LQ; constexpr int tws=4096>>LQ;
;   if (LQ==12){
;     _Pragma("unroll 2") for (int i=0;i<8;++i){ int t=tid+512*i; int k=t;
;       float2 w1=cmul(twA[k>>6],twB[k&63]), w2=cmul(w1,w1), w3=cmul(w2,w1);
;       bf4c<INV,false>(Z,t,t+q,t+2*q,t+3*q,w1,w2,w3); }
;   } else if (LQ==10){
;     _Pragma("unroll") for (int e=0;e<2;++e){ int j=tid+512*e; int k=j*tws;
;       float2 w1=cmul(twA[k>>6],twB[k&63]), w2=cmul(w1,w1), w3=cmul(w2,w1);
;       _Pragma("unroll") for (int ip=0;ip<4;++ip){ int base=ip*4096+j; bf4c<INV,false>(Z,base,base+q,base+2*q,base+3*q,w1,w2,w3); } }
;   } else {
;     int j=tid&(q-1); int base0=((tid>>LQ)<<(LQ+2))+j;
;     float2 w1=make_float2(1.f,0.f), w2=w1, w3=w1;
;     if (LQ>0){ int k=j*tws; w1=cmul(twA[k>>6],twB[k&63]); w2=cmul(w1,w1); w3=cmul(w2,w1); }
;     _Pragma("unroll") for (int i=0;i<8;++i){ int base=base0+i*2048; bf4c<INV,(LQ==0)>(Z,base,base+q,base+2*q,base+3*q,w1,w2,w3); }
;   }
;   if (BARRIER) __syncthreads(); else asm volatile("s_waitcnt lgkmcnt(0)" ::: "memory");
; }
; __device__ __forceinline__ void fft_fwd_head(float2* Z, const float2* twA, const float2* twB, int tid){
;   fft_pass<false,10>(Z,twA,twB,tid); fft_pass<false,8>(Z,twA,twB,tid); fft_pass<false,6,false>(Z,twA,twB,tid);
	v_pk_add_f32 v[20:21], v[242:243], v[246:247] neg_lo:[0,1] neg_hi:[0,1]
	ds_write_b64 v227, v[20:21] offset:1280
	v_pk_add_f32 v[28:29], v[244:245], v[248:249] op_sel:[0,1] op_sel_hi:[1,0] neg_hi:[0,1]
	ds_write_b64 v227, v[28:29] offset:1792
	v_pk_mul_f32 v[250:251], v[22:23], v[224:225] op_sel:[1,1] op_sel_hi:[1,0] neg_lo:[0,0] neg_hi:[0,1]
	v_pk_fma_f32 v[22:23], v[22:23], v[224:225], v[250:251] op_sel:[0,0,0] op_sel_hi:[0,1,1] neg_lo:[0,1,1] neg_hi:[0,0,0]
	v_pk_mul_f32 v[250:251], v[22:23], v[82:83] op_sel:[1,1] op_sel_hi:[0,1]
	v_pk_fma_f32 v[22:23], v[22:23], v[82:83], v[250:251] op_sel:[0,0,0] op_sel_hi:[1,0,1] neg_hi:[0,0,1]
	v_pk_mul_f32 v[250:251], v[14:15], v[222:223] op_sel:[1,0] op_sel_hi:[1,1] neg_lo:[0,0] neg_hi:[0,0]
	v_pk_fma_f32 v[14:15], v[14:15], v[222:223], v[250:251] op_sel:[0,1,0] op_sel_hi:[0,0,1] neg_lo:[0,0,1] neg_hi:[0,0,0]
	v_pk_mul_f32 v[250:251], v[14:15], v[80:81] op_sel:[1,1] op_sel_hi:[0,1]
	v_pk_fma_f32 v[14:15], v[14:15], v[80:81], v[250:251] op_sel:[0,0,0] op_sel_hi:[1,0,1] neg_hi:[0,0,1]
	v_pk_mul_f32 v[250:251], v[30:31], v[222:223] op_sel:[1,1] op_sel_hi:[1,0] neg_lo:[0,1] neg_hi:[0,1]
	v_pk_fma_f32 v[30:31], v[30:31], v[222:223], v[250:251] op_sel:[0,0,0] op_sel_hi:[0,1,1] neg_lo:[0,1,1] neg_hi:[0,1,0]
	v_pk_mul_f32 v[250:251], v[30:31], v[84:85] op_sel:[1,1] op_sel_hi:[0,1]
	v_pk_fma_f32 v[30:31], v[30:31], v[84:85], v[250:251] op_sel:[0,0,0] op_sel_hi:[1,0,1] neg_hi:[0,0,1]
	v_pk_add_f32 v[242:243], v[6:7], v[22:23]
	v_pk_add_f32 v[244:245], v[6:7], v[22:23] neg_lo:[0,1] neg_hi:[0,1]
	v_pk_add_f32 v[246:247], v[14:15], v[30:31]
	v_pk_add_f32 v[248:249], v[14:15], v[30:31] neg_lo:[0,1] neg_hi:[0,1]
	v_pk_add_f32 v[6:7], v[242:243], v[246:247]
	ds_write_b64 v227, v[6:7] offset:384
	v_pk_add_f32 v[14:15], v[244:245], v[248:249] op_sel:[0,1] op_sel_hi:[1,0] neg_lo:[0,1]
	ds_write_b64 v227, v[14:15] offset:896
	v_pk_add_f32 v[22:23], v[242:243], v[246:247] neg_lo:[0,1] neg_hi:[0,1]
	ds_write_b64 v227, v[22:23] offset:1408
	v_pk_add_f32 v[30:31], v[244:245], v[248:249] op_sel:[0,1] op_sel_hi:[1,0] neg_hi:[0,1]
	ds_write_b64 v227, v[30:31] offset:1920
	s_waitcnt lgkmcnt(0)
	s_barrier
	v_and_b32_e32 v8, 255, v154
	v_lshrrev_b32_e32 v9, 4, v8
	v_lshlrev_b32_e32 v9, 3, v9
	v_add_u32_e32 v9, 0x20800, v9
	v_and_b32_e32 v10, 15, v8
	v_lshlrev_b32_e32 v10, 5, v10
	v_add_u32_e32 v10, 0x20a00, v10
	ds_read_b64 v[0:1], v9
	ds_read_b64 v[2:3], v10
	s_waitcnt lgkmcnt(0)
	v_pk_mul_f32 v[250:251], v[0:1], v[2:3] op_sel:[1,1] op_sel_hi:[1,0]
	v_pk_fma_f32 v[80:81], v[0:1], v[2:3], v[250:251] op_sel:[0,0,0] op_sel_hi:[0,1,1] neg_lo:[0,0,1]
	v_pk_mul_f32 v[250:251], v[80:81], v[80:81] op_sel:[1,1] op_sel_hi:[1,0]
	v_pk_fma_f32 v[82:83], v[80:81], v[80:81], v[250:251] op_sel:[0,0,0] op_sel_hi:[0,1,1] neg_lo:[0,0,1]
	v_pk_mul_f32 v[250:251], v[82:83], v[80:81] op_sel:[1,1] op_sel_hi:[1,0]
	v_pk_fma_f32 v[84:85], v[82:83], v[80:81], v[250:251] op_sel:[0,0,0] op_sel_hi:[0,1,1] neg_lo:[0,0,1]
	v_lshrrev_b32_e32 v9, 2, v8
	v_lshlrev_b32_e32 v9, 3, v9
	v_add_u32_e32 v9, 0x20800, v9
	v_and_b32_e32 v10, 3, v8
	v_lshlrev_b32_e32 v10, 7, v10
	v_add_u32_e32 v10, 0x20a00, v10
	ds_read_b64 v[0:1], v9
	ds_read_b64 v[2:3], v10
	s_waitcnt lgkmcnt(0)
	v_pk_mul_f32 v[250:251], v[0:1], v[2:3] op_sel:[1,1] op_sel_hi:[1,0]
	v_pk_fma_f32 v[236:237], v[0:1], v[2:3], v[250:251] op_sel:[0,0,0] op_sel_hi:[0,1,1] neg_lo:[0,0,1]
	v_pk_mul_f32 v[250:251], v[236:237], v[236:237] op_sel:[1,1] op_sel_hi:[1,0]
	v_pk_fma_f32 v[238:239], v[236:237], v[236:237], v[250:251] op_sel:[0,0,0] op_sel_hi:[0,1,1] neg_lo:[0,0,1]
	v_pk_mul_f32 v[250:251], v[238:239], v[236:237] op_sel:[1,1] op_sel_hi:[1,0]
	v_pk_fma_f32 v[240:241], v[238:239], v[236:237], v[250:251] op_sel:[0,0,0] op_sel_hi:[0,1,1] neg_lo:[0,0,1]
	v_lshrrev_b32_e32 v226, 8, v154
	v_lshlrev_b32_e32 v226, 12, v226
	v_and_b32_e32 v227, 255, v154
	v_add_u32_e32 v226, v226, v227
	v_lshlrev_b32_e32 v226, 3, v226
	v_add_u32_e32 v227, 0x10000, v226
	ds_read_b64 v[0:1], v226 offset:0
	ds_read_b64 v[2:3], v226 offset:2048
	ds_read_b64 v[4:5], v226 offset:4096
	ds_read_b64 v[6:7], v226 offset:6144
	ds_read_b64 v[8:9], v226 offset:8192
	ds_read_b64 v[10:11], v226 offset:10240
	ds_read_b64 v[12:13], v226 offset:12288
	ds_read_b64 v[14:15], v226 offset:14336
	ds_read_b64 v[16:17], v226 offset:16384
	ds_read_b64 v[18:19], v226 offset:18432
	ds_read_b64 v[20:21], v226 offset:20480
	ds_read_b64 v[22:23], v226 offset:22528
	ds_read_b64 v[24:25], v226 offset:24576
	ds_read_b64 v[26:27], v226 offset:26624
	ds_read_b64 v[28:29], v226 offset:28672
	ds_read_b64 v[30:31], v226 offset:30720
	s_waitcnt lgkmcnt(12)
	v_pk_mul_f32 v[250:251], v[4:5], v[238:239] op_sel:[1,1] op_sel_hi:[0,1]
	v_pk_fma_f32 v[4:5], v[4:5], v[238:239], v[250:251] op_sel:[0,0,0] op_sel_hi:[1,0,1] neg_hi:[0,0,1]
	v_pk_mul_f32 v[250:251], v[2:3], v[236:237] op_sel:[1,1] op_sel_hi:[0,1]
	v_pk_fma_f32 v[2:3], v[2:3], v[236:237], v[250:251] op_sel:[0,0,0] op_sel_hi:[1,0,1] neg_hi:[0,0,1]
	v_pk_mul_f32 v[250:251], v[6:7], v[240:241] op_sel:[1,1] op_sel_hi:[0,1]
	v_pk_fma_f32 v[6:7], v[6:7], v[240:241], v[250:251] op_sel:[0,0,0] op_sel_hi:[1,0,1] neg_hi:[0,0,1]
	v_pk_add_f32 v[242:243], v[0:1], v[4:5]
	v_pk_add_f32 v[244:245], v[0:1], v[4:5] neg_lo:[0,1] neg_hi:[0,1]
	v_pk_add_f32 v[246:247], v[2:3], v[6:7]
	v_pk_add_f32 v[248:249], v[2:3], v[6:7] neg_lo:[0,1] neg_hi:[0,1]
	v_pk_add_f32 v[0:1], v[242:243], v[246:247]
	v_pk_add_f32 v[2:3], v[244:245], v[248:249] op_sel:[0,1] op_sel_hi:[1,0] neg_lo:[0,1]
	v_pk_add_f32 v[4:5], v[242:243], v[246:247] neg_lo:[0,1] neg_hi:[0,1]
	v_pk_add_f32 v[6:7], v[244:245], v[248:249] op_sel:[0,1] op_sel_hi:[1,0] neg_hi:[0,1]
	s_waitcnt lgkmcnt(8)
; HD float2 cmul(float2 a, float2 b){ return make_float2(a.x*b.x - a.y*b.y, a.x*b.y + a.y*b.x); }
; HD float2 cmulc(float2 a, float2 b){ return make_float2(a.x*b.x + a.y*b.y, a.y*b.x - a.x*b.y); }
; template<bool INV, bool NOTW>
; HD void bf4c(float2* Z, int i0, int i1, int i2, int i3, float2 w1, float2 w2, float2 w3){
;   float2 a0=Z[i0], a1=Z[i1], a2=Z[i2], a3=Z[i3];
;   if (INV && !NOTW){ a1=cmulc(a1,w1); a2=cmulc(a2,w2); a3=cmulc(a3,w3); }
;   float2 s02=make_float2(a0.x+a2.x,a0.y+a2.y), d02=make_float2(a0.x-a2.x,a0.y-a2.y);
;   float2 s13=make_float2(a1.x+a3.x,a1.y+a3.y), d13=make_float2(a1.x-a3.x,a1.y-a3.y);
;   float2 y0=make_float2(s02.x+s13.x,s02.y+s13.y), y2=make_float2(s02.x-s13.x,s02.y-s13.y);
;   float2 ym=make_float2(d02.x+d13.y,d02.y-d13.x);
;   float2 yp=make_float2(d02.x-d13.y,d02.y+d13.x);
;   float2 y1, y3;
;   if (INV){ y1=yp; y3=ym; } else if (NOTW){ y1=ym; y3=yp; } else { y1=cmul(ym,w1); y2=cmul(y2,w2); y3=cmul(yp,w3); }
;   Z[i0]=y0; Z[i1]=y1; Z[i2]=y2; Z[i3]=y3;
; }
	v_pk_mul_f32 v[250:251], v[12:13], v[238:239] op_sel:[1,1] op_sel_hi:[0,1]
	v_pk_fma_f32 v[12:13], v[12:13], v[238:239], v[250:251] op_sel:[0,0,0] op_sel_hi:[1,0,1] neg_hi:[0,0,1]
	v_pk_mul_f32 v[250:251], v[10:11], v[236:237] op_sel:[1,1] op_sel_hi:[0,1]
	v_pk_fma_f32 v[10:11], v[10:11], v[236:237], v[250:251] op_sel:[0,0,0] op_sel_hi:[1,0,1] neg_hi:[0,0,1]
	v_pk_mul_f32 v[250:251], v[14:15], v[240:241] op_sel:[1,1] op_sel_hi:[0,1]
	v_pk_fma_f32 v[14:15], v[14:15], v[240:241], v[250:251] op_sel:[0,0,0] op_sel_hi:[1,0,1] neg_hi:[0,0,1]
	v_pk_add_f32 v[242:243], v[8:9], v[12:13]
	v_pk_add_f32 v[244:245], v[8:9], v[12:13] neg_lo:[0,1] neg_hi:[0,1]
	v_pk_add_f32 v[246:247], v[10:11], v[14:15]
	v_pk_add_f32 v[248:249], v[10:11], v[14:15] neg_lo:[0,1] neg_hi:[0,1]
	v_pk_add_f32 v[8:9], v[242:243], v[246:247]
	v_pk_add_f32 v[10:11], v[244:245], v[248:249] op_sel:[0,1] op_sel_hi:[1,0] neg_lo:[0,1]
	v_pk_add_f32 v[12:13], v[242:243], v[246:247] neg_lo:[0,1] neg_hi:[0,1]
	v_pk_add_f32 v[14:15], v[244:245], v[248:249] op_sel:[0,1] op_sel_hi:[1,0] neg_hi:[0,1]
	s_waitcnt lgkmcnt(4)
	v_pk_mul_f32 v[250:251], v[20:21], v[238:239] op_sel:[1,1] op_sel_hi:[0,1]
	v_pk_fma_f32 v[20:21], v[20:21], v[238:239], v[250:251] op_sel:[0,0,0] op_sel_hi:[1,0,1] neg_hi:[0,0,1]
	v_pk_mul_f32 v[250:251], v[18:19], v[236:237] op_sel:[1,1] op_sel_hi:[0,1]
	v_pk_fma_f32 v[18:19], v[18:19], v[236:237], v[250:251] op_sel:[0,0,0] op_sel_hi:[1,0,1] neg_hi:[0,0,1]
	v_pk_mul_f32 v[250:251], v[22:23], v[240:241] op_sel:[1,1] op_sel_hi:[0,1]
	v_pk_fma_f32 v[22:23], v[22:23], v[240:241], v[250:251] op_sel:[0,0,0] op_sel_hi:[1,0,1] neg_hi:[0,0,1]
	v_pk_add_f32 v[242:243], v[16:17], v[20:21]
	v_pk_add_f32 v[244:245], v[16:17], v[20:21] neg_lo:[0,1] neg_hi:[0,1]
	v_pk_add_f32 v[246:247], v[18:19], v[22:23]
	v_pk_add_f32 v[248:249], v[18:19], v[22:23] neg_lo:[0,1] neg_hi:[0,1]
	v_pk_add_f32 v[16:17], v[242:243], v[246:247]
	v_pk_add_f32 v[18:19], v[244:245], v[248:249] op_sel:[0,1] op_sel_hi:[1,0] neg_lo:[0,1]
	v_pk_add_f32 v[20:21], v[242:243], v[246:247] neg_lo:[0,1] neg_hi:[0,1]
	v_pk_add_f32 v[22:23], v[244:245], v[248:249] op_sel:[0,1] op_sel_hi:[1,0] neg_hi:[0,1]
	s_waitcnt lgkmcnt(0)
	v_pk_mul_f32 v[250:251], v[28:29], v[238:239] op_sel:[1,1] op_sel_hi:[0,1]
	v_pk_fma_f32 v[28:29], v[28:29], v[238:239], v[250:251] op_sel:[0,0,0] op_sel_hi:[1,0,1] neg_hi:[0,0,1]
	v_pk_mul_f32 v[250:251], v[26:27], v[236:237] op_sel:[1,1] op_sel_hi:[0,1]
	v_pk_fma_f32 v[26:27], v[26:27], v[236:237], v[250:251] op_sel:[0,0,0] op_sel_hi:[1,0,1] neg_hi:[0,0,1]
	v_pk_mul_f32 v[250:251], v[30:31], v[240:241] op_sel:[1,1] op_sel_hi:[0,1]
	v_pk_fma_f32 v[30:31], v[30:31], v[240:241], v[250:251] op_sel:[0,0,0] op_sel_hi:[1,0,1] neg_hi:[0,0,1]
	v_pk_add_f32 v[242:243], v[24:25], v[28:29]
	v_pk_add_f32 v[244:245], v[24:25], v[28:29] neg_lo:[0,1] neg_hi:[0,1]
	v_pk_add_f32 v[246:247], v[26:27], v[30:31]
	v_pk_add_f32 v[248:249], v[26:27], v[30:31] neg_lo:[0,1] neg_hi:[0,1]
	v_pk_add_f32 v[24:25], v[242:243], v[246:247]
	v_pk_add_f32 v[26:27], v[244:245], v[248:249] op_sel:[0,1] op_sel_hi:[1,0] neg_lo:[0,1]
	v_pk_add_f32 v[28:29], v[242:243], v[246:247] neg_lo:[0,1] neg_hi:[0,1]
	v_pk_add_f32 v[30:31], v[244:245], v[248:249] op_sel:[0,1] op_sel_hi:[1,0] neg_hi:[0,1]
	v_pk_mul_f32 v[250:251], v[16:17], v[82:83] op_sel:[1,1] op_sel_hi:[0,1]
	v_pk_fma_f32 v[16:17], v[16:17], v[82:83], v[250:251] op_sel:[0,0,0] op_sel_hi:[1,0,1] neg_hi:[0,0,1]
	v_pk_mul_f32 v[250:251], v[8:9], v[80:81] op_sel:[1,1] op_sel_hi:[0,1]
	v_pk_fma_f32 v[8:9], v[8:9], v[80:81], v[250:251] op_sel:[0,0,0] op_sel_hi:[1,0,1] neg_hi:[0,0,1]
	v_pk_mul_f32 v[250:251], v[24:25], v[84:85] op_sel:[1,1] op_sel_hi:[0,1]
	v_pk_fma_f32 v[24:25], v[24:25], v[84:85], v[250:251] op_sel:[0,0,0] op_sel_hi:[1,0,1] neg_hi:[0,0,1]
	v_pk_add_f32 v[242:243], v[0:1], v[16:17]
	v_pk_add_f32 v[244:245], v[0:1], v[16:17] neg_lo:[0,1] neg_hi:[0,1]
	v_pk_add_f32 v[246:247], v[8:9], v[24:25]
	v_pk_add_f32 v[248:249], v[8:9], v[24:25] neg_lo:[0,1] neg_hi:[0,1]
	v_pk_add_f32 v[0:1], v[242:243], v[246:247]
	ds_write_b64 v226, v[0:1] offset:0
	v_pk_add_f32 v[8:9], v[244:245], v[248:249] op_sel:[0,1] op_sel_hi:[1,0] neg_lo:[0,1]
	ds_write_b64 v226, v[8:9] offset:8192
	v_pk_add_f32 v[16:17], v[242:243], v[246:247] neg_lo:[0,1] neg_hi:[0,1]
	ds_write_b64 v226, v[16:17] offset:16384
	v_pk_add_f32 v[24:25], v[244:245], v[248:249] op_sel:[0,1] op_sel_hi:[1,0] neg_hi:[0,1]
	ds_write_b64 v226, v[24:25] offset:24576
	v_pk_mul_f32 v[250:251], v[18:19], v[224:225] op_sel:[1,1] op_sel_hi:[1,0] neg_lo:[0,0] neg_hi:[0,0]
	v_pk_fma_f32 v[18:19], v[18:19], v[224:225], v[250:251] op_sel:[0,0,0] op_sel_hi:[0,1,1] neg_lo:[0,0,1] neg_hi:[0,0,0]
	v_pk_mul_f32 v[250:251], v[18:19], v[82:83] op_sel:[1,1] op_sel_hi:[0,1]
	v_pk_fma_f32 v[18:19], v[18:19], v[82:83], v[250:251] op_sel:[0,0,0] op_sel_hi:[1,0,1] neg_hi:[0,0,1]
	v_pk_mul_f32 v[250:251], v[10:11], v[222:223] op_sel:[1,1] op_sel_hi:[1,0] neg_lo:[0,0] neg_hi:[0,0]
	v_pk_fma_f32 v[10:11], v[10:11], v[222:223], v[250:251] op_sel:[0,0,0] op_sel_hi:[0,1,1] neg_lo:[0,0,1] neg_hi:[0,0,0]
	v_pk_mul_f32 v[250:251], v[10:11], v[80:81] op_sel:[1,1] op_sel_hi:[0,1]
	v_pk_fma_f32 v[10:11], v[10:11], v[80:81], v[250:251] op_sel:[0,0,0] op_sel_hi:[1,0,1] neg_hi:[0,0,1]
	v_pk_mul_f32 v[250:251], v[26:27], v[222:223] op_sel:[1,0] op_sel_hi:[1,1] neg_lo:[0,0] neg_hi:[0,0]
	v_pk_fma_f32 v[26:27], v[26:27], v[222:223], v[250:251] op_sel:[0,1,0] op_sel_hi:[0,0,1] neg_lo:[0,0,1] neg_hi:[0,0,0]
	v_pk_mul_f32 v[250:251], v[26:27], v[84:85] op_sel:[1,1] op_sel_hi:[0,1]
	v_pk_fma_f32 v[26:27], v[26:27], v[84:85], v[250:251] op_sel:[0,0,0] op_sel_hi:[1,0,1] neg_hi:[0,0,1]
; HD float2 cmul(float2 a, float2 b){ return make_float2(a.x*b.x - a.y*b.y, a.x*b.y + a.y*b.x); }
; HD float2 cmulc(float2 a, float2 b){ return make_float2(a.x*b.x + a.y*b.y, a.y*b.x - a.x*b.y); }
; template<bool INV, bool NOTW>
; HD void bf4c(float2* Z, int i0, int i1, int i2, int i3, float2 w1, float2 w2, float2 w3){
;   float2 a0=Z[i0], a1=Z[i1], a2=Z[i2], a3=Z[i3];
;   if (INV && !NOTW){ a1=cmulc(a1,w1); a2=cmulc(a2,w2); a3=cmulc(a3,w3); }
;   float2 s02=make_float2(a0.x+a2.x,a0.y+a2.y), d02=make_float2(a0.x-a2.x,a0.y-a2.y);
;   float2 s13=make_float2(a1.x+a3.x,a1.y+a3.y), d13=make_float2(a1.x-a3.x,a1.y-a3.y);
;   float2 y0=make_float2(s02.x+s13.x,s02.y+s13.y), y2=make_float2(s02.x-s13.x,s02.y-s13.y);
;   float2 ym=make_float2(d02.x+d13.y,d02.y-d13.x);
;   float2 yp=make_float2(d02.x-d13.y,d02.y+d13.x);
;   float2 y1, y3;
;   if (INV){ y1=yp; y3=ym; } else if (NOTW){ y1=ym; y3=yp; } else { y1=cmul(ym,w1); y2=cmul(y2,w2); y3=cmul(yp,w3); }
;   Z[i0]=y0; Z[i1]=y1; Z[i2]=y2; Z[i3]=y3;
; }
	v_pk_add_f32 v[242:243], v[2:3], v[18:19]
	v_pk_add_f32 v[244:245], v[2:3], v[18:19] neg_lo:[0,1] neg_hi:[0,1]
	v_pk_add_f32 v[246:247], v[10:11], v[26:27]
	v_pk_add_f32 v[248:249], v[10:11], v[26:27] neg_lo:[0,1] neg_hi:[0,1]
	v_pk_add_f32 v[2:3], v[242:243], v[246:247]
	ds_write_b64 v226, v[2:3] offset:2048
	v_pk_add_f32 v[10:11], v[244:245], v[248:249] op_sel:[0,1] op_sel_hi:[1,0] neg_lo:[0,1]
	ds_write_b64 v226, v[10:11] offset:10240
	v_pk_add_f32 v[18:19], v[242:243], v[246:247] neg_lo:[0,1] neg_hi:[0,1]
	ds_write_b64 v226, v[18:19] offset:18432
	v_pk_add_f32 v[26:27], v[244:245], v[248:249] op_sel:[0,1] op_sel_hi:[1,0] neg_hi:[0,1]
	ds_write_b64 v226, v[26:27] offset:26624
	v_pk_add_f32 v[20:21], v[20:21], 0 op_sel:[1,0] op_sel_hi:[0,0] neg_lo:[1,0]
	v_pk_mul_f32 v[250:251], v[20:21], v[82:83] op_sel:[1,1] op_sel_hi:[0,1]
	v_pk_fma_f32 v[20:21], v[20:21], v[82:83], v[250:251] op_sel:[0,0,0] op_sel_hi:[1,0,1] neg_hi:[0,0,1]
	v_pk_mul_f32 v[250:251], v[12:13], v[224:225] op_sel:[1,1] op_sel_hi:[1,0] neg_lo:[0,0] neg_hi:[0,0]
	v_pk_fma_f32 v[12:13], v[12:13], v[224:225], v[250:251] op_sel:[0,0,0] op_sel_hi:[0,1,1] neg_lo:[0,0,1] neg_hi:[0,0,0]
	v_pk_mul_f32 v[250:251], v[12:13], v[80:81] op_sel:[1,1] op_sel_hi:[0,1]
	v_pk_fma_f32 v[12:13], v[12:13], v[80:81], v[250:251] op_sel:[0,0,0] op_sel_hi:[1,0,1] neg_hi:[0,0,1]
	v_pk_mul_f32 v[250:251], v[28:29], v[224:225] op_sel:[1,1] op_sel_hi:[1,0] neg_lo:[0,0] neg_hi:[0,1]
	v_pk_fma_f32 v[28:29], v[28:29], v[224:225], v[250:251] op_sel:[0,0,0] op_sel_hi:[0,1,1] neg_lo:[0,1,1] neg_hi:[0,0,0]
	v_pk_mul_f32 v[250:251], v[28:29], v[84:85] op_sel:[1,1] op_sel_hi:[0,1]
	v_pk_fma_f32 v[28:29], v[28:29], v[84:85], v[250:251] op_sel:[0,0,0] op_sel_hi:[1,0,1] neg_hi:[0,0,1]
	v_pk_add_f32 v[242:243], v[4:5], v[20:21]
	v_pk_add_f32 v[244:245], v[4:5], v[20:21] neg_lo:[0,1] neg_hi:[0,1]
	v_pk_add_f32 v[246:247], v[12:13], v[28:29]
	v_pk_add_f32 v[248:249], v[12:13], v[28:29] neg_lo:[0,1] neg_hi:[0,1]
	v_pk_add_f32 v[4:5], v[242:243], v[246:247]
	ds_write_b64 v226, v[4:5] offset:4096
	v_pk_add_f32 v[12:13], v[244:245], v[248:249] op_sel:[0,1] op_sel_hi:[1,0] neg_lo:[0,1]
	ds_write_b64 v226, v[12:13] offset:12288
	v_pk_add_f32 v[20:21], v[242:243], v[246:247] neg_lo:[0,1] neg_hi:[0,1]
	ds_write_b64 v226, v[20:21] offset:20480
	v_pk_add_f32 v[28:29], v[244:245], v[248:249] op_sel:[0,1] op_sel_hi:[1,0] neg_hi:[0,1]
	ds_write_b64 v226, v[28:29] offset:28672
	v_pk_mul_f32 v[250:251], v[22:23], v[224:225] op_sel:[1,1] op_sel_hi:[1,0] neg_lo:[0,0] neg_hi:[0,1]
	v_pk_fma_f32 v[22:23], v[22:23], v[224:225], v[250:251] op_sel:[0,0,0] op_sel_hi:[0,1,1] neg_lo:[0,1,1] neg_hi:[0,0,0]
	v_pk_mul_f32 v[250:251], v[22:23], v[82:83] op_sel:[1,1] op_sel_hi:[0,1]
	v_pk_fma_f32 v[22:23], v[22:23], v[82:83], v[250:251] op_sel:[0,0,0] op_sel_hi:[1,0,1] neg_hi:[0,0,1]
	v_pk_mul_f32 v[250:251], v[14:15], v[222:223] op_sel:[1,0] op_sel_hi:[1,1] neg_lo:[0,0] neg_hi:[0,0]
	v_pk_fma_f32 v[14:15], v[14:15], v[222:223], v[250:251] op_sel:[0,1,0] op_sel_hi:[0,0,1] neg_lo:[0,0,1] neg_hi:[0,0,0]
	v_pk_mul_f32 v[250:251], v[14:15], v[80:81] op_sel:[1,1] op_sel_hi:[0,1]
	v_pk_fma_f32 v[14:15], v[14:15], v[80:81], v[250:251] op_sel:[0,0,0] op_sel_hi:[1,0,1] neg_hi:[0,0,1]
	v_pk_mul_f32 v[250:251], v[30:31], v[222:223] op_sel:[1,1] op_sel_hi:[1,0] neg_lo:[0,1] neg_hi:[0,1]
	v_pk_fma_f32 v[30:31], v[30:31], v[222:223], v[250:251] op_sel:[0,0,0] op_sel_hi:[0,1,1] neg_lo:[0,1,1] neg_hi:[0,1,0]
	v_pk_mul_f32 v[250:251], v[30:31], v[84:85] op_sel:[1,1] op_sel_hi:[0,1]
	v_pk_fma_f32 v[30:31], v[30:31], v[84:85], v[250:251] op_sel:[0,0,0] op_sel_hi:[1,0,1] neg_hi:[0,0,1]
	v_pk_add_f32 v[242:243], v[6:7], v[22:23]
	v_pk_add_f32 v[244:245], v[6:7], v[22:23] neg_lo:[0,1] neg_hi:[0,1]
	v_pk_add_f32 v[246:247], v[14:15], v[30:31]
	v_pk_add_f32 v[248:249], v[14:15], v[30:31] neg_lo:[0,1] neg_hi:[0,1]
	v_pk_add_f32 v[6:7], v[242:243], v[246:247]
	ds_write_b64 v226, v[6:7] offset:6144
	v_pk_add_f32 v[14:15], v[244:245], v[248:249] op_sel:[0,1] op_sel_hi:[1,0] neg_lo:[0,1]
	ds_write_b64 v226, v[14:15] offset:14336
	v_pk_add_f32 v[22:23], v[242:243], v[246:247] neg_lo:[0,1] neg_hi:[0,1]
	ds_write_b64 v226, v[22:23] offset:22528
	v_pk_add_f32 v[30:31], v[244:245], v[248:249] op_sel:[0,1] op_sel_hi:[1,0] neg_hi:[0,1]
	ds_write_b64 v226, v[30:31] offset:30720
	ds_read_b64 v[0:1], v227 offset:0
	ds_read_b64 v[2:3], v227 offset:2048
	ds_read_b64 v[4:5], v227 offset:4096
	ds_read_b64 v[6:7], v227 offset:6144
	ds_read_b64 v[8:9], v227 offset:8192
	ds_read_b64 v[10:11], v227 offset:10240
	ds_read_b64 v[12:13], v227 offset:12288
	ds_read_b64 v[14:15], v227 offset:14336
	ds_read_b64 v[16:17], v227 offset:16384
	ds_read_b64 v[18:19], v227 offset:18432
	ds_read_b64 v[20:21], v227 offset:20480
	ds_read_b64 v[22:23], v227 offset:22528
	ds_read_b64 v[24:25], v227 offset:24576
	ds_read_b64 v[26:27], v227 offset:26624
	ds_read_b64 v[28:29], v227 offset:28672
	ds_read_b64 v[30:31], v227 offset:30720
	s_waitcnt lgkmcnt(12)
	v_pk_mul_f32 v[250:251], v[4:5], v[238:239] op_sel:[1,1] op_sel_hi:[0,1]
	v_pk_fma_f32 v[4:5], v[4:5], v[238:239], v[250:251] op_sel:[0,0,0] op_sel_hi:[1,0,1] neg_hi:[0,0,1]
	v_pk_mul_f32 v[250:251], v[2:3], v[236:237] op_sel:[1,1] op_sel_hi:[0,1]
	v_pk_fma_f32 v[2:3], v[2:3], v[236:237], v[250:251] op_sel:[0,0,0] op_sel_hi:[1,0,1] neg_hi:[0,0,1]
	v_pk_mul_f32 v[250:251], v[6:7], v[240:241] op_sel:[1,1] op_sel_hi:[0,1]
	v_pk_fma_f32 v[6:7], v[6:7], v[240:241], v[250:251] op_sel:[0,0,0] op_sel_hi:[1,0,1] neg_hi:[0,0,1]
	v_pk_add_f32 v[242:243], v[0:1], v[4:5]
	v_pk_add_f32 v[244:245], v[0:1], v[4:5] neg_lo:[0,1] neg_hi:[0,1]
	v_pk_add_f32 v[246:247], v[2:3], v[6:7]
	v_pk_add_f32 v[248:249], v[2:3], v[6:7] neg_lo:[0,1] neg_hi:[0,1]
	v_pk_add_f32 v[0:1], v[242:243], v[246:247]
	v_pk_add_f32 v[2:3], v[244:245], v[248:249] op_sel:[0,1] op_sel_hi:[1,0] neg_lo:[0,1]
	v_pk_add_f32 v[4:5], v[242:243], v[246:247] neg_lo:[0,1] neg_hi:[0,1]
	v_pk_add_f32 v[6:7], v[244:245], v[248:249] op_sel:[0,1] op_sel_hi:[1,0] neg_hi:[0,1]
	s_waitcnt lgkmcnt(8)
; HD float2 cmul(float2 a, float2 b){ return make_float2(a.x*b.x - a.y*b.y, a.x*b.y + a.y*b.x); }
; HD float2 cmulc(float2 a, float2 b){ return make_float2(a.x*b.x + a.y*b.y, a.y*b.x - a.x*b.y); }
; template<bool INV, bool NOTW>
; HD void bf4c(float2* Z, int i0, int i1, int i2, int i3, float2 w1, float2 w2, float2 w3){
;   float2 a0=Z[i0], a1=Z[i1], a2=Z[i2], a3=Z[i3];
;   if (INV && !NOTW){ a1=cmulc(a1,w1); a2=cmulc(a2,w2); a3=cmulc(a3,w3); }
;   float2 s02=make_float2(a0.x+a2.x,a0.y+a2.y), d02=make_float2(a0.x-a2.x,a0.y-a2.y);
;   float2 s13=make_float2(a1.x+a3.x,a1.y+a3.y), d13=make_float2(a1.x-a3.x,a1.y-a3.y);
;   float2 y0=make_float2(s02.x+s13.x,s02.y+s13.y), y2=make_float2(s02.x-s13.x,s02.y-s13.y);
;   float2 ym=make_float2(d02.x+d13.y,d02.y-d13.x);
;   float2 yp=make_float2(d02.x-d13.y,d02.y+d13.x);
;   float2 y1, y3;
;   if (INV){ y1=yp; y3=ym; } else if (NOTW){ y1=ym; y3=yp; } else { y1=cmul(ym,w1); y2=cmul(y2,w2); y3=cmul(yp,w3); }
;   Z[i0]=y0; Z[i1]=y1; Z[i2]=y2; Z[i3]=y3;
; }
; template<bool INV, int LQ, bool BARRIER=true>
; HD void fft_pass(float2* Z, const float2* twA, const float2* twB, int tid){
;     ...
;   } else if (LQ==10){
;     _Pragma("unroll") for (int e=0;e<2;++e){ int j=tid+512*e; int k=j*tws;
;       float2 w1=cmul(twA[k>>6],twB[k&63]), w2=cmul(w1,w1), w3=cmul(w2,w1);
;       _Pragma("unroll") for (int ip=0;ip<4;++ip){ int base=ip*4096+j; bf4c<INV,false>(Z,base,base+q,base+2*q,base+3*q,w1,w2,w3); } }
	v_pk_mul_f32 v[250:251], v[12:13], v[238:239] op_sel:[1,1] op_sel_hi:[0,1]
	v_pk_fma_f32 v[12:13], v[12:13], v[238:239], v[250:251] op_sel:[0,0,0] op_sel_hi:[1,0,1] neg_hi:[0,0,1]
	v_pk_mul_f32 v[250:251], v[10:11], v[236:237] op_sel:[1,1] op_sel_hi:[0,1]
	v_pk_fma_f32 v[10:11], v[10:11], v[236:237], v[250:251] op_sel:[0,0,0] op_sel_hi:[1,0,1] neg_hi:[0,0,1]
	v_pk_mul_f32 v[250:251], v[14:15], v[240:241] op_sel:[1,1] op_sel_hi:[0,1]
	v_pk_fma_f32 v[14:15], v[14:15], v[240:241], v[250:251] op_sel:[0,0,0] op_sel_hi:[1,0,1] neg_hi:[0,0,1]
	v_pk_add_f32 v[242:243], v[8:9], v[12:13]
	v_pk_add_f32 v[244:245], v[8:9], v[12:13] neg_lo:[0,1] neg_hi:[0,1]
	v_pk_add_f32 v[246:247], v[10:11], v[14:15]
	v_pk_add_f32 v[248:249], v[10:11], v[14:15] neg_lo:[0,1] neg_hi:[0,1]
	v_pk_add_f32 v[8:9], v[242:243], v[246:247]
	v_pk_add_f32 v[10:11], v[244:245], v[248:249] op_sel:[0,1] op_sel_hi:[1,0] neg_lo:[0,1]
	v_pk_add_f32 v[12:13], v[242:243], v[246:247] neg_lo:[0,1] neg_hi:[0,1]
	v_pk_add_f32 v[14:15], v[244:245], v[248:249] op_sel:[0,1] op_sel_hi:[1,0] neg_hi:[0,1]
	s_waitcnt lgkmcnt(4)
	v_pk_mul_f32 v[250:251], v[20:21], v[238:239] op_sel:[1,1] op_sel_hi:[0,1]
	v_pk_fma_f32 v[20:21], v[20:21], v[238:239], v[250:251] op_sel:[0,0,0] op_sel_hi:[1,0,1] neg_hi:[0,0,1]
	v_pk_mul_f32 v[250:251], v[18:19], v[236:237] op_sel:[1,1] op_sel_hi:[0,1]
	v_pk_fma_f32 v[18:19], v[18:19], v[236:237], v[250:251] op_sel:[0,0,0] op_sel_hi:[1,0,1] neg_hi:[0,0,1]
	v_pk_mul_f32 v[250:251], v[22:23], v[240:241] op_sel:[1,1] op_sel_hi:[0,1]
	v_pk_fma_f32 v[22:23], v[22:23], v[240:241], v[250:251] op_sel:[0,0,0] op_sel_hi:[1,0,1] neg_hi:[0,0,1]
	v_pk_add_f32 v[242:243], v[16:17], v[20:21]
	v_pk_add_f32 v[244:245], v[16:17], v[20:21] neg_lo:[0,1] neg_hi:[0,1]
	v_pk_add_f32 v[246:247], v[18:19], v[22:23]
	v_pk_add_f32 v[248:249], v[18:19], v[22:23] neg_lo:[0,1] neg_hi:[0,1]
	v_pk_add_f32 v[16:17], v[242:243], v[246:247]
	v_pk_add_f32 v[18:19], v[244:245], v[248:249] op_sel:[0,1] op_sel_hi:[1,0] neg_lo:[0,1]
	v_pk_add_f32 v[20:21], v[242:243], v[246:247] neg_lo:[0,1] neg_hi:[0,1]
	v_pk_add_f32 v[22:23], v[244:245], v[248:249] op_sel:[0,1] op_sel_hi:[1,0] neg_hi:[0,1]
	s_waitcnt lgkmcnt(0)
	v_pk_mul_f32 v[250:251], v[28:29], v[238:239] op_sel:[1,1] op_sel_hi:[0,1]
	v_pk_fma_f32 v[28:29], v[28:29], v[238:239], v[250:251] op_sel:[0,0,0] op_sel_hi:[1,0,1] neg_hi:[0,0,1]
	v_pk_mul_f32 v[250:251], v[26:27], v[236:237] op_sel:[1,1] op_sel_hi:[0,1]
	v_pk_fma_f32 v[26:27], v[26:27], v[236:237], v[250:251] op_sel:[0,0,0] op_sel_hi:[1,0,1] neg_hi:[0,0,1]
	v_pk_mul_f32 v[250:251], v[30:31], v[240:241] op_sel:[1,1] op_sel_hi:[0,1]
	v_pk_fma_f32 v[30:31], v[30:31], v[240:241], v[250:251] op_sel:[0,0,0] op_sel_hi:[1,0,1] neg_hi:[0,0,1]
	v_pk_add_f32 v[242:243], v[24:25], v[28:29]
	v_pk_add_f32 v[244:245], v[24:25], v[28:29] neg_lo:[0,1] neg_hi:[0,1]
	v_pk_add_f32 v[246:247], v[26:27], v[30:31]
	v_pk_add_f32 v[248:249], v[26:27], v[30:31] neg_lo:[0,1] neg_hi:[0,1]
	v_pk_add_f32 v[24:25], v[242:243], v[246:247]
	v_pk_add_f32 v[26:27], v[244:245], v[248:249] op_sel:[0,1] op_sel_hi:[1,0] neg_lo:[0,1]
	v_pk_add_f32 v[28:29], v[242:243], v[246:247] neg_lo:[0,1] neg_hi:[0,1]
	v_pk_add_f32 v[30:31], v[244:245], v[248:249] op_sel:[0,1] op_sel_hi:[1,0] neg_hi:[0,1]
	v_pk_mul_f32 v[250:251], v[16:17], v[82:83] op_sel:[1,1] op_sel_hi:[0,1]
	v_pk_fma_f32 v[16:17], v[16:17], v[82:83], v[250:251] op_sel:[0,0,0] op_sel_hi:[1,0,1] neg_hi:[0,0,1]
	v_pk_mul_f32 v[250:251], v[8:9], v[80:81] op_sel:[1,1] op_sel_hi:[0,1]
	v_pk_fma_f32 v[8:9], v[8:9], v[80:81], v[250:251] op_sel:[0,0,0] op_sel_hi:[1,0,1] neg_hi:[0,0,1]
	v_pk_mul_f32 v[250:251], v[24:25], v[84:85] op_sel:[1,1] op_sel_hi:[0,1]
	v_pk_fma_f32 v[24:25], v[24:25], v[84:85], v[250:251] op_sel:[0,0,0] op_sel_hi:[1,0,1] neg_hi:[0,0,1]
	v_pk_add_f32 v[242:243], v[0:1], v[16:17]
	v_pk_add_f32 v[244:245], v[0:1], v[16:17] neg_lo:[0,1] neg_hi:[0,1]
	v_pk_add_f32 v[246:247], v[8:9], v[24:25]
	v_pk_add_f32 v[248:249], v[8:9], v[24:25] neg_lo:[0,1] neg_hi:[0,1]
	v_pk_add_f32 v[0:1], v[242:243], v[246:247]
	ds_write_b64 v227, v[0:1] offset:0
	v_pk_add_f32 v[8:9], v[244:245], v[248:249] op_sel:[0,1] op_sel_hi:[1,0] neg_lo:[0,1]
	ds_write_b64 v227, v[8:9] offset:8192
	v_pk_add_f32 v[16:17], v[242:243], v[246:247] neg_lo:[0,1] neg_hi:[0,1]
	ds_write_b64 v227, v[16:17] offset:16384
	v_pk_add_f32 v[24:25], v[244:245], v[248:249] op_sel:[0,1] op_sel_hi:[1,0] neg_hi:[0,1]
	ds_write_b64 v227, v[24:25] offset:24576
	v_pk_mul_f32 v[250:251], v[18:19], v[224:225] op_sel:[1,1] op_sel_hi:[1,0] neg_lo:[0,0] neg_hi:[0,0]
	v_pk_fma_f32 v[18:19], v[18:19], v[224:225], v[250:251] op_sel:[0,0,0] op_sel_hi:[0,1,1] neg_lo:[0,0,1] neg_hi:[0,0,0]
	v_pk_mul_f32 v[250:251], v[18:19], v[82:83] op_sel:[1,1] op_sel_hi:[0,1]
	v_pk_fma_f32 v[18:19], v[18:19], v[82:83], v[250:251] op_sel:[0,0,0] op_sel_hi:[1,0,1] neg_hi:[0,0,1]
	v_pk_mul_f32 v[250:251], v[10:11], v[222:223] op_sel:[1,1] op_sel_hi:[1,0] neg_lo:[0,0] neg_hi:[0,0]
	v_pk_fma_f32 v[10:11], v[10:11], v[222:223], v[250:251] op_sel:[0,0,0] op_sel_hi:[0,1,1] neg_lo:[0,0,1] neg_hi:[0,0,0]
	v_pk_mul_f32 v[250:251], v[10:11], v[80:81] op_sel:[1,1] op_sel_hi:[0,1]
	v_pk_fma_f32 v[10:11], v[10:11], v[80:81], v[250:251] op_sel:[0,0,0] op_sel_hi:[1,0,1] neg_hi:[0,0,1]
	v_pk_mul_f32 v[250:251], v[26:27], v[222:223] op_sel:[1,0] op_sel_hi:[1,1] neg_lo:[0,0] neg_hi:[0,0]
	v_pk_fma_f32 v[26:27], v[26:27], v[222:223], v[250:251] op_sel:[0,1,0] op_sel_hi:[0,0,1] neg_lo:[0,0,1] neg_hi:[0,0,0]
	v_pk_mul_f32 v[250:251], v[26:27], v[84:85] op_sel:[1,1] op_sel_hi:[0,1]
	v_pk_fma_f32 v[26:27], v[26:27], v[84:85], v[250:251] op_sel:[0,0,0] op_sel_hi:[1,0,1] neg_hi:[0,0,1]
; HD float2 cmul(float2 a, float2 b){ return make_float2(a.x*b.x - a.y*b.y, a.x*b.y + a.y*b.x); }
; template<bool INV, int LQ, bool BARRIER=true>
; HD void fft_pass(float2* Z, const float2* twA, const float2* twB, int tid){
;     ...
;   } else if (LQ==10){
;     _Pragma("unroll") for (int e=0;e<2;++e){ int j=tid+512*e; int k=j*tws;
;       float2 w1=cmul(twA[k>>6],twB[k&63]), w2=cmul(w1,w1), w3=cmul(w2,w1);
;       _Pragma("unroll") for (int ip=0;ip<4;++ip){ int base=ip*4096+j; bf4c<INV,false>(Z,base,base+q,base+2*q,base+3*q,w1,w2,w3); } }
;     ...
;   if (BARRIER) __syncthreads(); else asm volatile("s_waitcnt lgkmcnt(0)" ::: "memory");
	v_pk_add_f32 v[242:243], v[2:3], v[18:19]
	v_pk_add_f32 v[244:245], v[2:3], v[18:19] neg_lo:[0,1] neg_hi:[0,1]
	v_pk_add_f32 v[246:247], v[10:11], v[26:27]
	v_pk_add_f32 v[248:249], v[10:11], v[26:27] neg_lo:[0,1] neg_hi:[0,1]
	v_pk_add_f32 v[2:3], v[242:243], v[246:247]
	ds_write_b64 v227, v[2:3] offset:2048
	v_pk_add_f32 v[10:11], v[244:245], v[248:249] op_sel:[0,1] op_sel_hi:[1,0] neg_lo:[0,1]
	ds_write_b64 v227, v[10:11] offset:10240
	v_pk_add_f32 v[18:19], v[242:243], v[246:247] neg_lo:[0,1] neg_hi:[0,1]
	ds_write_b64 v227, v[18:19] offset:18432
	v_pk_add_f32 v[26:27], v[244:245], v[248:249] op_sel:[0,1] op_sel_hi:[1,0] neg_hi:[0,1]
	ds_write_b64 v227, v[26:27] offset:26624
	v_pk_add_f32 v[20:21], v[20:21], 0 op_sel:[1,0] op_sel_hi:[0,0] neg_lo:[1,0]
	v_pk_mul_f32 v[250:251], v[20:21], v[82:83] op_sel:[1,1] op_sel_hi:[0,1]
	v_pk_fma_f32 v[20:21], v[20:21], v[82:83], v[250:251] op_sel:[0,0,0] op_sel_hi:[1,0,1] neg_hi:[0,0,1]
	v_pk_mul_f32 v[250:251], v[12:13], v[224:225] op_sel:[1,1] op_sel_hi:[1,0] neg_lo:[0,0] neg_hi:[0,0]
	v_pk_fma_f32 v[12:13], v[12:13], v[224:225], v[250:251] op_sel:[0,0,0] op_sel_hi:[0,1,1] neg_lo:[0,0,1] neg_hi:[0,0,0]
	v_pk_mul_f32 v[250:251], v[12:13], v[80:81] op_sel:[1,1] op_sel_hi:[0,1]
	v_pk_fma_f32 v[12:13], v[12:13], v[80:81], v[250:251] op_sel:[0,0,0] op_sel_hi:[1,0,1] neg_hi:[0,0,1]
	v_pk_mul_f32 v[250:251], v[28:29], v[224:225] op_sel:[1,1] op_sel_hi:[1,0] neg_lo:[0,0] neg_hi:[0,1]
	v_pk_fma_f32 v[28:29], v[28:29], v[224:225], v[250:251] op_sel:[0,0,0] op_sel_hi:[0,1,1] neg_lo:[0,1,1] neg_hi:[0,0,0]
	v_pk_mul_f32 v[250:251], v[28:29], v[84:85] op_sel:[1,1] op_sel_hi:[0,1]
	v_pk_fma_f32 v[28:29], v[28:29], v[84:85], v[250:251] op_sel:[0,0,0] op_sel_hi:[1,0,1] neg_hi:[0,0,1]
	v_pk_add_f32 v[242:243], v[4:5], v[20:21]
	v_pk_add_f32 v[244:245], v[4:5], v[20:21] neg_lo:[0,1] neg_hi:[0,1]
	v_pk_add_f32 v[246:247], v[12:13], v[28:29]
	v_pk_add_f32 v[248:249], v[12:13], v[28:29] neg_lo:[0,1] neg_hi:[0,1]
	v_pk_add_f32 v[4:5], v[242:243], v[246:247]
	ds_write_b64 v227, v[4:5] offset:4096
	v_pk_add_f32 v[12:13], v[244:245], v[248:249] op_sel:[0,1] op_sel_hi:[1,0] neg_lo:[0,1]
	ds_write_b64 v227, v[12:13] offset:12288
	v_pk_add_f32 v[20:21], v[242:243], v[246:247] neg_lo:[0,1] neg_hi:[0,1]
	ds_write_b64 v227, v[20:21] offset:20480
	v_pk_add_f32 v[28:29], v[244:245], v[248:249] op_sel:[0,1] op_sel_hi:[1,0] neg_hi:[0,1]
	ds_write_b64 v227, v[28:29] offset:28672
	v_pk_mul_f32 v[250:251], v[22:23], v[224:225] op_sel:[1,1] op_sel_hi:[1,0] neg_lo:[0,0] neg_hi:[0,1]
	v_pk_fma_f32 v[22:23], v[22:23], v[224:225], v[250:251] op_sel:[0,0,0] op_sel_hi:[0,1,1] neg_lo:[0,1,1] neg_hi:[0,0,0]
	v_pk_mul_f32 v[250:251], v[22:23], v[82:83] op_sel:[1,1] op_sel_hi:[0,1]
	v_pk_fma_f32 v[22:23], v[22:23], v[82:83], v[250:251] op_sel:[0,0,0] op_sel_hi:[1,0,1] neg_hi:[0,0,1]
	v_pk_mul_f32 v[250:251], v[14:15], v[222:223] op_sel:[1,0] op_sel_hi:[1,1] neg_lo:[0,0] neg_hi:[0,0]
	v_pk_fma_f32 v[14:15], v[14:15], v[222:223], v[250:251] op_sel:[0,1,0] op_sel_hi:[0,0,1] neg_lo:[0,0,1] neg_hi:[0,0,0]
	v_pk_mul_f32 v[250:251], v[14:15], v[80:81] op_sel:[1,1] op_sel_hi:[0,1]
	v_pk_fma_f32 v[14:15], v[14:15], v[80:81], v[250:251] op_sel:[0,0,0] op_sel_hi:[1,0,1] neg_hi:[0,0,1]
	v_pk_mul_f32 v[250:251], v[30:31], v[222:223] op_sel:[1,1] op_sel_hi:[1,0] neg_lo:[0,1] neg_hi:[0,1]
	v_pk_fma_f32 v[30:31], v[30:31], v[222:223], v[250:251] op_sel:[0,0,0] op_sel_hi:[0,1,1] neg_lo:[0,1,1] neg_hi:[0,1,0]
	v_pk_mul_f32 v[250:251], v[30:31], v[84:85] op_sel:[1,1] op_sel_hi:[0,1]
	v_pk_fma_f32 v[30:31], v[30:31], v[84:85], v[250:251] op_sel:[0,0,0] op_sel_hi:[1,0,1] neg_hi:[0,0,1]
	v_pk_add_f32 v[242:243], v[6:7], v[22:23]
	v_pk_add_f32 v[244:245], v[6:7], v[22:23] neg_lo:[0,1] neg_hi:[0,1]
	v_pk_add_f32 v[246:247], v[14:15], v[30:31]
	v_pk_add_f32 v[248:249], v[14:15], v[30:31] neg_lo:[0,1] neg_hi:[0,1]
	v_pk_add_f32 v[6:7], v[242:243], v[246:247]
	ds_write_b64 v227, v[6:7] offset:6144
	v_pk_add_f32 v[14:15], v[244:245], v[248:249] op_sel:[0,1] op_sel_hi:[1,0] neg_lo:[0,1]
	ds_write_b64 v227, v[14:15] offset:14336
	v_pk_add_f32 v[22:23], v[242:243], v[246:247] neg_lo:[0,1] neg_hi:[0,1]
	ds_write_b64 v227, v[22:23] offset:22528
	v_pk_add_f32 v[30:31], v[244:245], v[248:249] op_sel:[0,1] op_sel_hi:[1,0] neg_hi:[0,1]
	ds_write_b64 v227, v[30:31] offset:30720
	s_waitcnt lgkmcnt(0)
	s_barrier
	s_mov_b64 s[12:13], -1
	s_and_b64 vcc, exec, s[50:51]
	s_cbranch_vccz .LBB0_1340
; __device__ __forceinline__ float bf2f(u16 h){ return __uint_as_float(((unsigned)h)<<16); }
; HD float2 cmul(float2 a, float2 b){ return make_float2(a.x*b.x - a.y*b.y, a.x*b.y + a.y*b.x); }
; HD float2 cmulc(float2 a, float2 b){ return make_float2(a.x*b.x + a.y*b.y, a.y*b.x - a.x*b.y); }
; HD void inv12_half(const float2* Z, const float2* twA, const float2* twB, int t, float2& x0, float2& x1){
;   float2 w1=cmul(twA[t>>6],twB[t&63]), w2=cmul(w1,w1), w3=cmul(w2,w1);
;   float2 b0=Z[t], b1=cmulc(Z[t+4096],w1), b2=cmulc(Z[t+8192],w2), b3=cmulc(Z[t+12288],w3);
;   float2 s02=make_float2(b0.x+b2.x,b0.y+b2.y), d02=make_float2(b0.x-b2.x,b0.y-b2.y);
;   float2 s13=make_float2(b1.x+b3.x,b1.y+b3.y), d13=make_float2(b1.x-b3.x,b1.y-b3.y);
;   x0=make_float2(s02.x+s13.x,s02.y+s13.y);
;   x1=make_float2(d02.x-d13.y,d02.y+d13.x);
; }
; __device__ __forceinline__ void phase_hyena(KP kp_, int hf){ asm volatile("" : "+s"(kp_)); const Params p=load_params(kp_);
;     ...
;         } else { int tq=tid; asm volatile("" : "+v"(tq));
;           _Pragma("unroll 4") for (int i=0;i<8;++i){ int tb=tq+512*i; float2 xr[2]; inv12_half(Z,twA,twB,tb,xr[0],xr[1]);
;             _Pragma("unroll") for (int hh=0;hh<2;++hh){ int t=tb+hh*4096;
;               float x0=hconv3(r2,t,wb0,wb1,wb2,bb_), x1=hconv3(r2+8192,t,wb0,wb1,wb2,bb_);
;               float2 y=xr[hh]; y.x*=(1.f/16384.f); y.y*=(1.f/16384.f); float2 z1=Zs[t];
;               float o0=x0*(y.x+z1.x*bias1)*bf2f(rz[t]); float o1=x1*(y.y+z1.y*bias1)*bf2f(rz[8192+t]);
;               ybT[(size_t)c*16384+t]=f2bf(o0); ybT[(size_t)c*16384+8192+t]=f2bf(o1); } }
	v_lshlrev_b32_e32 v0, 1, v86
	v_add_u32_e32 v1, 0x1000, v0
	v_add_u32_e32 v2, 0x2000, v0
	v_add_u32_e32 v4, 0x3000, v0
	v_lshlrev_b32_e32 v5, 3, v86
	v_mov_b32_e32 v8, v5
	v_add_u32_e32 v9, 0x10000, v5
	v_lshrrev_b32_e32 v7, 6, v86
	v_lshl_add_u32 v7, v7, 3, s88
	v_and_b32_e32 v108, 63, v86
	v_lshl_add_u32 v108, v108, 3, s91
	ds_read_b64 v[10:11], v108
	s_add_u32 s12, s72, 0x4000
	s_addc_u32 s13, s73, 0
	s_add_u32 s50, s80, 0x8000
	s_addc_u32 s51, s81, 0
	v_mov_b32_e32 v107, 0
	global_load_ushort v228, v0, s[96:97] offset:0
	global_load_ushort v230, v0, s[74:75] offset:0
	global_load_ushort v232, v0, s[72:73] offset:0
	global_load_ushort v234, v0, s[12:13] offset:0
	global_load_ushort v229, v2, s[96:97] offset:0
	global_load_ushort v231, v2, s[74:75] offset:0
	global_load_ushort v233, v2, s[72:73] offset:0
	global_load_ushort v235, v2, s[12:13] offset:0
	v_mov_b32_e32 v6, v5
	global_load_dwordx2 v[236:237], v6, s[80:81] sc1
	global_load_dwordx2 v[238:239], v6, s[50:51] sc1
	ds_read_b64 v[12:13], v7 offset:0
	ds_read_b64 v[14:15], v8 offset:0
	ds_read_b64 v[16:17], v8 offset:32768
	ds_read_b64 v[18:19], v9 offset:0
	ds_read_b64 v[20:21], v9 offset:32768
	global_load_ushort v240, v0, s[96:97] offset:1024
	global_load_ushort v242, v0, s[74:75] offset:1024
	global_load_ushort v244, v0, s[72:73] offset:1024
	global_load_ushort v246, v0, s[12:13] offset:1024
	global_load_ushort v241, v2, s[96:97] offset:1024
	global_load_ushort v243, v2, s[74:75] offset:1024
	global_load_ushort v245, v2, s[72:73] offset:1024
	global_load_ushort v247, v2, s[12:13] offset:1024
	v_add_u32_e32 v6, 0x1000, v5
	global_load_dwordx2 v[248:249], v6, s[80:81] sc1
	global_load_dwordx2 v[250:251], v6, s[50:51] sc1
	ds_read_b64 v[58:59], v7 offset:64
	ds_read_b64 v[60:61], v8 offset:4096
	ds_read_b64 v[62:63], v8 offset:36864
	ds_read_b64 v[64:65], v9 offset:4096
	ds_read_b64 v[66:67], v9 offset:36864
	s_waitcnt lgkmcnt(5)
	v_pk_mul_f32 v[222:223], v[12:13], v[10:11] op_sel:[1,1] op_sel_hi:[1,0]
	v_pk_fma_f32 v[22:23], v[12:13], v[10:11], v[222:223] op_sel:[0,0,0] op_sel_hi:[0,1,1] neg_lo:[0,0,1]
	v_pk_mul_f32 v[222:223], v[22:23], v[22:23] op_sel:[1,1] op_sel_hi:[1,0]
	v_pk_fma_f32 v[24:25], v[22:23], v[22:23], v[222:223] op_sel:[0,0,0] op_sel_hi:[0,1,1] neg_lo:[0,0,1]
	v_pk_mul_f32 v[222:223], v[24:25], v[22:23] op_sel:[1,1] op_sel_hi:[1,0]
	v_pk_fma_f32 v[26:27], v[24:25], v[22:23], v[222:223] op_sel:[0,0,0] op_sel_hi:[0,1,1] neg_lo:[0,0,1]
	v_pk_mul_f32 v[222:223], v[16:17], v[22:23] op_sel:[1,1] op_sel_hi:[0,1]
	v_pk_fma_f32 v[28:29], v[16:17], v[22:23], v[222:223] op_sel:[0,0,0] op_sel_hi:[1,0,1] neg_hi:[0,0,1]
	v_pk_mul_f32 v[222:223], v[18:19], v[24:25] op_sel:[1,1] op_sel_hi:[0,1]
	v_pk_fma_f32 v[30:31], v[18:19], v[24:25], v[222:223] op_sel:[0,0,0] op_sel_hi:[1,0,1] neg_hi:[0,0,1]
	v_pk_mul_f32 v[222:223], v[20:21], v[26:27] op_sel:[1,1] op_sel_hi:[0,1]
	v_pk_fma_f32 v[68:69], v[20:21], v[26:27], v[222:223] op_sel:[0,0,0] op_sel_hi:[1,0,1] neg_hi:[0,0,1]
	v_pk_add_f32 v[70:71], v[14:15], v[30:31]
	v_pk_add_f32 v[72:73], v[14:15], v[30:31] neg_lo:[0,1] neg_hi:[0,1]
	v_pk_add_f32 v[74:75], v[28:29], v[68:69]
	v_pk_add_f32 v[80:81], v[28:29], v[68:69] neg_lo:[0,1] neg_hi:[0,1]
	v_pk_add_f32 v[82:83], v[70:71], v[74:75]
	v_pk_add_f32 v[84:85], v[72:73], v[80:81] op_sel:[0,1] op_sel_hi:[1,0] neg_lo:[0,1]
	s_waitcnt vmcnt(10)
	v_lshlrev_b32_e32 v224, 16, v228
	v_mov_b32_e32 v225, 0
	v_mov_b32_e32 v226, 0
	v_mov_b32_dpp v225, v224 wave_shr:1 row_mask:0xf bank_mask:0xf
	v_mov_b32_dpp v226, v224 wave_shl:1 row_mask:0xf bank_mask:0xf
	v_mul_f32_e32 v227, v88, v224
	v_fmac_f32_e32 v227, v87, v225
	v_fmac_f32_e32 v227, v89, v226
	v_add_f32_e32 v94, v90, v227
	v_lshlrev_b32_e32 v224, 16, v230
	v_mov_b32_e32 v225, 0
	v_mov_b32_e32 v226, 0
	v_mov_b32_dpp v225, v224 wave_shr:1 row_mask:0xf bank_mask:0xf
	v_mov_b32_dpp v226, v224 wave_shl:1 row_mask:0xf bank_mask:0xf
	v_mul_f32_e32 v227, v88, v224
	v_fmac_f32_e32 v227, v87, v225
	v_fmac_f32_e32 v227, v89, v226
	v_add_f32_e32 v97, v90, v227
	v_lshlrev_b32_e32 v224, 16, v229
	v_mov_b32_e32 v225, 0
	v_mov_b32_e32 v226, 0
	v_mov_b32_dpp v225, v224 wave_shr:1 row_mask:0xf bank_mask:0xf
	v_mov_b32_dpp v226, v224 wave_shl:1 row_mask:0xf bank_mask:0xf
	v_mul_f32_e32 v227, v88, v224
	v_fmac_f32_e32 v227, v87, v225
	v_fmac_f32_e32 v227, v89, v226
	v_add_f32_e32 v98, v90, v227
	v_lshlrev_b32_e32 v224, 16, v231
	v_mov_b32_e32 v225, 0
	v_mov_b32_e32 v226, 0
	v_mov_b32_dpp v225, v224 wave_shr:1 row_mask:0xf bank_mask:0xf
	v_mov_b32_dpp v226, v224 wave_shl:1 row_mask:0xf bank_mask:0xf
	v_mul_f32_e32 v227, v88, v224
	v_fmac_f32_e32 v227, v87, v225
	v_fmac_f32_e32 v227, v89, v226
	v_add_f32_e32 v100, v90, v227
	v_mul_f32_e32 v108, v91, v236
	v_fmac_f32_e32 v108, 0x38800000, v82
	v_mul_f32_e32 v108, v94, v108
	v_lshlrev_b32_e32 v109, 16, v232
	v_mul_f32_e32 v108, v108, v109
	v_cvt_pk_bf16_f32 v224, v108, v108
	v_mul_f32_e32 v108, v91, v237
	v_fmac_f32_e32 v108, 0x38800000, v83
	v_mul_f32_e32 v108, v108, v97
	v_lshlrev_b32_e32 v109, 16, v234
	v_mul_f32_e32 v108, v108, v109
	v_cvt_pk_bf16_f32 v225, v108, v108
	v_add_u32_e32 v106, 0x0, v0
	v_lshl_add_u64 v[104:105], v[54:55], 0, v[106:107]
	global_store_short v[104:105], v224, off
	v_lshl_add_u64 v[104:105], v[56:57], 0, v[106:107]
	global_store_short v[104:105], v225, off
	v_mul_f32_e32 v108, v91, v238
	v_fmac_f32_e32 v108, 0x38800000, v84
	v_mul_f32_e32 v108, v98, v108
	v_lshlrev_b32_e32 v109, 16, v233
	v_mul_f32_e32 v108, v108, v109
	v_cvt_pk_bf16_f32 v224, v108, v108
	v_mul_f32_e32 v108, v91, v239
	v_fmac_f32_e32 v108, 0x38800000, v85
	v_mul_f32_e32 v108, v108, v100
	v_lshlrev_b32_e32 v109, 16, v235
	v_mul_f32_e32 v108, v108, v109
	v_cvt_pk_bf16_f32 v225, v108, v108
	v_add_u32_e32 v106, 0x0, v2
	v_lshl_add_u64 v[104:105], v[54:55], 0, v[106:107]
	global_store_short v[104:105], v224, off
	v_lshl_add_u64 v[104:105], v[56:57], 0, v[106:107]
	global_store_short v[104:105], v225, off
	global_load_ushort v228, v0, s[96:97] offset:2048
	global_load_ushort v230, v0, s[74:75] offset:2048
	global_load_ushort v232, v0, s[72:73] offset:2048
	global_load_ushort v234, v0, s[12:13] offset:2048
	global_load_ushort v229, v2, s[96:97] offset:2048
	global_load_ushort v231, v2, s[74:75] offset:2048
	global_load_ushort v233, v2, s[72:73] offset:2048
	global_load_ushort v235, v2, s[12:13] offset:2048
	v_add_u32_e32 v6, 0x2000, v5
	global_load_dwordx2 v[236:237], v6, s[80:81] sc1
	global_load_dwordx2 v[238:239], v6, s[50:51] sc1
	ds_read_b64 v[12:13], v7 offset:128
	ds_read_b64 v[14:15], v8 offset:8192
	ds_read_b64 v[16:17], v8 offset:40960
	ds_read_b64 v[18:19], v9 offset:8192
	ds_read_b64 v[20:21], v9 offset:40960
	s_waitcnt lgkmcnt(5)
; __device__ __forceinline__ float bf2f(u16 h){ return __uint_as_float(((unsigned)h)<<16); }
; HD float2 cmul(float2 a, float2 b){ return make_float2(a.x*b.x - a.y*b.y, a.x*b.y + a.y*b.x); }
; HD float2 cmulc(float2 a, float2 b){ return make_float2(a.x*b.x + a.y*b.y, a.y*b.x - a.x*b.y); }
; HD void inv12_half(const float2* Z, const float2* twA, const float2* twB, int t, float2& x0, float2& x1){
;   float2 w1=cmul(twA[t>>6],twB[t&63]), w2=cmul(w1,w1), w3=cmul(w2,w1);
;   float2 b0=Z[t], b1=cmulc(Z[t+4096],w1), b2=cmulc(Z[t+8192],w2), b3=cmulc(Z[t+12288],w3);
;   float2 s02=make_float2(b0.x+b2.x,b0.y+b2.y), d02=make_float2(b0.x-b2.x,b0.y-b2.y);
;   float2 s13=make_float2(b1.x+b3.x,b1.y+b3.y), d13=make_float2(b1.x-b3.x,b1.y-b3.y);
;   x0=make_float2(s02.x+s13.x,s02.y+s13.y);
;   x1=make_float2(d02.x-d13.y,d02.y+d13.x);
; }
; __device__ __forceinline__ void phase_hyena(KP kp_, int hf){ asm volatile("" : "+s"(kp_)); const Params p=load_params(kp_);
;     ...
;         } else { int tq=tid; asm volatile("" : "+v"(tq));
;           _Pragma("unroll 4") for (int i=0;i<8;++i){ int tb=tq+512*i; float2 xr[2]; inv12_half(Z,twA,twB,tb,xr[0],xr[1]);
;             _Pragma("unroll") for (int hh=0;hh<2;++hh){ int t=tb+hh*4096;
;               float x0=hconv3(r2,t,wb0,wb1,wb2,bb_), x1=hconv3(r2+8192,t,wb0,wb1,wb2,bb_);
;               float2 y=xr[hh]; y.x*=(1.f/16384.f); y.y*=(1.f/16384.f); float2 z1=Zs[t];
;               float o0=x0*(y.x+z1.x*bias1)*bf2f(rz[t]); float o1=x1*(y.y+z1.y*bias1)*bf2f(rz[8192+t]);
;               ybT[(size_t)c*16384+t]=f2bf(o0); ybT[(size_t)c*16384+8192+t]=f2bf(o1); } }
	v_pk_mul_f32 v[222:223], v[58:59], v[10:11] op_sel:[1,1] op_sel_hi:[1,0]
	v_pk_fma_f32 v[22:23], v[58:59], v[10:11], v[222:223] op_sel:[0,0,0] op_sel_hi:[0,1,1] neg_lo:[0,0,1]
	v_pk_mul_f32 v[222:223], v[22:23], v[22:23] op_sel:[1,1] op_sel_hi:[1,0]
	v_pk_fma_f32 v[24:25], v[22:23], v[22:23], v[222:223] op_sel:[0,0,0] op_sel_hi:[0,1,1] neg_lo:[0,0,1]
	v_pk_mul_f32 v[222:223], v[24:25], v[22:23] op_sel:[1,1] op_sel_hi:[1,0]
	v_pk_fma_f32 v[26:27], v[24:25], v[22:23], v[222:223] op_sel:[0,0,0] op_sel_hi:[0,1,1] neg_lo:[0,0,1]
	v_pk_mul_f32 v[222:223], v[62:63], v[22:23] op_sel:[1,1] op_sel_hi:[0,1]
	v_pk_fma_f32 v[28:29], v[62:63], v[22:23], v[222:223] op_sel:[0,0,0] op_sel_hi:[1,0,1] neg_hi:[0,0,1]
	v_pk_mul_f32 v[222:223], v[64:65], v[24:25] op_sel:[1,1] op_sel_hi:[0,1]
	v_pk_fma_f32 v[30:31], v[64:65], v[24:25], v[222:223] op_sel:[0,0,0] op_sel_hi:[1,0,1] neg_hi:[0,0,1]
	v_pk_mul_f32 v[222:223], v[66:67], v[26:27] op_sel:[1,1] op_sel_hi:[0,1]
	v_pk_fma_f32 v[68:69], v[66:67], v[26:27], v[222:223] op_sel:[0,0,0] op_sel_hi:[1,0,1] neg_hi:[0,0,1]
	v_pk_add_f32 v[70:71], v[60:61], v[30:31]
	v_pk_add_f32 v[72:73], v[60:61], v[30:31] neg_lo:[0,1] neg_hi:[0,1]
	v_pk_add_f32 v[74:75], v[28:29], v[68:69]
	v_pk_add_f32 v[80:81], v[28:29], v[68:69] neg_lo:[0,1] neg_hi:[0,1]
	v_pk_add_f32 v[82:83], v[70:71], v[74:75]
	v_pk_add_f32 v[84:85], v[72:73], v[80:81] op_sel:[0,1] op_sel_hi:[1,0] neg_lo:[0,1]
	s_waitcnt vmcnt(14)
	v_lshlrev_b32_e32 v224, 16, v240
	v_mov_b32_e32 v225, 0
	v_mov_b32_e32 v226, 0
	v_mov_b32_dpp v225, v224 wave_shr:1 row_mask:0xf bank_mask:0xf
	v_mov_b32_dpp v226, v224 wave_shl:1 row_mask:0xf bank_mask:0xf
	v_mul_f32_e32 v227, v88, v224
	v_fmac_f32_e32 v227, v87, v225
	v_fmac_f32_e32 v227, v89, v226
	v_add_f32_e32 v94, v90, v227
	v_lshlrev_b32_e32 v224, 16, v242
	v_mov_b32_e32 v225, 0
	v_mov_b32_e32 v226, 0
	v_mov_b32_dpp v225, v224 wave_shr:1 row_mask:0xf bank_mask:0xf
	v_mov_b32_dpp v226, v224 wave_shl:1 row_mask:0xf bank_mask:0xf
	v_mul_f32_e32 v227, v88, v224
	v_fmac_f32_e32 v227, v87, v225
	v_fmac_f32_e32 v227, v89, v226
	v_add_f32_e32 v97, v90, v227
	v_lshlrev_b32_e32 v224, 16, v241
	v_mov_b32_e32 v225, 0
	v_mov_b32_e32 v226, 0
	v_mov_b32_dpp v225, v224 wave_shr:1 row_mask:0xf bank_mask:0xf
	v_mov_b32_dpp v226, v224 wave_shl:1 row_mask:0xf bank_mask:0xf
	v_mul_f32_e32 v227, v88, v224
	v_fmac_f32_e32 v227, v87, v225
	v_fmac_f32_e32 v227, v89, v226
	v_add_f32_e32 v98, v90, v227
	v_lshlrev_b32_e32 v224, 16, v243
	v_mov_b32_e32 v225, 0
	v_mov_b32_e32 v226, 0
	v_mov_b32_dpp v225, v224 wave_shr:1 row_mask:0xf bank_mask:0xf
	v_mov_b32_dpp v226, v224 wave_shl:1 row_mask:0xf bank_mask:0xf
	v_mul_f32_e32 v227, v88, v224
	v_fmac_f32_e32 v227, v87, v225
	v_fmac_f32_e32 v227, v89, v226
	v_add_f32_e32 v100, v90, v227
	v_mul_f32_e32 v108, v91, v248
	v_fmac_f32_e32 v108, 0x38800000, v82
	v_mul_f32_e32 v108, v94, v108
	v_lshlrev_b32_e32 v109, 16, v244
	v_mul_f32_e32 v108, v108, v109
	v_cvt_pk_bf16_f32 v224, v108, v108
	v_mul_f32_e32 v108, v91, v249
	v_fmac_f32_e32 v108, 0x38800000, v83
	v_mul_f32_e32 v108, v108, v97
	v_lshlrev_b32_e32 v109, 16, v246
	v_mul_f32_e32 v108, v108, v109
	v_cvt_pk_bf16_f32 v225, v108, v108
	v_add_u32_e32 v106, 0x400, v0
	v_lshl_add_u64 v[104:105], v[54:55], 0, v[106:107]
	global_store_short v[104:105], v224, off
	v_lshl_add_u64 v[104:105], v[56:57], 0, v[106:107]
	global_store_short v[104:105], v225, off
	v_mul_f32_e32 v108, v91, v250
	v_fmac_f32_e32 v108, 0x38800000, v84
	v_mul_f32_e32 v108, v98, v108
	v_lshlrev_b32_e32 v109, 16, v245
	v_mul_f32_e32 v108, v108, v109
	v_cvt_pk_bf16_f32 v224, v108, v108
	v_mul_f32_e32 v108, v91, v251
	v_fmac_f32_e32 v108, 0x38800000, v85
	v_mul_f32_e32 v108, v108, v100
	v_lshlrev_b32_e32 v109, 16, v247
	v_mul_f32_e32 v108, v108, v109
	v_cvt_pk_bf16_f32 v225, v108, v108
	v_add_u32_e32 v106, 0x400, v2
	v_lshl_add_u64 v[104:105], v[54:55], 0, v[106:107]
	global_store_short v[104:105], v224, off
	v_lshl_add_u64 v[104:105], v[56:57], 0, v[106:107]
	global_store_short v[104:105], v225, off
	global_load_ushort v240, v0, s[96:97] offset:3072
	global_load_ushort v242, v0, s[74:75] offset:3072
	global_load_ushort v244, v0, s[72:73] offset:3072
	global_load_ushort v246, v0, s[12:13] offset:3072
	global_load_ushort v241, v2, s[96:97] offset:3072
	global_load_ushort v243, v2, s[74:75] offset:3072
	global_load_ushort v245, v2, s[72:73] offset:3072
	global_load_ushort v247, v2, s[12:13] offset:3072
	v_add_u32_e32 v6, 0x3000, v5
	global_load_dwordx2 v[248:249], v6, s[80:81] sc1
	global_load_dwordx2 v[250:251], v6, s[50:51] sc1
	ds_read_b64 v[58:59], v7 offset:192
	ds_read_b64 v[60:61], v8 offset:12288
	ds_read_b64 v[62:63], v8 offset:45056
	ds_read_b64 v[64:65], v9 offset:12288
	ds_read_b64 v[66:67], v9 offset:45056
	s_waitcnt lgkmcnt(5)
	v_pk_mul_f32 v[222:223], v[12:13], v[10:11] op_sel:[1,1] op_sel_hi:[1,0]
	v_pk_fma_f32 v[22:23], v[12:13], v[10:11], v[222:223] op_sel:[0,0,0] op_sel_hi:[0,1,1] neg_lo:[0,0,1]
	v_pk_mul_f32 v[222:223], v[22:23], v[22:23] op_sel:[1,1] op_sel_hi:[1,0]
	v_pk_fma_f32 v[24:25], v[22:23], v[22:23], v[222:223] op_sel:[0,0,0] op_sel_hi:[0,1,1] neg_lo:[0,0,1]
	v_pk_mul_f32 v[222:223], v[24:25], v[22:23] op_sel:[1,1] op_sel_hi:[1,0]
	v_pk_fma_f32 v[26:27], v[24:25], v[22:23], v[222:223] op_sel:[0,0,0] op_sel_hi:[0,1,1] neg_lo:[0,0,1]
	v_pk_mul_f32 v[222:223], v[16:17], v[22:23] op_sel:[1,1] op_sel_hi:[0,1]
	v_pk_fma_f32 v[28:29], v[16:17], v[22:23], v[222:223] op_sel:[0,0,0] op_sel_hi:[1,0,1] neg_hi:[0,0,1]
	v_pk_mul_f32 v[222:223], v[18:19], v[24:25] op_sel:[1,1] op_sel_hi:[0,1]
	v_pk_fma_f32 v[30:31], v[18:19], v[24:25], v[222:223] op_sel:[0,0,0] op_sel_hi:[1,0,1] neg_hi:[0,0,1]
	v_pk_mul_f32 v[222:223], v[20:21], v[26:27] op_sel:[1,1] op_sel_hi:[0,1]
	v_pk_fma_f32 v[68:69], v[20:21], v[26:27], v[222:223] op_sel:[0,0,0] op_sel_hi:[1,0,1] neg_hi:[0,0,1]
	v_pk_add_f32 v[70:71], v[14:15], v[30:31]
	v_pk_add_f32 v[72:73], v[14:15], v[30:31] neg_lo:[0,1] neg_hi:[0,1]
	v_pk_add_f32 v[74:75], v[28:29], v[68:69]
	v_pk_add_f32 v[80:81], v[28:29], v[68:69] neg_lo:[0,1] neg_hi:[0,1]
	v_pk_add_f32 v[82:83], v[70:71], v[74:75]
	v_pk_add_f32 v[84:85], v[72:73], v[80:81] op_sel:[0,1] op_sel_hi:[1,0] neg_lo:[0,1]
	s_waitcnt vmcnt(14)
; __device__ __forceinline__ float bf2f(u16 h){ return __uint_as_float(((unsigned)h)<<16); }
; HD float2 cmul(float2 a, float2 b){ return make_float2(a.x*b.x - a.y*b.y, a.x*b.y + a.y*b.x); }
; HD float2 cmulc(float2 a, float2 b){ return make_float2(a.x*b.x + a.y*b.y, a.y*b.x - a.x*b.y); }
; HD void inv12_half(const float2* Z, const float2* twA, const float2* twB, int t, float2& x0, float2& x1){
;   float2 w1=cmul(twA[t>>6],twB[t&63]), w2=cmul(w1,w1), w3=cmul(w2,w1);
;   float2 b0=Z[t], b1=cmulc(Z[t+4096],w1), b2=cmulc(Z[t+8192],w2), b3=cmulc(Z[t+12288],w3);
;   float2 s02=make_float2(b0.x+b2.x,b0.y+b2.y), d02=make_float2(b0.x-b2.x,b0.y-b2.y);
;   float2 s13=make_float2(b1.x+b3.x,b1.y+b3.y), d13=make_float2(b1.x-b3.x,b1.y-b3.y);
;   x0=make_float2(s02.x+s13.x,s02.y+s13.y);
;   x1=make_float2(d02.x-d13.y,d02.y+d13.x);
; }
; __device__ __forceinline__ void phase_hyena(KP kp_, int hf){ asm volatile("" : "+s"(kp_)); const Params p=load_params(kp_);
;     ...
;         } else { int tq=tid; asm volatile("" : "+v"(tq));
;           _Pragma("unroll 4") for (int i=0;i<8;++i){ int tb=tq+512*i; float2 xr[2]; inv12_half(Z,twA,twB,tb,xr[0],xr[1]);
;             _Pragma("unroll") for (int hh=0;hh<2;++hh){ int t=tb+hh*4096;
;               float x0=hconv3(r2,t,wb0,wb1,wb2,bb_), x1=hconv3(r2+8192,t,wb0,wb1,wb2,bb_);
;               float2 y=xr[hh]; y.x*=(1.f/16384.f); y.y*=(1.f/16384.f); float2 z1=Zs[t];
;               float o0=x0*(y.x+z1.x*bias1)*bf2f(rz[t]); float o1=x1*(y.y+z1.y*bias1)*bf2f(rz[8192+t]);
;               ybT[(size_t)c*16384+t]=f2bf(o0); ybT[(size_t)c*16384+8192+t]=f2bf(o1); } }
	v_lshlrev_b32_e32 v224, 16, v228
	v_mov_b32_e32 v225, 0
	v_mov_b32_e32 v226, 0
	v_mov_b32_dpp v225, v224 wave_shr:1 row_mask:0xf bank_mask:0xf
	v_mov_b32_dpp v226, v224 wave_shl:1 row_mask:0xf bank_mask:0xf
	v_mul_f32_e32 v227, v88, v224
	v_fmac_f32_e32 v227, v87, v225
	v_fmac_f32_e32 v227, v89, v226
	v_add_f32_e32 v94, v90, v227
	v_lshlrev_b32_e32 v224, 16, v230
	v_mov_b32_e32 v225, 0
	v_mov_b32_e32 v226, 0
	v_mov_b32_dpp v225, v224 wave_shr:1 row_mask:0xf bank_mask:0xf
	v_mov_b32_dpp v226, v224 wave_shl:1 row_mask:0xf bank_mask:0xf
	v_mul_f32_e32 v227, v88, v224
	v_fmac_f32_e32 v227, v87, v225
	v_fmac_f32_e32 v227, v89, v226
	v_add_f32_e32 v97, v90, v227
	v_lshlrev_b32_e32 v224, 16, v229
	v_mov_b32_e32 v225, 0
	v_mov_b32_e32 v226, 0
	v_mov_b32_dpp v225, v224 wave_shr:1 row_mask:0xf bank_mask:0xf
	v_mov_b32_dpp v226, v224 wave_shl:1 row_mask:0xf bank_mask:0xf
	v_mul_f32_e32 v227, v88, v224
	v_fmac_f32_e32 v227, v87, v225
	v_fmac_f32_e32 v227, v89, v226
	v_add_f32_e32 v98, v90, v227
	v_lshlrev_b32_e32 v224, 16, v231
	v_mov_b32_e32 v225, 0
	v_mov_b32_e32 v226, 0
	v_mov_b32_dpp v225, v224 wave_shr:1 row_mask:0xf bank_mask:0xf
	v_mov_b32_dpp v226, v224 wave_shl:1 row_mask:0xf bank_mask:0xf
	v_mul_f32_e32 v227, v88, v224
	v_fmac_f32_e32 v227, v87, v225
	v_fmac_f32_e32 v227, v89, v226
	v_add_f32_e32 v100, v90, v227
	v_mul_f32_e32 v108, v91, v236
	v_fmac_f32_e32 v108, 0x38800000, v82
	v_mul_f32_e32 v108, v94, v108
	v_lshlrev_b32_e32 v109, 16, v232
	v_mul_f32_e32 v108, v108, v109
	v_cvt_pk_bf16_f32 v224, v108, v108
	v_mul_f32_e32 v108, v91, v237
	v_fmac_f32_e32 v108, 0x38800000, v83
	v_mul_f32_e32 v108, v108, v97
	v_lshlrev_b32_e32 v109, 16, v234
	v_mul_f32_e32 v108, v108, v109
	v_cvt_pk_bf16_f32 v225, v108, v108
	v_add_u32_e32 v106, 0x800, v0
	v_lshl_add_u64 v[104:105], v[54:55], 0, v[106:107]
	global_store_short v[104:105], v224, off
	v_lshl_add_u64 v[104:105], v[56:57], 0, v[106:107]
	global_store_short v[104:105], v225, off
	v_mul_f32_e32 v108, v91, v238
	v_fmac_f32_e32 v108, 0x38800000, v84
	v_mul_f32_e32 v108, v98, v108
	v_lshlrev_b32_e32 v109, 16, v233
	v_mul_f32_e32 v108, v108, v109
	v_cvt_pk_bf16_f32 v224, v108, v108
	v_mul_f32_e32 v108, v91, v239
	v_fmac_f32_e32 v108, 0x38800000, v85
	v_mul_f32_e32 v108, v108, v100
	v_lshlrev_b32_e32 v109, 16, v235
	v_mul_f32_e32 v108, v108, v109
	v_cvt_pk_bf16_f32 v225, v108, v108
	v_add_u32_e32 v106, 0x800, v2
	v_lshl_add_u64 v[104:105], v[54:55], 0, v[106:107]
	global_store_short v[104:105], v224, off
	v_lshl_add_u64 v[104:105], v[56:57], 0, v[106:107]
	global_store_short v[104:105], v225, off
	global_load_ushort v228, v1, s[96:97] offset:0
	global_load_ushort v230, v1, s[74:75] offset:0
	global_load_ushort v232, v1, s[72:73] offset:0
	global_load_ushort v234, v1, s[12:13] offset:0
	global_load_ushort v229, v4, s[96:97] offset:0
	global_load_ushort v231, v4, s[74:75] offset:0
	global_load_ushort v233, v4, s[72:73] offset:0
	global_load_ushort v235, v4, s[12:13] offset:0
	v_add_u32_e32 v6, 0x4000, v5
	global_load_dwordx2 v[236:237], v6, s[80:81] sc1
	global_load_dwordx2 v[238:239], v6, s[50:51] sc1
	ds_read_b64 v[12:13], v7 offset:256
	ds_read_b64 v[14:15], v8 offset:16384
	ds_read_b64 v[16:17], v8 offset:49152
	ds_read_b64 v[18:19], v9 offset:16384
	ds_read_b64 v[20:21], v9 offset:49152
	s_waitcnt lgkmcnt(5)
	v_pk_mul_f32 v[222:223], v[58:59], v[10:11] op_sel:[1,1] op_sel_hi:[1,0]
	v_pk_fma_f32 v[22:23], v[58:59], v[10:11], v[222:223] op_sel:[0,0,0] op_sel_hi:[0,1,1] neg_lo:[0,0,1]
	v_pk_mul_f32 v[222:223], v[22:23], v[22:23] op_sel:[1,1] op_sel_hi:[1,0]
	v_pk_fma_f32 v[24:25], v[22:23], v[22:23], v[222:223] op_sel:[0,0,0] op_sel_hi:[0,1,1] neg_lo:[0,0,1]
	v_pk_mul_f32 v[222:223], v[24:25], v[22:23] op_sel:[1,1] op_sel_hi:[1,0]
	v_pk_fma_f32 v[26:27], v[24:25], v[22:23], v[222:223] op_sel:[0,0,0] op_sel_hi:[0,1,1] neg_lo:[0,0,1]
	v_pk_mul_f32 v[222:223], v[62:63], v[22:23] op_sel:[1,1] op_sel_hi:[0,1]
	v_pk_fma_f32 v[28:29], v[62:63], v[22:23], v[222:223] op_sel:[0,0,0] op_sel_hi:[1,0,1] neg_hi:[0,0,1]
	v_pk_mul_f32 v[222:223], v[64:65], v[24:25] op_sel:[1,1] op_sel_hi:[0,1]
	v_pk_fma_f32 v[30:31], v[64:65], v[24:25], v[222:223] op_sel:[0,0,0] op_sel_hi:[1,0,1] neg_hi:[0,0,1]
	v_pk_mul_f32 v[222:223], v[66:67], v[26:27] op_sel:[1,1] op_sel_hi:[0,1]
	v_pk_fma_f32 v[68:69], v[66:67], v[26:27], v[222:223] op_sel:[0,0,0] op_sel_hi:[1,0,1] neg_hi:[0,0,1]
	v_pk_add_f32 v[70:71], v[60:61], v[30:31]
	v_pk_add_f32 v[72:73], v[60:61], v[30:31] neg_lo:[0,1] neg_hi:[0,1]
	v_pk_add_f32 v[74:75], v[28:29], v[68:69]
	v_pk_add_f32 v[80:81], v[28:29], v[68:69] neg_lo:[0,1] neg_hi:[0,1]
	v_pk_add_f32 v[82:83], v[70:71], v[74:75]
	v_pk_add_f32 v[84:85], v[72:73], v[80:81] op_sel:[0,1] op_sel_hi:[1,0] neg_lo:[0,1]
	s_waitcnt vmcnt(14)
; __device__ __forceinline__ float bf2f(u16 h){ return __uint_as_float(((unsigned)h)<<16); }
; HD float2 cmul(float2 a, float2 b){ return make_float2(a.x*b.x - a.y*b.y, a.x*b.y + a.y*b.x); }
; HD float2 cmulc(float2 a, float2 b){ return make_float2(a.x*b.x + a.y*b.y, a.y*b.x - a.x*b.y); }
; HD void inv12_half(const float2* Z, const float2* twA, const float2* twB, int t, float2& x0, float2& x1){
;   float2 w1=cmul(twA[t>>6],twB[t&63]), w2=cmul(w1,w1), w3=cmul(w2,w1);
;   float2 b0=Z[t], b1=cmulc(Z[t+4096],w1), b2=cmulc(Z[t+8192],w2), b3=cmulc(Z[t+12288],w3);
;   float2 s02=make_float2(b0.x+b2.x,b0.y+b2.y), d02=make_float2(b0.x-b2.x,b0.y-b2.y);
;   float2 s13=make_float2(b1.x+b3.x,b1.y+b3.y), d13=make_float2(b1.x-b3.x,b1.y-b3.y);
;   x0=make_float2(s02.x+s13.x,s02.y+s13.y);
;   x1=make_float2(d02.x-d13.y,d02.y+d13.x);
; }
; __device__ __forceinline__ void phase_hyena(KP kp_, int hf){ asm volatile("" : "+s"(kp_)); const Params p=load_params(kp_);
;     ...
;         } else { int tq=tid; asm volatile("" : "+v"(tq));
;           _Pragma("unroll 4") for (int i=0;i<8;++i){ int tb=tq+512*i; float2 xr[2]; inv12_half(Z,twA,twB,tb,xr[0],xr[1]);
;             _Pragma("unroll") for (int hh=0;hh<2;++hh){ int t=tb+hh*4096;
;               float x0=hconv3(r2,t,wb0,wb1,wb2,bb_), x1=hconv3(r2+8192,t,wb0,wb1,wb2,bb_);
;               float2 y=xr[hh]; y.x*=(1.f/16384.f); y.y*=(1.f/16384.f); float2 z1=Zs[t];
;               float o0=x0*(y.x+z1.x*bias1)*bf2f(rz[t]); float o1=x1*(y.y+z1.y*bias1)*bf2f(rz[8192+t]);
;               ybT[(size_t)c*16384+t]=f2bf(o0); ybT[(size_t)c*16384+8192+t]=f2bf(o1); } }
	v_lshlrev_b32_e32 v224, 16, v240
	v_mov_b32_e32 v225, 0
	v_mov_b32_e32 v226, 0
	v_mov_b32_dpp v225, v224 wave_shr:1 row_mask:0xf bank_mask:0xf
	v_mov_b32_dpp v226, v224 wave_shl:1 row_mask:0xf bank_mask:0xf
	v_mul_f32_e32 v227, v88, v224
	v_fmac_f32_e32 v227, v87, v225
	v_fmac_f32_e32 v227, v89, v226
	v_add_f32_e32 v94, v90, v227
	v_lshlrev_b32_e32 v224, 16, v242
	v_mov_b32_e32 v225, 0
	v_mov_b32_e32 v226, 0
	v_mov_b32_dpp v225, v224 wave_shr:1 row_mask:0xf bank_mask:0xf
	v_mov_b32_dpp v226, v224 wave_shl:1 row_mask:0xf bank_mask:0xf
	v_mul_f32_e32 v227, v88, v224
	v_fmac_f32_e32 v227, v87, v225
	v_fmac_f32_e32 v227, v89, v226
	v_add_f32_e32 v97, v90, v227
	v_lshlrev_b32_e32 v224, 16, v241
	v_mov_b32_e32 v225, 0
	v_mov_b32_e32 v226, 0
	v_mov_b32_dpp v225, v224 wave_shr:1 row_mask:0xf bank_mask:0xf
	v_mov_b32_dpp v226, v224 wave_shl:1 row_mask:0xf bank_mask:0xf
	v_mul_f32_e32 v227, v88, v224
	v_fmac_f32_e32 v227, v87, v225
	v_fmac_f32_e32 v227, v89, v226
	v_add_f32_e32 v98, v90, v227
	v_lshlrev_b32_e32 v224, 16, v243
	v_mov_b32_e32 v225, 0
	v_mov_b32_e32 v226, 0
	v_mov_b32_dpp v225, v224 wave_shr:1 row_mask:0xf bank_mask:0xf
	v_mov_b32_dpp v226, v224 wave_shl:1 row_mask:0xf bank_mask:0xf
	v_mul_f32_e32 v227, v88, v224
	v_fmac_f32_e32 v227, v87, v225
	v_fmac_f32_e32 v227, v89, v226
	v_add_f32_e32 v100, v90, v227
	v_mul_f32_e32 v108, v91, v248
	v_fmac_f32_e32 v108, 0x38800000, v82
	v_mul_f32_e32 v108, v94, v108
	v_lshlrev_b32_e32 v109, 16, v244
	v_mul_f32_e32 v108, v108, v109
	v_cvt_pk_bf16_f32 v224, v108, v108
	v_mul_f32_e32 v108, v91, v249
	v_fmac_f32_e32 v108, 0x38800000, v83
	v_mul_f32_e32 v108, v108, v97
	v_lshlrev_b32_e32 v109, 16, v246
	v_mul_f32_e32 v108, v108, v109
	v_cvt_pk_bf16_f32 v225, v108, v108
	v_add_u32_e32 v106, 0xc00, v0
	v_lshl_add_u64 v[104:105], v[54:55], 0, v[106:107]
	global_store_short v[104:105], v224, off
	v_lshl_add_u64 v[104:105], v[56:57], 0, v[106:107]
	global_store_short v[104:105], v225, off
	v_mul_f32_e32 v108, v91, v250
	v_fmac_f32_e32 v108, 0x38800000, v84
	v_mul_f32_e32 v108, v98, v108
	v_lshlrev_b32_e32 v109, 16, v245
	v_mul_f32_e32 v108, v108, v109
	v_cvt_pk_bf16_f32 v224, v108, v108
	v_mul_f32_e32 v108, v91, v251
	v_fmac_f32_e32 v108, 0x38800000, v85
	v_mul_f32_e32 v108, v108, v100
	v_lshlrev_b32_e32 v109, 16, v247
	v_mul_f32_e32 v108, v108, v109
	v_cvt_pk_bf16_f32 v225, v108, v108
	v_add_u32_e32 v106, 0xc00, v2
	v_lshl_add_u64 v[104:105], v[54:55], 0, v[106:107]
	global_store_short v[104:105], v224, off
	v_lshl_add_u64 v[104:105], v[56:57], 0, v[106:107]
	global_store_short v[104:105], v225, off
	global_load_ushort v240, v1, s[96:97] offset:1024
	global_load_ushort v242, v1, s[74:75] offset:1024
	global_load_ushort v244, v1, s[72:73] offset:1024
	global_load_ushort v246, v1, s[12:13] offset:1024
	global_load_ushort v241, v4, s[96:97] offset:1024
	global_load_ushort v243, v4, s[74:75] offset:1024
	global_load_ushort v245, v4, s[72:73] offset:1024
	global_load_ushort v247, v4, s[12:13] offset:1024
	v_add_u32_e32 v6, 0x5000, v5
	global_load_dwordx2 v[248:249], v6, s[80:81] sc1
	global_load_dwordx2 v[250:251], v6, s[50:51] sc1
	ds_read_b64 v[58:59], v7 offset:320
	ds_read_b64 v[60:61], v8 offset:20480
	ds_read_b64 v[62:63], v8 offset:53248
	ds_read_b64 v[64:65], v9 offset:20480
	ds_read_b64 v[66:67], v9 offset:53248
	s_waitcnt lgkmcnt(5)
	v_pk_mul_f32 v[222:223], v[12:13], v[10:11] op_sel:[1,1] op_sel_hi:[1,0]
	v_pk_fma_f32 v[22:23], v[12:13], v[10:11], v[222:223] op_sel:[0,0,0] op_sel_hi:[0,1,1] neg_lo:[0,0,1]
	v_pk_mul_f32 v[222:223], v[22:23], v[22:23] op_sel:[1,1] op_sel_hi:[1,0]
	v_pk_fma_f32 v[24:25], v[22:23], v[22:23], v[222:223] op_sel:[0,0,0] op_sel_hi:[0,1,1] neg_lo:[0,0,1]
	v_pk_mul_f32 v[222:223], v[24:25], v[22:23] op_sel:[1,1] op_sel_hi:[1,0]
	v_pk_fma_f32 v[26:27], v[24:25], v[22:23], v[222:223] op_sel:[0,0,0] op_sel_hi:[0,1,1] neg_lo:[0,0,1]
	v_pk_mul_f32 v[222:223], v[16:17], v[22:23] op_sel:[1,1] op_sel_hi:[0,1]
	v_pk_fma_f32 v[28:29], v[16:17], v[22:23], v[222:223] op_sel:[0,0,0] op_sel_hi:[1,0,1] neg_hi:[0,0,1]
	v_pk_mul_f32 v[222:223], v[18:19], v[24:25] op_sel:[1,1] op_sel_hi:[0,1]
	v_pk_fma_f32 v[30:31], v[18:19], v[24:25], v[222:223] op_sel:[0,0,0] op_sel_hi:[1,0,1] neg_hi:[0,0,1]
	v_pk_mul_f32 v[222:223], v[20:21], v[26:27] op_sel:[1,1] op_sel_hi:[0,1]
	v_pk_fma_f32 v[68:69], v[20:21], v[26:27], v[222:223] op_sel:[0,0,0] op_sel_hi:[1,0,1] neg_hi:[0,0,1]
	v_pk_add_f32 v[70:71], v[14:15], v[30:31]
	v_pk_add_f32 v[72:73], v[14:15], v[30:31] neg_lo:[0,1] neg_hi:[0,1]
	v_pk_add_f32 v[74:75], v[28:29], v[68:69]
	v_pk_add_f32 v[80:81], v[28:29], v[68:69] neg_lo:[0,1] neg_hi:[0,1]
	v_pk_add_f32 v[82:83], v[70:71], v[74:75]
	v_pk_add_f32 v[84:85], v[72:73], v[80:81] op_sel:[0,1] op_sel_hi:[1,0] neg_lo:[0,1]
	s_waitcnt vmcnt(14)
; __device__ __forceinline__ float bf2f(u16 h){ return __uint_as_float(((unsigned)h)<<16); }
; HD float2 cmul(float2 a, float2 b){ return make_float2(a.x*b.x - a.y*b.y, a.x*b.y + a.y*b.x); }
; HD float2 cmulc(float2 a, float2 b){ return make_float2(a.x*b.x + a.y*b.y, a.y*b.x - a.x*b.y); }
; HD void inv12_half(const float2* Z, const float2* twA, const float2* twB, int t, float2& x0, float2& x1){
;   float2 w1=cmul(twA[t>>6],twB[t&63]), w2=cmul(w1,w1), w3=cmul(w2,w1);
;   float2 b0=Z[t], b1=cmulc(Z[t+4096],w1), b2=cmulc(Z[t+8192],w2), b3=cmulc(Z[t+12288],w3);
;   float2 s02=make_float2(b0.x+b2.x,b0.y+b2.y), d02=make_float2(b0.x-b2.x,b0.y-b2.y);
;   float2 s13=make_float2(b1.x+b3.x,b1.y+b3.y), d13=make_float2(b1.x-b3.x,b1.y-b3.y);
;   x0=make_float2(s02.x+s13.x,s02.y+s13.y);
;   x1=make_float2(d02.x-d13.y,d02.y+d13.x);
; }
; __device__ __forceinline__ void phase_hyena(KP kp_, int hf){ asm volatile("" : "+s"(kp_)); const Params p=load_params(kp_);
;     ...
;         } else { int tq=tid; asm volatile("" : "+v"(tq));
;           _Pragma("unroll 4") for (int i=0;i<8;++i){ int tb=tq+512*i; float2 xr[2]; inv12_half(Z,twA,twB,tb,xr[0],xr[1]);
;             _Pragma("unroll") for (int hh=0;hh<2;++hh){ int t=tb+hh*4096;
;               float x0=hconv3(r2,t,wb0,wb1,wb2,bb_), x1=hconv3(r2+8192,t,wb0,wb1,wb2,bb_);
;               float2 y=xr[hh]; y.x*=(1.f/16384.f); y.y*=(1.f/16384.f); float2 z1=Zs[t];
;               float o0=x0*(y.x+z1.x*bias1)*bf2f(rz[t]); float o1=x1*(y.y+z1.y*bias1)*bf2f(rz[8192+t]);
;               ybT[(size_t)c*16384+t]=f2bf(o0); ybT[(size_t)c*16384+8192+t]=f2bf(o1); } }
	v_lshlrev_b32_e32 v224, 16, v228
	v_mov_b32_e32 v225, 0
	v_mov_b32_e32 v226, 0
	v_mov_b32_dpp v225, v224 wave_shr:1 row_mask:0xf bank_mask:0xf
	v_mov_b32_dpp v226, v224 wave_shl:1 row_mask:0xf bank_mask:0xf
	v_mul_f32_e32 v227, v88, v224
	v_fmac_f32_e32 v227, v87, v225
	v_fmac_f32_e32 v227, v89, v226
	v_add_f32_e32 v94, v90, v227
	v_lshlrev_b32_e32 v224, 16, v230
	v_mov_b32_e32 v225, 0
	v_mov_b32_e32 v226, 0
	v_mov_b32_dpp v225, v224 wave_shr:1 row_mask:0xf bank_mask:0xf
	v_mov_b32_dpp v226, v224 wave_shl:1 row_mask:0xf bank_mask:0xf
	v_mul_f32_e32 v227, v88, v224
	v_fmac_f32_e32 v227, v87, v225
	v_fmac_f32_e32 v227, v89, v226
	v_add_f32_e32 v97, v90, v227
	v_lshlrev_b32_e32 v224, 16, v229
	v_mov_b32_e32 v225, 0
	v_mov_b32_e32 v226, 0
	v_mov_b32_dpp v225, v224 wave_shr:1 row_mask:0xf bank_mask:0xf
	v_mov_b32_dpp v226, v224 wave_shl:1 row_mask:0xf bank_mask:0xf
	v_mul_f32_e32 v227, v88, v224
	v_fmac_f32_e32 v227, v87, v225
	v_fmac_f32_e32 v227, v89, v226
	v_add_f32_e32 v98, v90, v227
	v_lshlrev_b32_e32 v224, 16, v231
	v_mov_b32_e32 v225, 0
	v_mov_b32_e32 v226, 0
	v_mov_b32_dpp v225, v224 wave_shr:1 row_mask:0xf bank_mask:0xf
	v_mov_b32_dpp v226, v224 wave_shl:1 row_mask:0xf bank_mask:0xf
	v_mul_f32_e32 v227, v88, v224
	v_fmac_f32_e32 v227, v87, v225
	v_fmac_f32_e32 v227, v89, v226
	v_add_f32_e32 v100, v90, v227
	v_mul_f32_e32 v108, v91, v236
	v_fmac_f32_e32 v108, 0x38800000, v82
	v_mul_f32_e32 v108, v94, v108
	v_lshlrev_b32_e32 v109, 16, v232
	v_mul_f32_e32 v108, v108, v109
	v_cvt_pk_bf16_f32 v224, v108, v108
	v_mul_f32_e32 v108, v91, v237
	v_fmac_f32_e32 v108, 0x38800000, v83
	v_mul_f32_e32 v108, v108, v97
	v_lshlrev_b32_e32 v109, 16, v234
	v_mul_f32_e32 v108, v108, v109
	v_cvt_pk_bf16_f32 v225, v108, v108
	v_add_u32_e32 v106, 0x0, v1
	v_lshl_add_u64 v[104:105], v[54:55], 0, v[106:107]
	global_store_short v[104:105], v224, off
	v_lshl_add_u64 v[104:105], v[56:57], 0, v[106:107]
	global_store_short v[104:105], v225, off
	v_mul_f32_e32 v108, v91, v238
	v_fmac_f32_e32 v108, 0x38800000, v84
	v_mul_f32_e32 v108, v98, v108
	v_lshlrev_b32_e32 v109, 16, v233
	v_mul_f32_e32 v108, v108, v109
	v_cvt_pk_bf16_f32 v224, v108, v108
	v_mul_f32_e32 v108, v91, v239
	v_fmac_f32_e32 v108, 0x38800000, v85
	v_mul_f32_e32 v108, v108, v100
	v_lshlrev_b32_e32 v109, 16, v235
	v_mul_f32_e32 v108, v108, v109
	v_cvt_pk_bf16_f32 v225, v108, v108
	v_add_u32_e32 v106, 0x0, v4
	v_lshl_add_u64 v[104:105], v[54:55], 0, v[106:107]
	global_store_short v[104:105], v224, off
	v_lshl_add_u64 v[104:105], v[56:57], 0, v[106:107]
	global_store_short v[104:105], v225, off
	global_load_ushort v228, v1, s[96:97] offset:2048
	global_load_ushort v230, v1, s[74:75] offset:2048
	global_load_ushort v232, v1, s[72:73] offset:2048
	global_load_ushort v234, v1, s[12:13] offset:2048
	global_load_ushort v229, v4, s[96:97] offset:2048
	global_load_ushort v231, v4, s[74:75] offset:2048
	global_load_ushort v233, v4, s[72:73] offset:2048
	global_load_ushort v235, v4, s[12:13] offset:2048
	v_add_u32_e32 v6, 0x6000, v5
	global_load_dwordx2 v[236:237], v6, s[80:81] sc1
	global_load_dwordx2 v[238:239], v6, s[50:51] sc1
	ds_read_b64 v[12:13], v7 offset:384
	ds_read_b64 v[14:15], v8 offset:24576
	ds_read_b64 v[16:17], v8 offset:57344
	ds_read_b64 v[18:19], v9 offset:24576
	ds_read_b64 v[20:21], v9 offset:57344
	s_waitcnt lgkmcnt(5)
	v_pk_mul_f32 v[222:223], v[58:59], v[10:11] op_sel:[1,1] op_sel_hi:[1,0]
	v_pk_fma_f32 v[22:23], v[58:59], v[10:11], v[222:223] op_sel:[0,0,0] op_sel_hi:[0,1,1] neg_lo:[0,0,1]
	v_pk_mul_f32 v[222:223], v[22:23], v[22:23] op_sel:[1,1] op_sel_hi:[1,0]
	v_pk_fma_f32 v[24:25], v[22:23], v[22:23], v[222:223] op_sel:[0,0,0] op_sel_hi:[0,1,1] neg_lo:[0,0,1]
	v_pk_mul_f32 v[222:223], v[24:25], v[22:23] op_sel:[1,1] op_sel_hi:[1,0]
	v_pk_fma_f32 v[26:27], v[24:25], v[22:23], v[222:223] op_sel:[0,0,0] op_sel_hi:[0,1,1] neg_lo:[0,0,1]
	v_pk_mul_f32 v[222:223], v[62:63], v[22:23] op_sel:[1,1] op_sel_hi:[0,1]
	v_pk_fma_f32 v[28:29], v[62:63], v[22:23], v[222:223] op_sel:[0,0,0] op_sel_hi:[1,0,1] neg_hi:[0,0,1]
	v_pk_mul_f32 v[222:223], v[64:65], v[24:25] op_sel:[1,1] op_sel_hi:[0,1]
	v_pk_fma_f32 v[30:31], v[64:65], v[24:25], v[222:223] op_sel:[0,0,0] op_sel_hi:[1,0,1] neg_hi:[0,0,1]
	v_pk_mul_f32 v[222:223], v[66:67], v[26:27] op_sel:[1,1] op_sel_hi:[0,1]
	v_pk_fma_f32 v[68:69], v[66:67], v[26:27], v[222:223] op_sel:[0,0,0] op_sel_hi:[1,0,1] neg_hi:[0,0,1]
	v_pk_add_f32 v[70:71], v[60:61], v[30:31]
	v_pk_add_f32 v[72:73], v[60:61], v[30:31] neg_lo:[0,1] neg_hi:[0,1]
	v_pk_add_f32 v[74:75], v[28:29], v[68:69]
	v_pk_add_f32 v[80:81], v[28:29], v[68:69] neg_lo:[0,1] neg_hi:[0,1]
	v_pk_add_f32 v[82:83], v[70:71], v[74:75]
	v_pk_add_f32 v[84:85], v[72:73], v[80:81] op_sel:[0,1] op_sel_hi:[1,0] neg_lo:[0,1]
	s_waitcnt vmcnt(14)
; __device__ __forceinline__ float bf2f(u16 h){ return __uint_as_float(((unsigned)h)<<16); }
; HD float2 cmul(float2 a, float2 b){ return make_float2(a.x*b.x - a.y*b.y, a.x*b.y + a.y*b.x); }
; HD float2 cmulc(float2 a, float2 b){ return make_float2(a.x*b.x + a.y*b.y, a.y*b.x - a.x*b.y); }
; HD void inv12_half(const float2* Z, const float2* twA, const float2* twB, int t, float2& x0, float2& x1){
;   float2 w1=cmul(twA[t>>6],twB[t&63]), w2=cmul(w1,w1), w3=cmul(w2,w1);
;   float2 b0=Z[t], b1=cmulc(Z[t+4096],w1), b2=cmulc(Z[t+8192],w2), b3=cmulc(Z[t+12288],w3);
;   float2 s02=make_float2(b0.x+b2.x,b0.y+b2.y), d02=make_float2(b0.x-b2.x,b0.y-b2.y);
;   float2 s13=make_float2(b1.x+b3.x,b1.y+b3.y), d13=make_float2(b1.x-b3.x,b1.y-b3.y);
;   x0=make_float2(s02.x+s13.x,s02.y+s13.y);
;   x1=make_float2(d02.x-d13.y,d02.y+d13.x);
; }
; __device__ __forceinline__ void phase_hyena(KP kp_, int hf){ asm volatile("" : "+s"(kp_)); const Params p=load_params(kp_);
;     ...
;         } else { int tq=tid; asm volatile("" : "+v"(tq));
;           _Pragma("unroll 4") for (int i=0;i<8;++i){ int tb=tq+512*i; float2 xr[2]; inv12_half(Z,twA,twB,tb,xr[0],xr[1]);
;             _Pragma("unroll") for (int hh=0;hh<2;++hh){ int t=tb+hh*4096;
;               float x0=hconv3(r2,t,wb0,wb1,wb2,bb_), x1=hconv3(r2+8192,t,wb0,wb1,wb2,bb_);
;               float2 y=xr[hh]; y.x*=(1.f/16384.f); y.y*=(1.f/16384.f); float2 z1=Zs[t];
;               float o0=x0*(y.x+z1.x*bias1)*bf2f(rz[t]); float o1=x1*(y.y+z1.y*bias1)*bf2f(rz[8192+t]);
;               ybT[(size_t)c*16384+t]=f2bf(o0); ybT[(size_t)c*16384+8192+t]=f2bf(o1); } }
	v_lshlrev_b32_e32 v224, 16, v240
	v_mov_b32_e32 v225, 0
	v_mov_b32_e32 v226, 0
	v_mov_b32_dpp v225, v224 wave_shr:1 row_mask:0xf bank_mask:0xf
	v_mov_b32_dpp v226, v224 wave_shl:1 row_mask:0xf bank_mask:0xf
	v_mul_f32_e32 v227, v88, v224
	v_fmac_f32_e32 v227, v87, v225
	v_fmac_f32_e32 v227, v89, v226
	v_add_f32_e32 v94, v90, v227
	v_lshlrev_b32_e32 v224, 16, v242
	v_mov_b32_e32 v225, 0
	v_mov_b32_e32 v226, 0
	v_mov_b32_dpp v225, v224 wave_shr:1 row_mask:0xf bank_mask:0xf
	v_mov_b32_dpp v226, v224 wave_shl:1 row_mask:0xf bank_mask:0xf
	v_mul_f32_e32 v227, v88, v224
	v_fmac_f32_e32 v227, v87, v225
	v_fmac_f32_e32 v227, v89, v226
	v_add_f32_e32 v97, v90, v227
	v_lshlrev_b32_e32 v224, 16, v241
	v_mov_b32_e32 v225, 0
	v_mov_b32_e32 v226, 0
	v_mov_b32_dpp v225, v224 wave_shr:1 row_mask:0xf bank_mask:0xf
	v_mov_b32_dpp v226, v224 wave_shl:1 row_mask:0xf bank_mask:0xf
	v_mul_f32_e32 v227, v88, v224
	v_fmac_f32_e32 v227, v87, v225
	v_fmac_f32_e32 v227, v89, v226
	v_add_f32_e32 v98, v90, v227
	v_lshlrev_b32_e32 v224, 16, v243
	v_mov_b32_e32 v225, 0
	v_mov_b32_e32 v226, 0
	v_mov_b32_dpp v225, v224 wave_shr:1 row_mask:0xf bank_mask:0xf
	v_mov_b32_dpp v226, v224 wave_shl:1 row_mask:0xf bank_mask:0xf
	v_mul_f32_e32 v227, v88, v224
	v_fmac_f32_e32 v227, v87, v225
	v_fmac_f32_e32 v227, v89, v226
	v_add_f32_e32 v100, v90, v227
	v_mul_f32_e32 v108, v91, v248
	v_fmac_f32_e32 v108, 0x38800000, v82
	v_mul_f32_e32 v108, v94, v108
	v_lshlrev_b32_e32 v109, 16, v244
	v_mul_f32_e32 v108, v108, v109
	v_cvt_pk_bf16_f32 v224, v108, v108
	v_mul_f32_e32 v108, v91, v249
	v_fmac_f32_e32 v108, 0x38800000, v83
	v_mul_f32_e32 v108, v108, v97
	v_lshlrev_b32_e32 v109, 16, v246
	v_mul_f32_e32 v108, v108, v109
	v_cvt_pk_bf16_f32 v225, v108, v108
	v_add_u32_e32 v106, 0x400, v1
	v_lshl_add_u64 v[104:105], v[54:55], 0, v[106:107]
	global_store_short v[104:105], v224, off
	v_lshl_add_u64 v[104:105], v[56:57], 0, v[106:107]
	global_store_short v[104:105], v225, off
	v_mul_f32_e32 v108, v91, v250
	v_fmac_f32_e32 v108, 0x38800000, v84
	v_mul_f32_e32 v108, v98, v108
	v_lshlrev_b32_e32 v109, 16, v245
	v_mul_f32_e32 v108, v108, v109
	v_cvt_pk_bf16_f32 v224, v108, v108
	v_mul_f32_e32 v108, v91, v251
	v_fmac_f32_e32 v108, 0x38800000, v85
	v_mul_f32_e32 v108, v108, v100
	v_lshlrev_b32_e32 v109, 16, v247
	v_mul_f32_e32 v108, v108, v109
	v_cvt_pk_bf16_f32 v225, v108, v108
	v_add_u32_e32 v106, 0x400, v4
	v_lshl_add_u64 v[104:105], v[54:55], 0, v[106:107]
	global_store_short v[104:105], v224, off
	v_lshl_add_u64 v[104:105], v[56:57], 0, v[106:107]
	global_store_short v[104:105], v225, off
	global_load_ushort v240, v1, s[96:97] offset:3072
	global_load_ushort v242, v1, s[74:75] offset:3072
	global_load_ushort v244, v1, s[72:73] offset:3072
	global_load_ushort v246, v1, s[12:13] offset:3072
	global_load_ushort v241, v4, s[96:97] offset:3072
	global_load_ushort v243, v4, s[74:75] offset:3072
	global_load_ushort v245, v4, s[72:73] offset:3072
	global_load_ushort v247, v4, s[12:13] offset:3072
	v_add_u32_e32 v6, 0x7000, v5
	global_load_dwordx2 v[248:249], v6, s[80:81] sc1
	global_load_dwordx2 v[250:251], v6, s[50:51] sc1
	ds_read_b64 v[58:59], v7 offset:448
	ds_read_b64 v[60:61], v8 offset:28672
	ds_read_b64 v[62:63], v8 offset:61440
	ds_read_b64 v[64:65], v9 offset:28672
	ds_read_b64 v[66:67], v9 offset:61440
	s_waitcnt lgkmcnt(5)
	v_pk_mul_f32 v[222:223], v[12:13], v[10:11] op_sel:[1,1] op_sel_hi:[1,0]
	v_pk_fma_f32 v[22:23], v[12:13], v[10:11], v[222:223] op_sel:[0,0,0] op_sel_hi:[0,1,1] neg_lo:[0,0,1]
	v_pk_mul_f32 v[222:223], v[22:23], v[22:23] op_sel:[1,1] op_sel_hi:[1,0]
	v_pk_fma_f32 v[24:25], v[22:23], v[22:23], v[222:223] op_sel:[0,0,0] op_sel_hi:[0,1,1] neg_lo:[0,0,1]
	v_pk_mul_f32 v[222:223], v[24:25], v[22:23] op_sel:[1,1] op_sel_hi:[1,0]
	v_pk_fma_f32 v[26:27], v[24:25], v[22:23], v[222:223] op_sel:[0,0,0] op_sel_hi:[0,1,1] neg_lo:[0,0,1]
	v_pk_mul_f32 v[222:223], v[16:17], v[22:23] op_sel:[1,1] op_sel_hi:[0,1]
	v_pk_fma_f32 v[28:29], v[16:17], v[22:23], v[222:223] op_sel:[0,0,0] op_sel_hi:[1,0,1] neg_hi:[0,0,1]
	v_pk_mul_f32 v[222:223], v[18:19], v[24:25] op_sel:[1,1] op_sel_hi:[0,1]
	v_pk_fma_f32 v[30:31], v[18:19], v[24:25], v[222:223] op_sel:[0,0,0] op_sel_hi:[1,0,1] neg_hi:[0,0,1]
	v_pk_mul_f32 v[222:223], v[20:21], v[26:27] op_sel:[1,1] op_sel_hi:[0,1]
	v_pk_fma_f32 v[68:69], v[20:21], v[26:27], v[222:223] op_sel:[0,0,0] op_sel_hi:[1,0,1] neg_hi:[0,0,1]
	v_pk_add_f32 v[70:71], v[14:15], v[30:31]
	v_pk_add_f32 v[72:73], v[14:15], v[30:31] neg_lo:[0,1] neg_hi:[0,1]
	v_pk_add_f32 v[74:75], v[28:29], v[68:69]
	v_pk_add_f32 v[80:81], v[28:29], v[68:69] neg_lo:[0,1] neg_hi:[0,1]
	v_pk_add_f32 v[82:83], v[70:71], v[74:75]
	v_pk_add_f32 v[84:85], v[72:73], v[80:81] op_sel:[0,1] op_sel_hi:[1,0] neg_lo:[0,1]
	s_waitcnt vmcnt(14)
; __device__ __forceinline__ float bf2f(u16 h){ return __uint_as_float(((unsigned)h)<<16); }
; HD float2 cmul(float2 a, float2 b){ return make_float2(a.x*b.x - a.y*b.y, a.x*b.y + a.y*b.x); }
; HD float2 cmulc(float2 a, float2 b){ return make_float2(a.x*b.x + a.y*b.y, a.y*b.x - a.x*b.y); }
; HD void inv12_half(const float2* Z, const float2* twA, const float2* twB, int t, float2& x0, float2& x1){
;   float2 w1=cmul(twA[t>>6],twB[t&63]), w2=cmul(w1,w1), w3=cmul(w2,w1);
;   float2 b0=Z[t], b1=cmulc(Z[t+4096],w1), b2=cmulc(Z[t+8192],w2), b3=cmulc(Z[t+12288],w3);
;   float2 s02=make_float2(b0.x+b2.x,b0.y+b2.y), d02=make_float2(b0.x-b2.x,b0.y-b2.y);
;   float2 s13=make_float2(b1.x+b3.x,b1.y+b3.y), d13=make_float2(b1.x-b3.x,b1.y-b3.y);
;   x0=make_float2(s02.x+s13.x,s02.y+s13.y);
;   x1=make_float2(d02.x-d13.y,d02.y+d13.x);
; }
; __device__ __forceinline__ void phase_hyena(KP kp_, int hf){ asm volatile("" : "+s"(kp_)); const Params p=load_params(kp_);
;     ...
;         } else { int tq=tid; asm volatile("" : "+v"(tq));
;           _Pragma("unroll 4") for (int i=0;i<8;++i){ int tb=tq+512*i; float2 xr[2]; inv12_half(Z,twA,twB,tb,xr[0],xr[1]);
;             _Pragma("unroll") for (int hh=0;hh<2;++hh){ int t=tb+hh*4096;
;               float x0=hconv3(r2,t,wb0,wb1,wb2,bb_), x1=hconv3(r2+8192,t,wb0,wb1,wb2,bb_);
;               float2 y=xr[hh]; y.x*=(1.f/16384.f); y.y*=(1.f/16384.f); float2 z1=Zs[t];
;               float o0=x0*(y.x+z1.x*bias1)*bf2f(rz[t]); float o1=x1*(y.y+z1.y*bias1)*bf2f(rz[8192+t]);
;               ybT[(size_t)c*16384+t]=f2bf(o0); ybT[(size_t)c*16384+8192+t]=f2bf(o1); } }
	v_lshlrev_b32_e32 v224, 16, v228
	v_mov_b32_e32 v225, 0
	v_mov_b32_e32 v226, 0
	v_mov_b32_dpp v225, v224 wave_shr:1 row_mask:0xf bank_mask:0xf
	v_mov_b32_dpp v226, v224 wave_shl:1 row_mask:0xf bank_mask:0xf
	v_mul_f32_e32 v227, v88, v224
	v_fmac_f32_e32 v227, v87, v225
	v_fmac_f32_e32 v227, v89, v226
	v_add_f32_e32 v94, v90, v227
	v_lshlrev_b32_e32 v224, 16, v230
	v_mov_b32_e32 v225, 0
	v_mov_b32_e32 v226, 0
	v_mov_b32_dpp v225, v224 wave_shr:1 row_mask:0xf bank_mask:0xf
	v_mov_b32_dpp v226, v224 wave_shl:1 row_mask:0xf bank_mask:0xf
	v_mul_f32_e32 v227, v88, v224
	v_fmac_f32_e32 v227, v87, v225
	v_fmac_f32_e32 v227, v89, v226
	v_add_f32_e32 v97, v90, v227
	v_lshlrev_b32_e32 v224, 16, v229
	v_mov_b32_e32 v225, 0
	v_mov_b32_e32 v226, 0
	v_mov_b32_dpp v225, v224 wave_shr:1 row_mask:0xf bank_mask:0xf
	v_mov_b32_dpp v226, v224 wave_shl:1 row_mask:0xf bank_mask:0xf
	v_mul_f32_e32 v227, v88, v224
	v_fmac_f32_e32 v227, v87, v225
	v_fmac_f32_e32 v227, v89, v226
	v_add_f32_e32 v98, v90, v227
	v_lshlrev_b32_e32 v224, 16, v231
	v_mov_b32_e32 v225, 0
	v_mov_b32_e32 v226, 0
	v_mov_b32_dpp v225, v224 wave_shr:1 row_mask:0xf bank_mask:0xf
	v_mov_b32_dpp v226, v224 wave_shl:1 row_mask:0xf bank_mask:0xf
	v_mul_f32_e32 v227, v88, v224
	v_fmac_f32_e32 v227, v87, v225
	v_fmac_f32_e32 v227, v89, v226
	v_add_f32_e32 v100, v90, v227
	v_mul_f32_e32 v108, v91, v236
	v_fmac_f32_e32 v108, 0x38800000, v82
	v_mul_f32_e32 v108, v94, v108
	v_lshlrev_b32_e32 v109, 16, v232
	v_mul_f32_e32 v108, v108, v109
	v_cvt_pk_bf16_f32 v224, v108, v108
	v_mul_f32_e32 v108, v91, v237
	v_fmac_f32_e32 v108, 0x38800000, v83
	v_mul_f32_e32 v108, v108, v97
	v_lshlrev_b32_e32 v109, 16, v234
	v_mul_f32_e32 v108, v108, v109
	v_cvt_pk_bf16_f32 v225, v108, v108
	v_add_u32_e32 v106, 0x800, v1
	v_lshl_add_u64 v[104:105], v[54:55], 0, v[106:107]
	global_store_short v[104:105], v224, off
	v_lshl_add_u64 v[104:105], v[56:57], 0, v[106:107]
	global_store_short v[104:105], v225, off
	v_mul_f32_e32 v108, v91, v238
	v_fmac_f32_e32 v108, 0x38800000, v84
	v_mul_f32_e32 v108, v98, v108
	v_lshlrev_b32_e32 v109, 16, v233
	v_mul_f32_e32 v108, v108, v109
	v_cvt_pk_bf16_f32 v224, v108, v108
	v_mul_f32_e32 v108, v91, v239
	v_fmac_f32_e32 v108, 0x38800000, v85
	v_mul_f32_e32 v108, v108, v100
	v_lshlrev_b32_e32 v109, 16, v235
	v_mul_f32_e32 v108, v108, v109
	v_cvt_pk_bf16_f32 v225, v108, v108
	v_add_u32_e32 v106, 0x800, v4
	v_lshl_add_u64 v[104:105], v[54:55], 0, v[106:107]
	global_store_short v[104:105], v224, off
	v_lshl_add_u64 v[104:105], v[56:57], 0, v[106:107]
	global_store_short v[104:105], v225, off
	s_waitcnt lgkmcnt(0)
	v_pk_mul_f32 v[222:223], v[58:59], v[10:11] op_sel:[1,1] op_sel_hi:[1,0]
	v_pk_fma_f32 v[22:23], v[58:59], v[10:11], v[222:223] op_sel:[0,0,0] op_sel_hi:[0,1,1] neg_lo:[0,0,1]
	v_pk_mul_f32 v[222:223], v[22:23], v[22:23] op_sel:[1,1] op_sel_hi:[1,0]
	v_pk_fma_f32 v[24:25], v[22:23], v[22:23], v[222:223] op_sel:[0,0,0] op_sel_hi:[0,1,1] neg_lo:[0,0,1]
	v_pk_mul_f32 v[222:223], v[24:25], v[22:23] op_sel:[1,1] op_sel_hi:[1,0]
	v_pk_fma_f32 v[26:27], v[24:25], v[22:23], v[222:223] op_sel:[0,0,0] op_sel_hi:[0,1,1] neg_lo:[0,0,1]
	v_pk_mul_f32 v[222:223], v[62:63], v[22:23] op_sel:[1,1] op_sel_hi:[0,1]
	v_pk_fma_f32 v[28:29], v[62:63], v[22:23], v[222:223] op_sel:[0,0,0] op_sel_hi:[1,0,1] neg_hi:[0,0,1]
	v_pk_mul_f32 v[222:223], v[64:65], v[24:25] op_sel:[1,1] op_sel_hi:[0,1]
	v_pk_fma_f32 v[30:31], v[64:65], v[24:25], v[222:223] op_sel:[0,0,0] op_sel_hi:[1,0,1] neg_hi:[0,0,1]
	v_pk_mul_f32 v[222:223], v[66:67], v[26:27] op_sel:[1,1] op_sel_hi:[0,1]
	v_pk_fma_f32 v[68:69], v[66:67], v[26:27], v[222:223] op_sel:[0,0,0] op_sel_hi:[1,0,1] neg_hi:[0,0,1]
	v_pk_add_f32 v[70:71], v[60:61], v[30:31]
	v_pk_add_f32 v[72:73], v[60:61], v[30:31] neg_lo:[0,1] neg_hi:[0,1]
	v_pk_add_f32 v[74:75], v[28:29], v[68:69]
	v_pk_add_f32 v[80:81], v[28:29], v[68:69] neg_lo:[0,1] neg_hi:[0,1]
	v_pk_add_f32 v[82:83], v[70:71], v[74:75]
	v_pk_add_f32 v[84:85], v[72:73], v[80:81] op_sel:[0,1] op_sel_hi:[1,0] neg_lo:[0,1]
	s_waitcnt vmcnt(4)
	v_lshlrev_b32_e32 v224, 16, v240
	v_mov_b32_e32 v225, 0
	v_mov_b32_e32 v226, 0
	v_mov_b32_dpp v225, v224 wave_shr:1 row_mask:0xf bank_mask:0xf
	v_mov_b32_dpp v226, v224 wave_shl:1 row_mask:0xf bank_mask:0xf
	v_mul_f32_e32 v227, v88, v224
	v_fmac_f32_e32 v227, v87, v225
	v_fmac_f32_e32 v227, v89, v226
	v_add_f32_e32 v94, v90, v227
	v_lshlrev_b32_e32 v224, 16, v242
	v_mov_b32_e32 v225, 0
	v_mov_b32_e32 v226, 0
	v_mov_b32_dpp v225, v224 wave_shr:1 row_mask:0xf bank_mask:0xf
	v_mov_b32_dpp v226, v224 wave_shl:1 row_mask:0xf bank_mask:0xf
	v_mul_f32_e32 v227, v88, v224
	v_fmac_f32_e32 v227, v87, v225
	v_fmac_f32_e32 v227, v89, v226
	v_add_f32_e32 v97, v90, v227
	v_lshlrev_b32_e32 v224, 16, v241
	v_mov_b32_e32 v225, 0
	v_mov_b32_e32 v226, 0
	v_mov_b32_dpp v225, v224 wave_shr:1 row_mask:0xf bank_mask:0xf
	v_mov_b32_dpp v226, v224 wave_shl:1 row_mask:0xf bank_mask:0xf
	v_mul_f32_e32 v227, v88, v224
	v_fmac_f32_e32 v227, v87, v225
	v_fmac_f32_e32 v227, v89, v226
	v_add_f32_e32 v98, v90, v227
	v_lshlrev_b32_e32 v224, 16, v243
	v_mov_b32_e32 v225, 0
	v_mov_b32_e32 v226, 0
	v_mov_b32_dpp v225, v224 wave_shr:1 row_mask:0xf bank_mask:0xf
	v_mov_b32_dpp v226, v224 wave_shl:1 row_mask:0xf bank_mask:0xf
	v_mul_f32_e32 v227, v88, v224
	v_fmac_f32_e32 v227, v87, v225
	v_fmac_f32_e32 v227, v89, v226
	v_add_f32_e32 v100, v90, v227
	v_mul_f32_e32 v108, v91, v248
	v_fmac_f32_e32 v108, 0x38800000, v82
	v_mul_f32_e32 v108, v94, v108
	v_lshlrev_b32_e32 v109, 16, v244
	v_mul_f32_e32 v108, v108, v109
	v_cvt_pk_bf16_f32 v224, v108, v108
	v_mul_f32_e32 v108, v91, v249
	v_fmac_f32_e32 v108, 0x38800000, v83
	v_mul_f32_e32 v108, v108, v97
	v_lshlrev_b32_e32 v109, 16, v246
	v_mul_f32_e32 v108, v108, v109
	v_cvt_pk_bf16_f32 v225, v108, v108
	v_add_u32_e32 v106, 0xc00, v1
	v_lshl_add_u64 v[104:105], v[54:55], 0, v[106:107]
	global_store_short v[104:105], v224, off
	v_lshl_add_u64 v[104:105], v[56:57], 0, v[106:107]
	global_store_short v[104:105], v225, off
	v_mul_f32_e32 v108, v91, v250
	v_fmac_f32_e32 v108, 0x38800000, v84
	v_mul_f32_e32 v108, v98, v108
	v_lshlrev_b32_e32 v109, 16, v245
	v_mul_f32_e32 v108, v108, v109
	v_cvt_pk_bf16_f32 v224, v108, v108
	v_mul_f32_e32 v108, v91, v251
	v_fmac_f32_e32 v108, 0x38800000, v85
	v_mul_f32_e32 v108, v108, v100
	v_lshlrev_b32_e32 v109, 16, v247
	v_mul_f32_e32 v108, v108, v109
	v_cvt_pk_bf16_f32 v225, v108, v108
	v_add_u32_e32 v106, 0xc00, v4
	v_lshl_add_u64 v[104:105], v[54:55], 0, v[106:107]
	global_store_short v[104:105], v224, off
	v_lshl_add_u64 v[104:105], v[56:57], 0, v[106:107]
	global_store_short v[104:105], v225, off
	s_mov_b32 s50, 0x2000
	s_mov_b32 s51, 0
	s_mov_b64 s[12:13], 0

; HD float2 cmul(float2 a, float2 b){ return make_float2(a.x*b.x - a.y*b.y, a.x*b.y + a.y*b.x); }
; HD int rev4_14(int p){ unsigned r = __brev((unsigned)p) >> 18; return (int)(((r & 0x2AAAu) >> 1) | ((r & 0x1555u) << 1)); }
; template<bool INV, int LQ, bool BARRIER=true>
; HD void fft_pass(float2* Z, const float2* twA, const float2* twB, int tid){
;     ...
;     int j=tid&(q-1); int base0=((tid>>LQ)<<(LQ+2))+j;
;     float2 w1=make_float2(1.f,0.f), w2=w1, w3=w1;
;     if (LQ>0){ int k=j*tws; w1=cmul(twA[k>>6],twB[k&63]); w2=cmul(w1,w1); w3=cmul(w2,w1); }
;     _Pragma("unroll") for (int i=0;i<8;++i){ int base=base0+i*2048; bf4c<INV,(LQ==0)>(Z,base,base+q,base+2*q,base+3*q,w1,w2,w3); }
;   }
;   if (BARRIER) __syncthreads(); else asm volatile("s_waitcnt lgkmcnt(0)" ::: "memory");
; __device__ __forceinline__ void phase_hyena(KP kp_, int hf){ asm volatile("" : "+s"(kp_)); const Params p=load_params(kp_);
;     ...
;         fft_pass<false,0>(Z,twA,twB,tid);
;     _Pragma("unroll 2") for (int i=0;i<8;++i){ int q0=(tid+512*i)*4; u32x4 h0w, h1w;
;       _Pragma("unroll") for (int m=0;m<4;++m){ int q=q0+m; int k=rev4_14(q);
;         float2 Fk=Z[q], Fn=Z[rev4_14((16384-k)&16383)];
;         f16x2 h0v={(_Float16)(0.5f*nrm0*(Fk.x+Fn.x)),(_Float16)(0.5f*nrm0*(Fk.y-Fn.y))};
.LBB0_1344:
	s_and_b64 vcc, exec, s[12:13]
	s_cbranch_vccz .LBB0_1198
	ds_read_b128 v[0:3], v203
	ds_read_b128 v[4:7], v203 offset:16
	s_mov_b32 s12, 0.5
	s_mov_b32 s13, -0.5
	s_waitcnt lgkmcnt(0)
	v_pk_add_f32 v[12:13], v[0:1], v[4:5]
	v_pk_add_f32 v[14:15], v[2:3], v[6:7]
	v_pk_add_f32 v[0:1], v[0:1], v[4:5] neg_lo:[0,1] neg_hi:[0,1]
	v_pk_add_f32 v[2:3], v[2:3], v[6:7] neg_lo:[0,1] neg_hi:[0,1]
	v_pk_add_f32 v[8:9], v[12:13], v[14:15]
	v_pk_add_f32 v[4:5], v[0:1], v[2:3] op_sel:[0,1] op_sel_hi:[1,0]
	v_pk_add_f32 v[2:3], v[0:1], v[2:3] op_sel:[0,1] op_sel_hi:[1,0] neg_lo:[0,1] neg_hi:[0,1]
	v_mov_b32_e32 v10, v4
	v_mov_b32_e32 v11, v3
	v_pk_add_f32 v[0:1], v[12:13], v[14:15] neg_lo:[0,1] neg_hi:[0,1]
	v_mov_b32_e32 v3, v5
	ds_write_b128 v203, v[8:11]
	ds_write_b128 v203, v[0:3] offset:16
	ds_read_b128 v[0:3], v203 offset:16384
	ds_read_b128 v[4:7], v203 offset:16400
	s_waitcnt lgkmcnt(0)
	v_pk_add_f32 v[12:13], v[0:1], v[4:5]
	v_pk_add_f32 v[14:15], v[2:3], v[6:7]
	v_pk_add_f32 v[0:1], v[0:1], v[4:5] neg_lo:[0,1] neg_hi:[0,1]
	v_pk_add_f32 v[2:3], v[2:3], v[6:7] neg_lo:[0,1] neg_hi:[0,1]
	v_pk_add_f32 v[8:9], v[12:13], v[14:15]
	v_pk_add_f32 v[4:5], v[0:1], v[2:3] op_sel:[0,1] op_sel_hi:[1,0]
	v_pk_add_f32 v[2:3], v[0:1], v[2:3] op_sel:[0,1] op_sel_hi:[1,0] neg_lo:[0,1] neg_hi:[0,1]
	v_mov_b32_e32 v10, v4
	v_mov_b32_e32 v11, v3
	v_pk_add_f32 v[0:1], v[12:13], v[14:15] neg_lo:[0,1] neg_hi:[0,1]
	v_mov_b32_e32 v3, v5
	ds_write_b128 v203, v[8:11] offset:16384
	ds_write_b128 v203, v[0:3] offset:16400
	ds_read_b128 v[0:3], v203 offset:32768
	ds_read_b128 v[4:7], v203 offset:32784
	s_waitcnt lgkmcnt(0)
	v_pk_add_f32 v[12:13], v[0:1], v[4:5]
	v_pk_add_f32 v[14:15], v[2:3], v[6:7]
	v_pk_add_f32 v[0:1], v[0:1], v[4:5] neg_lo:[0,1] neg_hi:[0,1]
	v_pk_add_f32 v[2:3], v[2:3], v[6:7] neg_lo:[0,1] neg_hi:[0,1]
	v_pk_add_f32 v[8:9], v[12:13], v[14:15]
	v_pk_add_f32 v[4:5], v[0:1], v[2:3] op_sel:[0,1] op_sel_hi:[1,0]
	v_pk_add_f32 v[2:3], v[0:1], v[2:3] op_sel:[0,1] op_sel_hi:[1,0] neg_lo:[0,1] neg_hi:[0,1]
	v_mov_b32_e32 v10, v4
	v_mov_b32_e32 v11, v3
	v_pk_add_f32 v[0:1], v[12:13], v[14:15] neg_lo:[0,1] neg_hi:[0,1]
	v_mov_b32_e32 v3, v5
	ds_write_b128 v203, v[8:11] offset:32768
	ds_write_b128 v203, v[0:3] offset:32784
	ds_read_b128 v[0:3], v203 offset:49152
	ds_read_b128 v[4:7], v203 offset:49168
	s_waitcnt lgkmcnt(0)
	v_pk_add_f32 v[12:13], v[0:1], v[4:5]
	v_pk_add_f32 v[14:15], v[2:3], v[6:7]
	v_pk_add_f32 v[0:1], v[0:1], v[4:5] neg_lo:[0,1] neg_hi:[0,1]
	v_pk_add_f32 v[2:3], v[2:3], v[6:7] neg_lo:[0,1] neg_hi:[0,1]
	v_pk_add_f32 v[8:9], v[12:13], v[14:15]
	v_pk_add_f32 v[4:5], v[0:1], v[2:3] op_sel:[0,1] op_sel_hi:[1,0]
	v_pk_add_f32 v[2:3], v[0:1], v[2:3] op_sel:[0,1] op_sel_hi:[1,0] neg_lo:[0,1] neg_hi:[0,1]
	v_mov_b32_e32 v10, v4
	v_mov_b32_e32 v11, v3
	v_pk_add_f32 v[0:1], v[12:13], v[14:15] neg_lo:[0,1] neg_hi:[0,1]
	v_mov_b32_e32 v3, v5
	ds_write_b128 v203, v[8:11] offset:49152
	ds_write_b128 v203, v[0:3] offset:49168
	ds_read_b128 v[0:3], v204
	ds_read_b128 v[4:7], v205
	s_waitcnt lgkmcnt(0)
	v_pk_add_f32 v[12:13], v[0:1], v[4:5]
	v_pk_add_f32 v[14:15], v[2:3], v[6:7]
	v_pk_add_f32 v[0:1], v[0:1], v[4:5] neg_lo:[0,1] neg_hi:[0,1]
	v_pk_add_f32 v[2:3], v[2:3], v[6:7] neg_lo:[0,1] neg_hi:[0,1]
	v_pk_add_f32 v[8:9], v[12:13], v[14:15]
	v_pk_add_f32 v[4:5], v[0:1], v[2:3] op_sel:[0,1] op_sel_hi:[1,0]
	v_pk_add_f32 v[2:3], v[0:1], v[2:3] op_sel:[0,1] op_sel_hi:[1,0] neg_lo:[0,1] neg_hi:[0,1]
	v_mov_b32_e32 v10, v4
	v_mov_b32_e32 v11, v3
	v_pk_add_f32 v[0:1], v[12:13], v[14:15] neg_lo:[0,1] neg_hi:[0,1]
	v_mov_b32_e32 v3, v5
	ds_write_b128 v204, v[8:11]
	ds_write_b128 v205, v[0:3]
	ds_read_b128 v[0:3], v206
	ds_read_b128 v[4:7], v207
	s_waitcnt lgkmcnt(0)
	v_pk_add_f32 v[12:13], v[0:1], v[4:5]
	v_pk_add_f32 v[14:15], v[2:3], v[6:7]
	v_pk_add_f32 v[0:1], v[0:1], v[4:5] neg_lo:[0,1] neg_hi:[0,1]
	v_pk_add_f32 v[2:3], v[2:3], v[6:7] neg_lo:[0,1] neg_hi:[0,1]
	v_pk_add_f32 v[8:9], v[12:13], v[14:15]
	v_pk_add_f32 v[4:5], v[0:1], v[2:3] op_sel:[0,1] op_sel_hi:[1,0]
	v_pk_add_f32 v[2:3], v[0:1], v[2:3] op_sel:[0,1] op_sel_hi:[1,0] neg_lo:[0,1] neg_hi:[0,1]
	v_mov_b32_e32 v10, v4
	v_mov_b32_e32 v11, v3
	v_pk_add_f32 v[0:1], v[12:13], v[14:15] neg_lo:[0,1] neg_hi:[0,1]
	v_mov_b32_e32 v3, v5
	ds_write_b128 v206, v[8:11]
	ds_write_b128 v207, v[0:3]
	ds_read_b128 v[0:3], v208
	ds_read_b128 v[4:7], v209
	s_waitcnt lgkmcnt(0)
	v_pk_add_f32 v[12:13], v[0:1], v[4:5]
	v_pk_add_f32 v[14:15], v[2:3], v[6:7]
	v_pk_add_f32 v[0:1], v[0:1], v[4:5] neg_lo:[0,1] neg_hi:[0,1]
	v_pk_add_f32 v[2:3], v[2:3], v[6:7] neg_lo:[0,1] neg_hi:[0,1]
	v_pk_add_f32 v[8:9], v[12:13], v[14:15]
	v_pk_add_f32 v[4:5], v[0:1], v[2:3] op_sel:[0,1] op_sel_hi:[1,0]
	v_pk_add_f32 v[2:3], v[0:1], v[2:3] op_sel:[0,1] op_sel_hi:[1,0] neg_lo:[0,1] neg_hi:[0,1]
	v_mov_b32_e32 v10, v4
	v_mov_b32_e32 v11, v3
	v_pk_add_f32 v[0:1], v[12:13], v[14:15] neg_lo:[0,1] neg_hi:[0,1]
	v_mov_b32_e32 v3, v5
	ds_write_b128 v208, v[8:11]
	ds_write_b128 v209, v[0:3]
	ds_read_b128 v[0:3], v210
	ds_read_b128 v[4:7], v211
	s_waitcnt lgkmcnt(0)
	v_pk_add_f32 v[12:13], v[0:1], v[4:5]
	v_pk_add_f32 v[14:15], v[2:3], v[6:7]
	v_pk_add_f32 v[0:1], v[0:1], v[4:5] neg_lo:[0,1] neg_hi:[0,1]
	v_pk_add_f32 v[2:3], v[2:3], v[6:7] neg_lo:[0,1] neg_hi:[0,1]
	v_pk_add_f32 v[8:9], v[12:13], v[14:15]
	v_pk_add_f32 v[4:5], v[0:1], v[2:3] op_sel:[0,1] op_sel_hi:[1,0]
	v_pk_add_f32 v[2:3], v[0:1], v[2:3] op_sel:[0,1] op_sel_hi:[1,0] neg_lo:[0,1] neg_hi:[0,1]
	v_pk_add_f32 v[0:1], v[12:13], v[14:15] neg_lo:[0,1] neg_hi:[0,1]
	v_mov_b32_e32 v11, v3
	v_mov_b32_e32 v3, v5
	v_mov_b32_e32 v10, v4
	ds_write_b128 v211, v[0:3]
	v_mul_f32_e32 v2, 0.5, v78
	v_pk_mul_f32 v[0:1], v[78:79], s[12:13] op_sel:[1,0]
	s_mov_b32 s12, 0
	v_mov_b32_e32 v3, v203
	ds_write_b128 v210, v[8:11]
	s_waitcnt lgkmcnt(0)
	s_barrier
; HD int rev4_14(int p){ unsigned r = __brev((unsigned)p) >> 18; return (int)(((r & 0x2AAAu) >> 1) | ((r & 0x1555u) << 1)); }
; __device__ __forceinline__ void phase_hyena(KP kp_, int hf){ asm volatile("" : "+s"(kp_)); const Params p=load_params(kp_);
;     ...
;     _Pragma("unroll 2") for (int i=0;i<8;++i){ int q0=(tid+512*i)*4; u32x4 h0w, h1w;
;       _Pragma("unroll") for (int m=0;m<4;++m){ int q=q0+m; int k=rev4_14(q);
;         float2 Fk=Z[q], Fn=Z[rev4_14((16384-k)&16383)];
;         f16x2 h0v={(_Float16)(0.5f*nrm0*(Fk.x+Fn.x)),(_Float16)(0.5f*nrm0*(Fk.y-Fn.y))};
;         f16x2 h1v={(_Float16)(0.5f*nrm1*(Fk.y+Fn.y)),(_Float16)(-0.5f*nrm1*(Fk.x-Fn.x))};
;         unsigned u0=__builtin_bit_cast(unsigned,h0v), u1=__builtin_bit_cast(unsigned,h1v);
;         h0w[m]=u0; h1w[m]=u1; }
;       *(u32x4*)(H0p+q0)=h0w; *(u32x4*)(H1p+q0)=h1w; }
	v_lshlrev_b32_e32 v70, 5, v154
	v_add_u32_e32 v71, 0x10000, v70
	v_lshlrev_b32_e32 v72, 4, v154
	v_cmp_eq_u32_e64 s[12:13], 0, v154
	v_mov_b32_e32 v68, v154
	v_bfrev_b32_e32 v66, v68
	v_lshrrev_b32_e32 v66, 20, v66
	v_and_b32_e32 v67, 0xaaa, v66
	v_and_b32_e32 v66, 0x555, v66
	v_lshrrev_b32_e32 v67, 1, v67
	v_lshl_or_b32 v69, v66, 1, v67
	v_sub_u32_e32 v69, 0x1000, v69
	v_and_b32_e32 v69, 0xfff, v69
	v_bfrev_b32_e32 v66, v69
	v_lshrrev_b32_e32 v66, 20, v66
	v_and_b32_e32 v67, 0xaaa, v66
	v_and_b32_e32 v66, 0x555, v66
	v_lshrrev_b32_e32 v67, 1, v67
	v_lshl_or_b32 v68, v66, 1, v67
	v_lshlrev_b32_e32 v73, 5, v68
	ds_read_b128 v[4:7], v70 offset:0
	ds_read_b128 v[8:11], v70 offset:16
	ds_read_b128 v[12:15], v73
	ds_read_b128 v[16:19], v73 offset:16
	v_add_u32_e32 v68, 0x200, v154
	v_bfrev_b32_e32 v66, v68
	v_lshrrev_b32_e32 v66, 20, v66
	v_and_b32_e32 v67, 0xaaa, v66
	v_and_b32_e32 v66, 0x555, v66
	v_lshrrev_b32_e32 v67, 1, v67
	v_lshl_or_b32 v69, v66, 1, v67
	v_sub_u32_e32 v69, 0x1000, v69
	v_and_b32_e32 v69, 0xfff, v69
	v_bfrev_b32_e32 v66, v69
	v_lshrrev_b32_e32 v66, 20, v66
	v_and_b32_e32 v67, 0xaaa, v66
	v_and_b32_e32 v66, 0x555, v66
	v_lshrrev_b32_e32 v67, 1, v67
	v_lshl_or_b32 v68, v66, 1, v67
	v_lshlrev_b32_e32 v73, 5, v68
	ds_read_b128 v[20:23], v70 offset:16384
	ds_read_b128 v[24:27], v70 offset:16400
	ds_read_b128 v[58:61], v73
	ds_read_b128 v[62:65], v73 offset:16
	s_waitcnt lgkmcnt(4)
	v_cndmask_b32_e64 v112, v18, v12, s[12:13]
	v_cndmask_b32_e64 v113, v19, v13, s[12:13]
	v_cndmask_b32_e64 v114, v16, v18, s[12:13]
	v_cndmask_b32_e64 v115, v17, v19, s[12:13]
	v_cndmask_b32_e64 v116, v14, v16, s[12:13]
	v_cndmask_b32_e64 v117, v15, v17, s[12:13]
	v_cndmask_b32_e64 v118, v12, v14, s[12:13]
	v_cndmask_b32_e64 v119, v13, v15, s[12:13]
	v_pk_add_f32 v[104:105], v[4:5], v[112:113]
	v_pk_add_f32 v[106:107], v[4:5], v[112:113] neg_lo:[0,1] neg_hi:[0,1]
	v_mul_f32_e32 v108, v2, v104
	v_mul_f32_e32 v109, v2, v107
	v_mul_f32_e32 v110, v0, v105
	v_mul_f32_e32 v111, v1, v106
	v_cvt_pk_f16_f32 v82, v108, v109
	v_cvt_pk_f16_f32 v100, v110, v111
	v_pk_add_f32 v[104:105], v[6:7], v[114:115]
	v_pk_add_f32 v[106:107], v[6:7], v[114:115] neg_lo:[0,1] neg_hi:[0,1]
	v_mul_f32_e32 v108, v2, v104
	v_mul_f32_e32 v109, v2, v107
	v_mul_f32_e32 v110, v0, v105
	v_mul_f32_e32 v111, v1, v106
	v_cvt_pk_f16_f32 v83, v108, v109
	v_cvt_pk_f16_f32 v101, v110, v111
	v_pk_add_f32 v[104:105], v[8:9], v[116:117]
	v_pk_add_f32 v[106:107], v[8:9], v[116:117] neg_lo:[0,1] neg_hi:[0,1]
	v_mul_f32_e32 v108, v2, v104
	v_mul_f32_e32 v109, v2, v107
	v_mul_f32_e32 v110, v0, v105
	v_mul_f32_e32 v111, v1, v106
	v_cvt_pk_f16_f32 v84, v108, v109
	v_cvt_pk_f16_f32 v102, v110, v111
	v_pk_add_f32 v[104:105], v[10:11], v[118:119]
	v_pk_add_f32 v[106:107], v[10:11], v[118:119] neg_lo:[0,1] neg_hi:[0,1]
	v_mul_f32_e32 v108, v2, v104
	v_mul_f32_e32 v109, v2, v107
	v_mul_f32_e32 v110, v0, v105
	v_mul_f32_e32 v111, v1, v106
	v_cvt_pk_f16_f32 v85, v108, v109
	v_cvt_pk_f16_f32 v103, v110, v111
	v_mov_b32_e32 v74, v72
	global_store_dwordx4 v74, v[82:85], s[76:77]
	global_store_dwordx4 v74, v[100:103], s[78:79]
	s_nop 1
	v_add_u32_e32 v68, 0x400, v154
	v_bfrev_b32_e32 v66, v68
	v_lshrrev_b32_e32 v66, 20, v66
	v_and_b32_e32 v67, 0xaaa, v66
	v_and_b32_e32 v66, 0x555, v66
	v_lshrrev_b32_e32 v67, 1, v67
	v_lshl_or_b32 v69, v66, 1, v67
	v_sub_u32_e32 v69, 0x1000, v69
	v_and_b32_e32 v69, 0xfff, v69
	v_bfrev_b32_e32 v66, v69
	v_lshrrev_b32_e32 v66, 20, v66
	v_and_b32_e32 v67, 0xaaa, v66
	v_and_b32_e32 v66, 0x555, v66
	v_lshrrev_b32_e32 v67, 1, v67
	v_lshl_or_b32 v68, v66, 1, v67
	v_lshlrev_b32_e32 v73, 5, v68
	ds_read_b128 v[4:7], v70 offset:32768
	ds_read_b128 v[8:11], v70 offset:32784
	ds_read_b128 v[12:15], v73
	ds_read_b128 v[16:19], v73 offset:16
	s_waitcnt lgkmcnt(4)
	v_pk_add_f32 v[104:105], v[20:21], v[64:65]
	v_pk_add_f32 v[106:107], v[20:21], v[64:65] neg_lo:[0,1] neg_hi:[0,1]
	v_mul_f32_e32 v108, v2, v104
	v_mul_f32_e32 v109, v2, v107
	v_mul_f32_e32 v110, v0, v105
	v_mul_f32_e32 v111, v1, v106
	v_cvt_pk_f16_f32 v82, v108, v109
	v_cvt_pk_f16_f32 v100, v110, v111
	v_pk_add_f32 v[104:105], v[22:23], v[62:63]
	v_pk_add_f32 v[106:107], v[22:23], v[62:63] neg_lo:[0,1] neg_hi:[0,1]
	v_mul_f32_e32 v108, v2, v104
	v_mul_f32_e32 v109, v2, v107
	v_mul_f32_e32 v110, v0, v105
	v_mul_f32_e32 v111, v1, v106
	v_cvt_pk_f16_f32 v83, v108, v109
	v_cvt_pk_f16_f32 v101, v110, v111
	v_pk_add_f32 v[104:105], v[24:25], v[60:61]
	v_pk_add_f32 v[106:107], v[24:25], v[60:61] neg_lo:[0,1] neg_hi:[0,1]
	v_mul_f32_e32 v108, v2, v104
	v_mul_f32_e32 v109, v2, v107
	v_mul_f32_e32 v110, v0, v105
	v_mul_f32_e32 v111, v1, v106
	v_cvt_pk_f16_f32 v84, v108, v109
	v_cvt_pk_f16_f32 v102, v110, v111
	v_pk_add_f32 v[104:105], v[26:27], v[58:59]
	v_pk_add_f32 v[106:107], v[26:27], v[58:59] neg_lo:[0,1] neg_hi:[0,1]
	v_mul_f32_e32 v108, v2, v104
	v_mul_f32_e32 v109, v2, v107
	v_mul_f32_e32 v110, v0, v105
	v_mul_f32_e32 v111, v1, v106
	v_cvt_pk_f16_f32 v85, v108, v109
	v_cvt_pk_f16_f32 v103, v110, v111
	v_add_u32_e32 v74, 0x2000, v72
	global_store_dwordx4 v74, v[82:85], s[76:77]
	global_store_dwordx4 v74, v[100:103], s[78:79]
	s_nop 1
	v_add_u32_e32 v68, 0x600, v154
	v_bfrev_b32_e32 v66, v68
	v_lshrrev_b32_e32 v66, 20, v66
	v_and_b32_e32 v67, 0xaaa, v66
	v_and_b32_e32 v66, 0x555, v66
	v_lshrrev_b32_e32 v67, 1, v67
	v_lshl_or_b32 v69, v66, 1, v67
	v_sub_u32_e32 v69, 0x1000, v69
	v_and_b32_e32 v69, 0xfff, v69
	v_bfrev_b32_e32 v66, v69
	v_lshrrev_b32_e32 v66, 20, v66
	v_and_b32_e32 v67, 0xaaa, v66
	v_and_b32_e32 v66, 0x555, v66
	v_lshrrev_b32_e32 v67, 1, v67
	v_lshl_or_b32 v68, v66, 1, v67
	v_lshlrev_b32_e32 v73, 5, v68
	ds_read_b128 v[20:23], v70 offset:49152
	ds_read_b128 v[24:27], v70 offset:49168
	ds_read_b128 v[58:61], v73
	ds_read_b128 v[62:65], v73 offset:16
	s_waitcnt lgkmcnt(4)
; HD int rev4_14(int p){ unsigned r = __brev((unsigned)p) >> 18; return (int)(((r & 0x2AAAu) >> 1) | ((r & 0x1555u) << 1)); }
; __device__ __forceinline__ void phase_hyena(KP kp_, int hf){ asm volatile("" : "+s"(kp_)); const Params p=load_params(kp_);
;     ...
;     _Pragma("unroll 2") for (int i=0;i<8;++i){ int q0=(tid+512*i)*4; u32x4 h0w, h1w;
;       _Pragma("unroll") for (int m=0;m<4;++m){ int q=q0+m; int k=rev4_14(q);
;         float2 Fk=Z[q], Fn=Z[rev4_14((16384-k)&16383)];
;         f16x2 h0v={(_Float16)(0.5f*nrm0*(Fk.x+Fn.x)),(_Float16)(0.5f*nrm0*(Fk.y-Fn.y))};
;         f16x2 h1v={(_Float16)(0.5f*nrm1*(Fk.y+Fn.y)),(_Float16)(-0.5f*nrm1*(Fk.x-Fn.x))};
;         unsigned u0=__builtin_bit_cast(unsigned,h0v), u1=__builtin_bit_cast(unsigned,h1v);
;         h0w[m]=u0; h1w[m]=u1; }
;       *(u32x4*)(H0p+q0)=h0w; *(u32x4*)(H1p+q0)=h1w; }
	v_pk_add_f32 v[104:105], v[4:5], v[18:19]
	v_pk_add_f32 v[106:107], v[4:5], v[18:19] neg_lo:[0,1] neg_hi:[0,1]
	v_mul_f32_e32 v108, v2, v104
	v_mul_f32_e32 v109, v2, v107
	v_mul_f32_e32 v110, v0, v105
	v_mul_f32_e32 v111, v1, v106
	v_cvt_pk_f16_f32 v82, v108, v109
	v_cvt_pk_f16_f32 v100, v110, v111
	v_pk_add_f32 v[104:105], v[6:7], v[16:17]
	v_pk_add_f32 v[106:107], v[6:7], v[16:17] neg_lo:[0,1] neg_hi:[0,1]
	v_mul_f32_e32 v108, v2, v104
	v_mul_f32_e32 v109, v2, v107
	v_mul_f32_e32 v110, v0, v105
	v_mul_f32_e32 v111, v1, v106
	v_cvt_pk_f16_f32 v83, v108, v109
	v_cvt_pk_f16_f32 v101, v110, v111
	v_pk_add_f32 v[104:105], v[8:9], v[14:15]
	v_pk_add_f32 v[106:107], v[8:9], v[14:15] neg_lo:[0,1] neg_hi:[0,1]
	v_mul_f32_e32 v108, v2, v104
	v_mul_f32_e32 v109, v2, v107
	v_mul_f32_e32 v110, v0, v105
	v_mul_f32_e32 v111, v1, v106
	v_cvt_pk_f16_f32 v84, v108, v109
	v_cvt_pk_f16_f32 v102, v110, v111
	v_pk_add_f32 v[104:105], v[10:11], v[12:13]
	v_pk_add_f32 v[106:107], v[10:11], v[12:13] neg_lo:[0,1] neg_hi:[0,1]
	v_mul_f32_e32 v108, v2, v104
	v_mul_f32_e32 v109, v2, v107
	v_mul_f32_e32 v110, v0, v105
	v_mul_f32_e32 v111, v1, v106
	v_cvt_pk_f16_f32 v85, v108, v109
	v_cvt_pk_f16_f32 v103, v110, v111
	v_add_u32_e32 v74, 0x4000, v72
	global_store_dwordx4 v74, v[82:85], s[76:77]
	global_store_dwordx4 v74, v[100:103], s[78:79]
	s_nop 1
	v_add_u32_e32 v68, 0x800, v154
	v_bfrev_b32_e32 v66, v68
	v_lshrrev_b32_e32 v66, 20, v66
	v_and_b32_e32 v67, 0xaaa, v66
	v_and_b32_e32 v66, 0x555, v66
	v_lshrrev_b32_e32 v67, 1, v67
	v_lshl_or_b32 v69, v66, 1, v67
	v_sub_u32_e32 v69, 0x1000, v69
	v_and_b32_e32 v69, 0xfff, v69
	v_bfrev_b32_e32 v66, v69
	v_lshrrev_b32_e32 v66, 20, v66
	v_and_b32_e32 v67, 0xaaa, v66
	v_and_b32_e32 v66, 0x555, v66
	v_lshrrev_b32_e32 v67, 1, v67
	v_lshl_or_b32 v68, v66, 1, v67
	v_lshlrev_b32_e32 v73, 5, v68
	ds_read_b128 v[4:7], v71 offset:0
	ds_read_b128 v[8:11], v71 offset:16
	ds_read_b128 v[12:15], v73
	ds_read_b128 v[16:19], v73 offset:16
	s_waitcnt lgkmcnt(4)
	v_pk_add_f32 v[104:105], v[20:21], v[64:65]
	v_pk_add_f32 v[106:107], v[20:21], v[64:65] neg_lo:[0,1] neg_hi:[0,1]
	v_mul_f32_e32 v108, v2, v104
	v_mul_f32_e32 v109, v2, v107
	v_mul_f32_e32 v110, v0, v105
	v_mul_f32_e32 v111, v1, v106
	v_cvt_pk_f16_f32 v82, v108, v109
	v_cvt_pk_f16_f32 v100, v110, v111
	v_pk_add_f32 v[104:105], v[22:23], v[62:63]
	v_pk_add_f32 v[106:107], v[22:23], v[62:63] neg_lo:[0,1] neg_hi:[0,1]
	v_mul_f32_e32 v108, v2, v104
	v_mul_f32_e32 v109, v2, v107
	v_mul_f32_e32 v110, v0, v105
	v_mul_f32_e32 v111, v1, v106
	v_cvt_pk_f16_f32 v83, v108, v109
	v_cvt_pk_f16_f32 v101, v110, v111
	v_pk_add_f32 v[104:105], v[24:25], v[60:61]
	v_pk_add_f32 v[106:107], v[24:25], v[60:61] neg_lo:[0,1] neg_hi:[0,1]
	v_mul_f32_e32 v108, v2, v104
	v_mul_f32_e32 v109, v2, v107
	v_mul_f32_e32 v110, v0, v105
	v_mul_f32_e32 v111, v1, v106
	v_cvt_pk_f16_f32 v84, v108, v109
	v_cvt_pk_f16_f32 v102, v110, v111
	v_pk_add_f32 v[104:105], v[26:27], v[58:59]
	v_pk_add_f32 v[106:107], v[26:27], v[58:59] neg_lo:[0,1] neg_hi:[0,1]
	v_mul_f32_e32 v108, v2, v104
	v_mul_f32_e32 v109, v2, v107
	v_mul_f32_e32 v110, v0, v105
	v_mul_f32_e32 v111, v1, v106
	v_cvt_pk_f16_f32 v85, v108, v109
	v_cvt_pk_f16_f32 v103, v110, v111
	v_add_u32_e32 v74, 0x6000, v72
	global_store_dwordx4 v74, v[82:85], s[76:77]
	global_store_dwordx4 v74, v[100:103], s[78:79]
	s_nop 1
	v_add_u32_e32 v68, 0xa00, v154
	v_bfrev_b32_e32 v66, v68
	v_lshrrev_b32_e32 v66, 20, v66
	v_and_b32_e32 v67, 0xaaa, v66
	v_and_b32_e32 v66, 0x555, v66
	v_lshrrev_b32_e32 v67, 1, v67
	v_lshl_or_b32 v69, v66, 1, v67
	v_sub_u32_e32 v69, 0x1000, v69
	v_and_b32_e32 v69, 0xfff, v69
	v_bfrev_b32_e32 v66, v69
	v_lshrrev_b32_e32 v66, 20, v66
	v_and_b32_e32 v67, 0xaaa, v66
	v_and_b32_e32 v66, 0x555, v66
	v_lshrrev_b32_e32 v67, 1, v67
	v_lshl_or_b32 v68, v66, 1, v67
	v_lshlrev_b32_e32 v73, 5, v68
	ds_read_b128 v[20:23], v71 offset:16384
	ds_read_b128 v[24:27], v71 offset:16400
	ds_read_b128 v[58:61], v73
	ds_read_b128 v[62:65], v73 offset:16
	s_waitcnt lgkmcnt(4)
	v_pk_add_f32 v[104:105], v[4:5], v[18:19]
	v_pk_add_f32 v[106:107], v[4:5], v[18:19] neg_lo:[0,1] neg_hi:[0,1]
	v_mul_f32_e32 v108, v2, v104
	v_mul_f32_e32 v109, v2, v107
	v_mul_f32_e32 v110, v0, v105
	v_mul_f32_e32 v111, v1, v106
	v_cvt_pk_f16_f32 v82, v108, v109
	v_cvt_pk_f16_f32 v100, v110, v111
	v_pk_add_f32 v[104:105], v[6:7], v[16:17]
	v_pk_add_f32 v[106:107], v[6:7], v[16:17] neg_lo:[0,1] neg_hi:[0,1]
	v_mul_f32_e32 v108, v2, v104
	v_mul_f32_e32 v109, v2, v107
	v_mul_f32_e32 v110, v0, v105
	v_mul_f32_e32 v111, v1, v106
	v_cvt_pk_f16_f32 v83, v108, v109
	v_cvt_pk_f16_f32 v101, v110, v111
	v_pk_add_f32 v[104:105], v[8:9], v[14:15]
	v_pk_add_f32 v[106:107], v[8:9], v[14:15] neg_lo:[0,1] neg_hi:[0,1]
	v_mul_f32_e32 v108, v2, v104
	v_mul_f32_e32 v109, v2, v107
	v_mul_f32_e32 v110, v0, v105
	v_mul_f32_e32 v111, v1, v106
	v_cvt_pk_f16_f32 v84, v108, v109
	v_cvt_pk_f16_f32 v102, v110, v111
	v_pk_add_f32 v[104:105], v[10:11], v[12:13]
	v_pk_add_f32 v[106:107], v[10:11], v[12:13] neg_lo:[0,1] neg_hi:[0,1]
	v_mul_f32_e32 v108, v2, v104
	v_mul_f32_e32 v109, v2, v107
	v_mul_f32_e32 v110, v0, v105
	v_mul_f32_e32 v111, v1, v106
	v_cvt_pk_f16_f32 v85, v108, v109
	v_cvt_pk_f16_f32 v103, v110, v111
	v_add_u32_e32 v74, 0x8000, v72
	global_store_dwordx4 v74, v[82:85], s[76:77]
	global_store_dwordx4 v74, v[100:103], s[78:79]
	s_nop 1
	v_add_u32_e32 v68, 0xc00, v154
	v_bfrev_b32_e32 v66, v68
	v_lshrrev_b32_e32 v66, 20, v66
	v_and_b32_e32 v67, 0xaaa, v66
	v_and_b32_e32 v66, 0x555, v66
	v_lshrrev_b32_e32 v67, 1, v67
	v_lshl_or_b32 v69, v66, 1, v67
	v_sub_u32_e32 v69, 0x1000, v69
	v_and_b32_e32 v69, 0xfff, v69
	v_bfrev_b32_e32 v66, v69
	v_lshrrev_b32_e32 v66, 20, v66
	v_and_b32_e32 v67, 0xaaa, v66
	v_and_b32_e32 v66, 0x555, v66
	v_lshrrev_b32_e32 v67, 1, v67
	v_lshl_or_b32 v68, v66, 1, v67
	v_lshlrev_b32_e32 v73, 5, v68
	ds_read_b128 v[4:7], v71 offset:32768
	ds_read_b128 v[8:11], v71 offset:32784
	ds_read_b128 v[12:15], v73
	ds_read_b128 v[16:19], v73 offset:16
	s_waitcnt lgkmcnt(4)
; HD int rev4_14(int p){ unsigned r = __brev((unsigned)p) >> 18; return (int)(((r & 0x2AAAu) >> 1) | ((r & 0x1555u) << 1)); }
; __device__ __forceinline__ void phase_hyena(KP kp_, int hf){ asm volatile("" : "+s"(kp_)); const Params p=load_params(kp_);
;     ...
;     _Pragma("unroll 2") for (int i=0;i<8;++i){ int q0=(tid+512*i)*4; u32x4 h0w, h1w;
;       _Pragma("unroll") for (int m=0;m<4;++m){ int q=q0+m; int k=rev4_14(q);
;         float2 Fk=Z[q], Fn=Z[rev4_14((16384-k)&16383)];
;         f16x2 h0v={(_Float16)(0.5f*nrm0*(Fk.x+Fn.x)),(_Float16)(0.5f*nrm0*(Fk.y-Fn.y))};
;         f16x2 h1v={(_Float16)(0.5f*nrm1*(Fk.y+Fn.y)),(_Float16)(-0.5f*nrm1*(Fk.x-Fn.x))};
;         unsigned u0=__builtin_bit_cast(unsigned,h0v), u1=__builtin_bit_cast(unsigned,h1v);
;         h0w[m]=u0; h1w[m]=u1; }
;       *(u32x4*)(H0p+q0)=h0w; *(u32x4*)(H1p+q0)=h1w; }
;         __builtin_amdgcn_fence(__ATOMIC_ACQUIRE, "agent");
	v_pk_add_f32 v[104:105], v[20:21], v[64:65]
	v_pk_add_f32 v[106:107], v[20:21], v[64:65] neg_lo:[0,1] neg_hi:[0,1]
	v_mul_f32_e32 v108, v2, v104
	v_mul_f32_e32 v109, v2, v107
	v_mul_f32_e32 v110, v0, v105
	v_mul_f32_e32 v111, v1, v106
	v_cvt_pk_f16_f32 v82, v108, v109
	v_cvt_pk_f16_f32 v100, v110, v111
	v_pk_add_f32 v[104:105], v[22:23], v[62:63]
	v_pk_add_f32 v[106:107], v[22:23], v[62:63] neg_lo:[0,1] neg_hi:[0,1]
	v_mul_f32_e32 v108, v2, v104
	v_mul_f32_e32 v109, v2, v107
	v_mul_f32_e32 v110, v0, v105
	v_mul_f32_e32 v111, v1, v106
	v_cvt_pk_f16_f32 v83, v108, v109
	v_cvt_pk_f16_f32 v101, v110, v111
	v_pk_add_f32 v[104:105], v[24:25], v[60:61]
	v_pk_add_f32 v[106:107], v[24:25], v[60:61] neg_lo:[0,1] neg_hi:[0,1]
	v_mul_f32_e32 v108, v2, v104
	v_mul_f32_e32 v109, v2, v107
	v_mul_f32_e32 v110, v0, v105
	v_mul_f32_e32 v111, v1, v106
	v_cvt_pk_f16_f32 v84, v108, v109
	v_cvt_pk_f16_f32 v102, v110, v111
	v_pk_add_f32 v[104:105], v[26:27], v[58:59]
	v_pk_add_f32 v[106:107], v[26:27], v[58:59] neg_lo:[0,1] neg_hi:[0,1]
	v_mul_f32_e32 v108, v2, v104
	v_mul_f32_e32 v109, v2, v107
	v_mul_f32_e32 v110, v0, v105
	v_mul_f32_e32 v111, v1, v106
	v_cvt_pk_f16_f32 v85, v108, v109
	v_cvt_pk_f16_f32 v103, v110, v111
	v_add_u32_e32 v74, 0xa000, v72
	global_store_dwordx4 v74, v[82:85], s[76:77]
	global_store_dwordx4 v74, v[100:103], s[78:79]
	s_nop 1
	v_add_u32_e32 v68, 0xe00, v154
	v_bfrev_b32_e32 v66, v68
	v_lshrrev_b32_e32 v66, 20, v66
	v_and_b32_e32 v67, 0xaaa, v66
	v_and_b32_e32 v66, 0x555, v66
	v_lshrrev_b32_e32 v67, 1, v67
	v_lshl_or_b32 v69, v66, 1, v67
	v_sub_u32_e32 v69, 0x1000, v69
	v_and_b32_e32 v69, 0xfff, v69
	v_bfrev_b32_e32 v66, v69
	v_lshrrev_b32_e32 v66, 20, v66
	v_and_b32_e32 v67, 0xaaa, v66
	v_and_b32_e32 v66, 0x555, v66
	v_lshrrev_b32_e32 v67, 1, v67
	v_lshl_or_b32 v68, v66, 1, v67
	v_lshlrev_b32_e32 v73, 5, v68
	ds_read_b128 v[20:23], v71 offset:49152
	ds_read_b128 v[24:27], v71 offset:49168
	ds_read_b128 v[58:61], v73
	ds_read_b128 v[62:65], v73 offset:16
	s_waitcnt lgkmcnt(4)
	v_pk_add_f32 v[104:105], v[4:5], v[18:19]
	v_pk_add_f32 v[106:107], v[4:5], v[18:19] neg_lo:[0,1] neg_hi:[0,1]
	v_mul_f32_e32 v108, v2, v104
	v_mul_f32_e32 v109, v2, v107
	v_mul_f32_e32 v110, v0, v105
	v_mul_f32_e32 v111, v1, v106
	v_cvt_pk_f16_f32 v82, v108, v109
	v_cvt_pk_f16_f32 v100, v110, v111
	v_pk_add_f32 v[104:105], v[6:7], v[16:17]
	v_pk_add_f32 v[106:107], v[6:7], v[16:17] neg_lo:[0,1] neg_hi:[0,1]
	v_mul_f32_e32 v108, v2, v104
	v_mul_f32_e32 v109, v2, v107
	v_mul_f32_e32 v110, v0, v105
	v_mul_f32_e32 v111, v1, v106
	v_cvt_pk_f16_f32 v83, v108, v109
	v_cvt_pk_f16_f32 v101, v110, v111
	v_pk_add_f32 v[104:105], v[8:9], v[14:15]
	v_pk_add_f32 v[106:107], v[8:9], v[14:15] neg_lo:[0,1] neg_hi:[0,1]
	v_mul_f32_e32 v108, v2, v104
	v_mul_f32_e32 v109, v2, v107
	v_mul_f32_e32 v110, v0, v105
	v_mul_f32_e32 v111, v1, v106
	v_cvt_pk_f16_f32 v84, v108, v109
	v_cvt_pk_f16_f32 v102, v110, v111
	v_pk_add_f32 v[104:105], v[10:11], v[12:13]
	v_pk_add_f32 v[106:107], v[10:11], v[12:13] neg_lo:[0,1] neg_hi:[0,1]
	v_mul_f32_e32 v108, v2, v104
	v_mul_f32_e32 v109, v2, v107
	v_mul_f32_e32 v110, v0, v105
	v_mul_f32_e32 v111, v1, v106
	v_cvt_pk_f16_f32 v85, v108, v109
	v_cvt_pk_f16_f32 v103, v110, v111
	v_add_u32_e32 v74, 0xc000, v72
	global_store_dwordx4 v74, v[82:85], s[76:77]
	global_store_dwordx4 v74, v[100:103], s[78:79]
	s_nop 1
	s_waitcnt lgkmcnt(0)
	v_pk_add_f32 v[104:105], v[20:21], v[64:65]
	v_pk_add_f32 v[106:107], v[20:21], v[64:65] neg_lo:[0,1] neg_hi:[0,1]
	v_mul_f32_e32 v108, v2, v104
	v_mul_f32_e32 v109, v2, v107
	v_mul_f32_e32 v110, v0, v105
	v_mul_f32_e32 v111, v1, v106
	v_cvt_pk_f16_f32 v82, v108, v109
	v_cvt_pk_f16_f32 v100, v110, v111
	v_pk_add_f32 v[104:105], v[22:23], v[62:63]
	v_pk_add_f32 v[106:107], v[22:23], v[62:63] neg_lo:[0,1] neg_hi:[0,1]
	v_mul_f32_e32 v108, v2, v104
	v_mul_f32_e32 v109, v2, v107
	v_mul_f32_e32 v110, v0, v105
	v_mul_f32_e32 v111, v1, v106
	v_cvt_pk_f16_f32 v83, v108, v109
	v_cvt_pk_f16_f32 v101, v110, v111
	v_pk_add_f32 v[104:105], v[24:25], v[60:61]
	v_pk_add_f32 v[106:107], v[24:25], v[60:61] neg_lo:[0,1] neg_hi:[0,1]
	v_mul_f32_e32 v108, v2, v104
	v_mul_f32_e32 v109, v2, v107
	v_mul_f32_e32 v110, v0, v105
	v_mul_f32_e32 v111, v1, v106
	v_cvt_pk_f16_f32 v84, v108, v109
	v_cvt_pk_f16_f32 v102, v110, v111
	v_pk_add_f32 v[104:105], v[26:27], v[58:59]
	v_pk_add_f32 v[106:107], v[26:27], v[58:59] neg_lo:[0,1] neg_hi:[0,1]
	v_mul_f32_e32 v108, v2, v104
	v_mul_f32_e32 v109, v2, v107
	v_mul_f32_e32 v110, v0, v105
	v_mul_f32_e32 v111, v1, v106
	v_cvt_pk_f16_f32 v85, v108, v109
	v_cvt_pk_f16_f32 v103, v110, v111
	v_add_u32_e32 v74, 0xe000, v72
	global_store_dwordx4 v74, v[82:85], s[76:77]
	global_store_dwordx4 v74, v[100:103], s[78:79]
	s_nop 1
	s_waitcnt vmcnt(0) lgkmcnt(0)
	s_branch .LBB0_1198
